# hazard-safe variant: s_setprio deleted only inside the 4 GEMM K-loops, replaced by s_nop elsewhere (adjacent nops coalesced); saddr DMA; lean SwiGLU epilogue
# baseline (speedup 1.0000x reference)
; #define PG8_STAGE(bufoff, gbase, voff) do { _Pragma("unroll") for (int _i = 0; _i < 2; ++_i) \
;         __builtin_amdgcn_global_load_lds((const unsigned*)((const char*)(gbase) + (voff)[_i]), (LAS unsigned*)(lds + (bufoff) + ldsw + _i * 8192), 16, 0, 0); } while (0)
; #define PG8_LDA(dst, b, h) do { _Pragma("unroll") for (int m = 0; m < 4; ++m) _Pragma("unroll") for (int k = 0; k < 2; ++k) dst[m][k] = *(const LAS bf16x8*)(lds + PG8_SA(b, h) + aoff + m * 2048 + k * 1024); } while (0)
; #define PG8_LDB(dst, b, h) do { _Pragma("unroll") for (int n = 0; n < 2; ++n) _Pragma("unroll") for (int k = 0; k < 2; ++k) dst[n][k] = *(const LAS bf16x8*)(lds + PG8_SB(b, h) + boff + n * 2048 + k * 1024); } while (0)
; #define PG8_MMA(ai, bj, At, Bt) do { __builtin_amdgcn_s_setprio(1); _Pragma("unroll") for (int m = 0; m < 4; ++m) _Pragma("unroll") for (int n = 0; n < 2; ++n) _Pragma("unroll") for (int k = 0; k < 2; ++k) \
;         acc[ai][bj][m][n] = __builtin_amdgcn_mfma_f32_16x16x32_bf16(Bt[n][k], At[m][k], acc[ai][bj][m][n], 0, 0, 0); __builtin_amdgcn_s_setprio(0); } while (0)
; #define PG8_WAIT_V(n) asm volatile("s_waitcnt vmcnt(" #n ")" ::: "memory")
; #define PG8_WAIT_L(n) asm volatile("s_waitcnt lgkmcnt(" #n ")" ::: "memory")
; #define PG8_BAR __builtin_amdgcn_s_barrier()
; #define PG8_SCHED __builtin_amdgcn_sched_barrier(0)
; template <class Epi, bool ALIGN_EPI>
; __device__ __forceinline__ void gemm_phase(LAS unsigned char* lds, const Gemm g, const StaticOrder& S, const Epi& E, const int tid) {
;     ...
;         for (int t = 0; t < nt; t += 2) {
;             const bool last = (t == nt - 2);
;             const char* a1 = cA + (size_t)(t + 1) * kstepA;
;             const char* a2 = last ? nA : cA + (size_t)(t + 2) * kstepA; const char* b2 = last ? nB : cB + (size_t)(t + 2) * kstepB;
;             const char* a3 = a2 + kstepA; const char* b3 = b2 + kstepB;
;             PG8_LDB(B0, 0, 0); PG8_LDB(B1, 0, 1); PG8_SCHED; PG8_LDA(At, 0, 0); PG8_STAGE(PG8_SA(1, 1), a1 + hstepA, voffA);
;             PG8_WAIT_V(8); PG8_WAIT_L(0); PG8_BAR; PG8_MMA(0, 0, At, B0); PG8_MMA(0, 1, At, B1); PG8_BAR; PG8_SCHED;
.LBB0_717:
	s_ashr_i32 s45, s44, 31
	s_lshl_b64 s[46:47], s[44:45], 19
	s_add_u32 s45, s30, s46
	s_addc_u32 s48, s60, s47
	s_ashr_i32 s43, s42, 31
	s_lshl_b64 s[46:47], s[42:43], 9
	s_add_u32 s46, s45, s46
	s_addc_u32 s47, s48, s47
	s_and_b64 s[48:49], s[38:39], exec
	s_cselect_b32 s57, s47, s51
	s_cselect_b32 s56, s46, s50
	s_lshl_b64 s[48:49], s[42:43], 17
	s_add_u32 s48, s61, s48
	s_addc_u32 s49, s71, s49
	s_and_b64 s[54:55], s[38:39], exec
	s_cselect_b32 s55, s49, s53
	s_cselect_b32 s54, s48, s52
	s_add_i32 s45, 0, 0x10000
	s_add_i32 s83, 0, 0x14000
	v_add_u32_e32 v222, s45, v170
	v_add_u32_e32 v223, s83, v170
	ds_read_b128 v[130:133], v222
	ds_read_b128 v[134:137], v222 offset:1024
	ds_read_b128 v[138:141], v222 offset:2048
	ds_read_b128 v[142:145], v222 offset:3072
	ds_read_b128 v[146:149], v223
	ds_read_b128 v[150:153], v223 offset:1024
	ds_read_b128 v[154:157], v223 offset:2048
	ds_read_b128 v[164:167], v223 offset:3072
	s_add_u32 s84, s50, 0x40080
	s_addc_u32 s85, s51, 0
	s_add_i32 s87, s73, 0xc000
	v_lshl_add_u64 v[168:169], s[84:85], 0, v[162:163]
	s_mov_b32 m0, s87
	s_add_i32 s43, s73, 0xe000
	ds_read_b128 v[172:175], v171
	ds_read_b128 v[176:179], v171 offset:1024
	ds_read_b128 v[180:183], v171 offset:2048
	ds_read_b128 v[184:187], v171 offset:3072
	ds_read_b128 v[188:191], v171 offset:4096
	ds_read_b128 v[192:195], v171 offset:5120
	ds_read_b128 v[196:199], v171 offset:6144
	ds_read_b128 v[214:217], v171 offset:7168
	global_load_lds_dwordx4 v[168:169], off
	v_lshl_add_u64 v[168:169], s[84:85], 0, v[160:161]
	s_mov_b32 m0, s43
	s_nop 0
	global_load_lds_dwordx4 v[168:169], off
	s_waitcnt vmcnt(8)
	s_waitcnt lgkmcnt(0)
	s_barrier
	s_nop 0
	s_waitcnt lgkmcnt(0)
	v_mfma_f32_16x16x32_bf16 v[30:33], v[130:133], v[180:183], v[30:33]
	v_mfma_f32_16x16x32_bf16 v[26:29], v[138:141], v[180:183], v[26:29]
	v_mfma_f32_16x16x32_bf16 v[42:45], v[130:133], v[188:191], v[42:45]
	v_mfma_f32_16x16x32_bf16 v[34:37], v[138:141], v[188:191], v[34:37]
	v_mfma_f32_16x16x32_bf16 v[70:73], v[130:133], v[196:199], v[70:73]
	v_mfma_f32_16x16x32_bf16 v[78:81], v[138:141], v[196:199], v[78:81]
	v_mfma_f32_16x16x32_bf16 v[14:17], v[130:133], v[172:175], v[14:17]
	v_mfma_f32_16x16x32_bf16 v[10:13], v[138:141], v[172:175], v[10:13]
	v_mfma_f32_16x16x32_bf16 v[30:33], v[134:137], v[184:187], v[30:33]
	v_mfma_f32_16x16x32_bf16 v[26:29], v[142:145], v[184:187], v[26:29]
	v_mfma_f32_16x16x32_bf16 v[42:45], v[134:137], v[192:195], v[42:45]
	v_mfma_f32_16x16x32_bf16 v[34:37], v[142:145], v[192:195], v[34:37]
	v_mfma_f32_16x16x32_bf16 v[70:73], v[134:137], v[214:217], v[70:73]
	v_mfma_f32_16x16x32_bf16 v[78:81], v[142:145], v[214:217], v[78:81]
	v_mfma_f32_16x16x32_bf16 v[14:17], v[134:137], v[176:179], v[14:17]
	v_mfma_f32_16x16x32_bf16 v[10:13], v[142:145], v[176:179], v[10:13]
	s_nop 1

; #define PG8_STAGE(bufoff, gbase, voff) do { _Pragma("unroll") for (int _i = 0; _i < 2; ++_i) \
;         __builtin_amdgcn_global_load_lds((const unsigned*)((const char*)(gbase) + (voff)[_i]), (LAS unsigned*)(lds + (bufoff) + ldsw + _i * 8192), 16, 0, 0); } while (0)
; #define PG8_LDA(dst, b, h) do { _Pragma("unroll") for (int m = 0; m < 4; ++m) _Pragma("unroll") for (int k = 0; k < 2; ++k) dst[m][k] = *(const LAS bf16x8*)(lds + PG8_SA(b, h) + aoff + m * 2048 + k * 1024); } while (0)
; #define PG8_MMA(ai, bj, At, Bt) do { __builtin_amdgcn_s_setprio(1); _Pragma("unroll") for (int m = 0; m < 4; ++m) _Pragma("unroll") for (int n = 0; n < 2; ++n) _Pragma("unroll") for (int k = 0; k < 2; ++k) \
;         acc[ai][bj][m][n] = __builtin_amdgcn_mfma_f32_16x16x32_bf16(Bt[n][k], At[m][k], acc[ai][bj][m][n], 0, 0, 0); __builtin_amdgcn_s_setprio(0); } while (0)
; #define PG8_WAIT_V(n) asm volatile("s_waitcnt vmcnt(" #n ")" ::: "memory")
; #define PG8_WAIT_L(n) asm volatile("s_waitcnt lgkmcnt(" #n ")" ::: "memory")
; #define PG8_BAR __builtin_amdgcn_s_barrier()
; #define PG8_SCHED __builtin_amdgcn_sched_barrier(0)
; template <class Epi, bool ALIGN_EPI>
; __device__ __forceinline__ void gemm_phase(LAS unsigned char* lds, const Gemm g, const StaticOrder& S, const Epi& E, const int tid) {
;     ...
;             PG8_WAIT_V(8); PG8_WAIT_L(0); PG8_BAR; PG8_MMA(0, 0, At, B0); PG8_MMA(0, 1, At, B1); PG8_BAR; PG8_SCHED;
;             PG8_LDA(At, 0, 1); PG8_STAGE(PG8_SB(0, 0), b2, voffB); PG8_STAGE(PG8_SB(0, 1), b2 + hstepB, voffB); PG8_STAGE(PG8_SA(0, 0), a2, voffA);
;             PG8_WAIT_V(8); PG8_WAIT_L(0); PG8_BAR; PG8_MMA(1, 0, At, B0); PG8_MMA(1, 1, At, B1); PG8_BAR; PG8_SCHED;
	v_mfma_f32_16x16x32_bf16 v[6:9], v[146:149], v[172:175], v[6:9]
	v_mfma_f32_16x16x32_bf16 v[2:5], v[154:157], v[172:175], v[2:5]
	v_mfma_f32_16x16x32_bf16 v[22:25], v[146:149], v[180:183], v[22:25]
	v_mfma_f32_16x16x32_bf16 v[18:21], v[154:157], v[180:183], v[18:21]
	v_mfma_f32_16x16x32_bf16 v[38:41], v[146:149], v[188:191], v[38:41]
	v_mfma_f32_16x16x32_bf16 v[46:49], v[154:157], v[188:191], v[46:49]
	v_mfma_f32_16x16x32_bf16 v[62:65], v[146:149], v[196:199], v[62:65]
	v_mfma_f32_16x16x32_bf16 v[74:77], v[154:157], v[196:199], v[74:77]
	v_mfma_f32_16x16x32_bf16 v[6:9], v[150:153], v[176:179], v[6:9]
	v_mfma_f32_16x16x32_bf16 v[2:5], v[164:167], v[176:179], v[2:5]
	v_mfma_f32_16x16x32_bf16 v[22:25], v[150:153], v[184:187], v[22:25]
	v_mfma_f32_16x16x32_bf16 v[18:21], v[164:167], v[184:187], v[18:21]
	v_mfma_f32_16x16x32_bf16 v[38:41], v[150:153], v[192:195], v[38:41]
	v_mfma_f32_16x16x32_bf16 v[46:49], v[164:167], v[192:195], v[46:49]
	v_mfma_f32_16x16x32_bf16 v[62:65], v[150:153], v[214:217], v[62:65]
	v_mfma_f32_16x16x32_bf16 v[74:77], v[164:167], v[214:217], v[74:77]
	s_nop 0
	s_barrier
	v_lshl_add_u64 v[168:169], s[52:53], 0, v[0:1]
	s_mov_b64 s[90:91], 0x100
	s_add_i32 s85, s45, s72
	v_lshl_add_u64 v[200:201], v[168:169], 0, s[90:91]
	s_mov_b32 m0, s85
	s_add_i32 s45, s85, 0x2000
	ds_read_b128 v[172:175], v171 offset:16384
	ds_read_b128 v[176:179], v171 offset:17408
	ds_read_b128 v[180:183], v171 offset:18432
	ds_read_b128 v[184:187], v171 offset:19456
	ds_read_b128 v[188:191], v171 offset:20480
	ds_read_b128 v[192:195], v171 offset:21504
	ds_read_b128 v[196:199], v171 offset:22528
	ds_read_b128 v[214:217], v171 offset:23552
	global_load_lds_dwordx4 v[200:201], off
	v_lshl_add_u64 v[200:201], s[52:53], 0, v[158:159]
	s_add_u32 s88, s52, 0x10100
	v_lshl_add_u64 v[210:211], v[200:201], 0, s[90:91]
	s_mov_b32 m0, s45
	s_addc_u32 s89, s53, 0
	s_add_i32 s83, s83, s72
	global_load_lds_dwordx4 v[210:211], off
	v_lshl_add_u64 v[210:211], s[88:89], 0, v[0:1]
	s_mov_b32 m0, s83
	s_add_i32 s84, s83, 0x2000
	global_load_lds_dwordx4 v[210:211], off
	v_lshl_add_u64 v[210:211], s[88:89], 0, v[158:159]
	s_mov_b32 m0, s84
	s_nop 0
	global_load_lds_dwordx4 v[210:211], off
	v_lshl_add_u64 v[210:211], s[50:51], 0, v[162:163]
	v_lshl_add_u64 v[218:219], v[210:211], 0, s[90:91]
	s_mov_b32 m0, s73
	s_nop 0
	global_load_lds_dwordx4 v[218:219], off
	v_lshl_add_u64 v[218:219], s[50:51], 0, v[160:161]
	v_lshl_add_u64 v[220:221], v[218:219], 0, s[90:91]
	s_mov_b32 m0, s74
	s_nop 0
	global_load_lds_dwordx4 v[220:221], off
	s_waitcnt vmcnt(8)
	s_waitcnt lgkmcnt(0)
	s_barrier
	s_nop 0
	s_waitcnt lgkmcnt(0)
	v_mfma_f32_16x16x32_bf16 v[50:53], v[130:133], v[172:175], v[50:53]
	v_mfma_f32_16x16x32_bf16 v[58:61], v[138:141], v[172:175], v[58:61]
	v_mfma_f32_16x16x32_bf16 v[82:85], v[130:133], v[180:183], v[82:85]
	v_mfma_f32_16x16x32_bf16 v[90:93], v[138:141], v[180:183], v[90:93]
	v_mfma_f32_16x16x32_bf16 v[98:101], v[130:133], v[188:191], v[98:101]
	v_mfma_f32_16x16x32_bf16 v[106:109], v[138:141], v[188:191], v[106:109]
	v_mfma_f32_16x16x32_bf16 v[118:121], v[130:133], v[196:199], v[118:121]
	v_mfma_f32_16x16x32_bf16 v[126:129], v[138:141], v[196:199], v[126:129]
	v_mfma_f32_16x16x32_bf16 v[50:53], v[134:137], v[176:179], v[50:53]
	v_mfma_f32_16x16x32_bf16 v[58:61], v[142:145], v[176:179], v[58:61]
	v_mfma_f32_16x16x32_bf16 v[82:85], v[134:137], v[184:187], v[82:85]
	v_mfma_f32_16x16x32_bf16 v[90:93], v[142:145], v[184:187], v[90:93]
	v_mfma_f32_16x16x32_bf16 v[98:101], v[134:137], v[192:195], v[98:101]
	v_mfma_f32_16x16x32_bf16 v[106:109], v[142:145], v[192:195], v[106:109]
	v_mfma_f32_16x16x32_bf16 v[118:121], v[134:137], v[214:217], v[118:121]
	v_mfma_f32_16x16x32_bf16 v[126:129], v[142:145], v[214:217], v[126:129]
	s_nop 1

; #define PG8_STAGE(bufoff, gbase, voff) do { _Pragma("unroll") for (int _i = 0; _i < 2; ++_i) \
;         __builtin_amdgcn_global_load_lds((const unsigned*)((const char*)(gbase) + (voff)[_i]), (LAS unsigned*)(lds + (bufoff) + ldsw + _i * 8192), 16, 0, 0); } while (0)
; #define PG8_LDA(dst, b, h) do { _Pragma("unroll") for (int m = 0; m < 4; ++m) _Pragma("unroll") for (int k = 0; k < 2; ++k) dst[m][k] = *(const LAS bf16x8*)(lds + PG8_SA(b, h) + aoff + m * 2048 + k * 1024); } while (0)
; #define PG8_LDB(dst, b, h) do { _Pragma("unroll") for (int n = 0; n < 2; ++n) _Pragma("unroll") for (int k = 0; k < 2; ++k) dst[n][k] = *(const LAS bf16x8*)(lds + PG8_SB(b, h) + boff + n * 2048 + k * 1024); } while (0)
; #define PG8_MMA(ai, bj, At, Bt) do { __builtin_amdgcn_s_setprio(1); _Pragma("unroll") for (int m = 0; m < 4; ++m) _Pragma("unroll") for (int n = 0; n < 2; ++n) _Pragma("unroll") for (int k = 0; k < 2; ++k) \
;         acc[ai][bj][m][n] = __builtin_amdgcn_mfma_f32_16x16x32_bf16(Bt[n][k], At[m][k], acc[ai][bj][m][n], 0, 0, 0); __builtin_amdgcn_s_setprio(0); } while (0)
; #define PG8_WAIT_V(n) asm volatile("s_waitcnt vmcnt(" #n ")" ::: "memory")
; #define PG8_WAIT_L(n) asm volatile("s_waitcnt lgkmcnt(" #n ")" ::: "memory")
; #define PG8_BAR __builtin_amdgcn_s_barrier()
; #define PG8_SCHED __builtin_amdgcn_sched_barrier(0)
; template <class Epi, bool ALIGN_EPI>
; __device__ __forceinline__ void gemm_phase(LAS unsigned char* lds, const Gemm g, const StaticOrder& S, const Epi& E, const int tid) {
;     ...
;             PG8_WAIT_V(8); PG8_WAIT_L(0); PG8_BAR; PG8_MMA(1, 0, At, B0); PG8_MMA(1, 1, At, B1); PG8_BAR; PG8_SCHED;
;             PG8_LDB(B0, 1, 0); PG8_LDB(B1, 1, 1); PG8_SCHED; PG8_LDA(At, 1, 0); PG8_STAGE(PG8_SA(0, 1), a2 + hstepA, voffA);
;             PG8_WAIT_V(8); PG8_WAIT_L(0); PG8_BAR; PG8_MMA(0, 0, At, B0); PG8_MMA(0, 1, At, B1); PG8_BAR; PG8_SCHED;
	v_mfma_f32_16x16x32_bf16 v[54:57], v[146:149], v[172:175], v[54:57]
	v_mfma_f32_16x16x32_bf16 v[66:69], v[154:157], v[172:175], v[66:69]
	v_mfma_f32_16x16x32_bf16 v[86:89], v[146:149], v[180:183], v[86:89]
	v_mfma_f32_16x16x32_bf16 v[94:97], v[154:157], v[180:183], v[94:97]
	v_mfma_f32_16x16x32_bf16 v[102:105], v[146:149], v[188:191], v[102:105]
	v_mfma_f32_16x16x32_bf16 v[110:113], v[154:157], v[188:191], v[110:113]
	v_mfma_f32_16x16x32_bf16 v[122:125], v[146:149], v[196:199], v[122:125]
	v_mfma_f32_16x16x32_bf16 v[114:117], v[154:157], v[196:199], v[114:117]
	v_mfma_f32_16x16x32_bf16 v[54:57], v[150:153], v[176:179], v[54:57]
	v_mfma_f32_16x16x32_bf16 v[66:69], v[164:167], v[176:179], v[66:69]
	v_mfma_f32_16x16x32_bf16 v[86:89], v[150:153], v[184:187], v[86:89]
	v_mfma_f32_16x16x32_bf16 v[94:97], v[164:167], v[184:187], v[94:97]
	v_mfma_f32_16x16x32_bf16 v[102:105], v[150:153], v[192:195], v[102:105]
	v_mfma_f32_16x16x32_bf16 v[110:113], v[164:167], v[192:195], v[110:113]
	v_mfma_f32_16x16x32_bf16 v[122:125], v[150:153], v[214:217], v[122:125]
	v_mfma_f32_16x16x32_bf16 v[114:117], v[164:167], v[214:217], v[114:117]
	s_nop 0
	s_barrier
	s_add_i32 s86, 0, 0x18000
	s_add_i32 s92, 0, 0x1c000
	v_add_u32_e32 v224, s86, v170
	v_add_u32_e32 v225, s92, v170
	ds_read_b128 v[130:133], v224
	ds_read_b128 v[134:137], v224 offset:1024
	ds_read_b128 v[138:141], v224 offset:2048
	ds_read_b128 v[142:145], v224 offset:3072
	ds_read_b128 v[146:149], v225
	ds_read_b128 v[150:153], v225 offset:1024
	ds_read_b128 v[154:157], v225 offset:2048
	ds_read_b128 v[164:167], v225 offset:3072
	s_add_u32 s88, s50, 0x40100
	s_addc_u32 s89, s51, 0
	s_mov_b32 m0, s75
	v_lshl_add_u64 v[220:221], s[88:89], 0, v[162:163]
	ds_read_b128 v[172:175], v171 offset:32768
	ds_read_b128 v[176:179], v171 offset:33792
	ds_read_b128 v[180:183], v171 offset:34816
	ds_read_b128 v[184:187], v171 offset:35840
	ds_read_b128 v[188:191], v171 offset:36864
	ds_read_b128 v[192:195], v171 offset:37888
	ds_read_b128 v[196:199], v171 offset:38912
	ds_read_b128 v[214:217], v171 offset:39936
	global_load_lds_dwordx4 v[220:221], off
	v_lshl_add_u64 v[220:221], s[88:89], 0, v[160:161]
	s_mov_b32 m0, s76
	s_nop 0
	global_load_lds_dwordx4 v[220:221], off
	s_waitcnt vmcnt(8)
	s_waitcnt lgkmcnt(0)
	s_barrier
	s_nop 0
	s_waitcnt lgkmcnt(0)
	v_mfma_f32_16x16x32_bf16 v[30:33], v[130:133], v[180:183], v[30:33]
	v_mfma_f32_16x16x32_bf16 v[26:29], v[138:141], v[180:183], v[26:29]
	v_mfma_f32_16x16x32_bf16 v[42:45], v[130:133], v[188:191], v[42:45]
	v_mfma_f32_16x16x32_bf16 v[34:37], v[138:141], v[188:191], v[34:37]
	v_mfma_f32_16x16x32_bf16 v[70:73], v[130:133], v[196:199], v[70:73]
	v_mfma_f32_16x16x32_bf16 v[78:81], v[138:141], v[196:199], v[78:81]
	v_mfma_f32_16x16x32_bf16 v[14:17], v[130:133], v[172:175], v[14:17]
	v_mfma_f32_16x16x32_bf16 v[10:13], v[138:141], v[172:175], v[10:13]
	v_mfma_f32_16x16x32_bf16 v[30:33], v[134:137], v[184:187], v[30:33]
	v_mfma_f32_16x16x32_bf16 v[26:29], v[142:145], v[184:187], v[26:29]
	v_mfma_f32_16x16x32_bf16 v[42:45], v[134:137], v[192:195], v[42:45]
	v_mfma_f32_16x16x32_bf16 v[34:37], v[142:145], v[192:195], v[34:37]
	v_mfma_f32_16x16x32_bf16 v[70:73], v[134:137], v[214:217], v[70:73]
	v_mfma_f32_16x16x32_bf16 v[78:81], v[142:145], v[214:217], v[78:81]
	v_mfma_f32_16x16x32_bf16 v[14:17], v[134:137], v[176:179], v[14:17]
	v_mfma_f32_16x16x32_bf16 v[10:13], v[142:145], v[176:179], v[10:13]
	s_nop 1

; #define PG8_STAGE(bufoff, gbase, voff) do { _Pragma("unroll") for (int _i = 0; _i < 2; ++_i) \
;         __builtin_amdgcn_global_load_lds((const unsigned*)((const char*)(gbase) + (voff)[_i]), (LAS unsigned*)(lds + (bufoff) + ldsw + _i * 8192), 16, 0, 0); } while (0)
; #define PG8_LDA(dst, b, h) do { _Pragma("unroll") for (int m = 0; m < 4; ++m) _Pragma("unroll") for (int k = 0; k < 2; ++k) dst[m][k] = *(const LAS bf16x8*)(lds + PG8_SA(b, h) + aoff + m * 2048 + k * 1024); } while (0)
; #define PG8_MMA(ai, bj, At, Bt) do { __builtin_amdgcn_s_setprio(1); _Pragma("unroll") for (int m = 0; m < 4; ++m) _Pragma("unroll") for (int n = 0; n < 2; ++n) _Pragma("unroll") for (int k = 0; k < 2; ++k) \
;         acc[ai][bj][m][n] = __builtin_amdgcn_mfma_f32_16x16x32_bf16(Bt[n][k], At[m][k], acc[ai][bj][m][n], 0, 0, 0); __builtin_amdgcn_s_setprio(0); } while (0)
; #define PG8_WAIT_V(n) asm volatile("s_waitcnt vmcnt(" #n ")" ::: "memory")
; #define PG8_WAIT_L(n) asm volatile("s_waitcnt lgkmcnt(" #n ")" ::: "memory")
; #define PG8_BAR __builtin_amdgcn_s_barrier()
; #define PG8_SCHED __builtin_amdgcn_sched_barrier(0)
; template <class Epi, bool ALIGN_EPI>
; __device__ __forceinline__ void gemm_phase(LAS unsigned char* lds, const Gemm g, const StaticOrder& S, const Epi& E, const int tid) {
;     ...
;             PG8_WAIT_V(8); PG8_WAIT_L(0); PG8_BAR; PG8_MMA(0, 0, At, B0); PG8_MMA(0, 1, At, B1); PG8_BAR; PG8_SCHED;
;             PG8_LDA(At, 1, 1); PG8_STAGE(PG8_SB(1, 0), b3, voffB); PG8_STAGE(PG8_SB(1, 1), b3 + hstepB, voffB); PG8_STAGE(PG8_SA(1, 0), a3, voffA);
;             PG8_WAIT_V(8); PG8_WAIT_L(0); PG8_BAR; PG8_MMA(1, 0, At, B0); PG8_MMA(1, 1, At, B1); PG8_BAR; PG8_SCHED;
	v_mfma_f32_16x16x32_bf16 v[6:9], v[146:149], v[172:175], v[6:9]
	v_mfma_f32_16x16x32_bf16 v[2:5], v[154:157], v[172:175], v[2:5]
	v_mfma_f32_16x16x32_bf16 v[22:25], v[146:149], v[180:183], v[22:25]
	v_mfma_f32_16x16x32_bf16 v[18:21], v[154:157], v[180:183], v[18:21]
	v_mfma_f32_16x16x32_bf16 v[38:41], v[146:149], v[188:191], v[38:41]
	v_mfma_f32_16x16x32_bf16 v[46:49], v[154:157], v[188:191], v[46:49]
	v_mfma_f32_16x16x32_bf16 v[62:65], v[146:149], v[196:199], v[62:65]
	v_mfma_f32_16x16x32_bf16 v[74:77], v[154:157], v[196:199], v[74:77]
	v_mfma_f32_16x16x32_bf16 v[6:9], v[150:153], v[176:179], v[6:9]
	v_mfma_f32_16x16x32_bf16 v[2:5], v[164:167], v[176:179], v[2:5]
	v_mfma_f32_16x16x32_bf16 v[22:25], v[150:153], v[184:187], v[22:25]
	v_mfma_f32_16x16x32_bf16 v[18:21], v[164:167], v[184:187], v[18:21]
	v_mfma_f32_16x16x32_bf16 v[38:41], v[150:153], v[192:195], v[38:41]
	v_mfma_f32_16x16x32_bf16 v[46:49], v[164:167], v[192:195], v[46:49]
	v_mfma_f32_16x16x32_bf16 v[62:65], v[150:153], v[214:217], v[62:65]
	v_mfma_f32_16x16x32_bf16 v[74:77], v[164:167], v[214:217], v[74:77]
	s_nop 0
	s_barrier
	s_add_i32 s88, s86, s72
	s_mov_b64 vcc, 0x180
	s_add_i32 s86, s88, 0x2000
	v_lshl_add_u64 v[168:169], v[168:169], 0, vcc
	s_mov_b32 m0, s88
	s_add_u32 s90, s52, 0x10180
	ds_read_b128 v[172:175], v171 offset:49152
	ds_read_b128 v[176:179], v171 offset:50176
	ds_read_b128 v[180:183], v171 offset:51200
	ds_read_b128 v[184:187], v171 offset:52224
	ds_read_b128 v[188:191], v171 offset:53248
	ds_read_b128 v[192:195], v171 offset:54272
	ds_read_b128 v[196:199], v171 offset:55296
	ds_read_b128 v[214:217], v171 offset:56320
	global_load_lds_dwordx4 v[168:169], off
	v_lshl_add_u64 v[168:169], v[200:201], 0, vcc
	s_mov_b32 m0, s86
	s_addc_u32 s91, s53, 0
	s_add_i32 s52, s92, s72
	global_load_lds_dwordx4 v[168:169], off
	v_lshl_add_u64 v[168:169], s[90:91], 0, v[0:1]
	s_mov_b32 m0, s52
	s_add_i32 s53, s52, 0x2000
	global_load_lds_dwordx4 v[168:169], off
	v_lshl_add_u64 v[168:169], s[90:91], 0, v[158:159]
	s_mov_b32 m0, s53
	s_nop 0
	global_load_lds_dwordx4 v[168:169], off
	v_lshl_add_u64 v[168:169], v[210:211], 0, vcc
	s_mov_b32 m0, s79
	s_nop 0
	global_load_lds_dwordx4 v[168:169], off
	v_lshl_add_u64 v[168:169], v[218:219], 0, vcc
	s_mov_b32 m0, s80
	s_nop 0
	global_load_lds_dwordx4 v[168:169], off
	s_waitcnt vmcnt(8)
	s_waitcnt lgkmcnt(0)
	s_barrier
	s_nop 0
	s_waitcnt lgkmcnt(0)
	v_mfma_f32_16x16x32_bf16 v[50:53], v[130:133], v[172:175], v[50:53]
	v_mfma_f32_16x16x32_bf16 v[58:61], v[138:141], v[172:175], v[58:61]
	v_mfma_f32_16x16x32_bf16 v[82:85], v[130:133], v[180:183], v[82:85]
	v_mfma_f32_16x16x32_bf16 v[90:93], v[138:141], v[180:183], v[90:93]
	v_mfma_f32_16x16x32_bf16 v[98:101], v[130:133], v[188:191], v[98:101]
	v_mfma_f32_16x16x32_bf16 v[106:109], v[138:141], v[188:191], v[106:109]
	v_mfma_f32_16x16x32_bf16 v[118:121], v[130:133], v[196:199], v[118:121]
	v_mfma_f32_16x16x32_bf16 v[126:129], v[138:141], v[196:199], v[126:129]
	v_mfma_f32_16x16x32_bf16 v[50:53], v[134:137], v[176:179], v[50:53]
	v_mfma_f32_16x16x32_bf16 v[58:61], v[142:145], v[176:179], v[58:61]
	v_mfma_f32_16x16x32_bf16 v[82:85], v[134:137], v[184:187], v[82:85]
	v_mfma_f32_16x16x32_bf16 v[90:93], v[142:145], v[184:187], v[90:93]
	v_mfma_f32_16x16x32_bf16 v[98:101], v[134:137], v[192:195], v[98:101]
	v_mfma_f32_16x16x32_bf16 v[106:109], v[142:145], v[192:195], v[106:109]
	v_mfma_f32_16x16x32_bf16 v[118:121], v[134:137], v[214:217], v[118:121]
	v_mfma_f32_16x16x32_bf16 v[126:129], v[142:145], v[214:217], v[126:129]
	s_nop 1

; #define PG8_STAGE(bufoff, gbase, voff) do { _Pragma("unroll") for (int _i = 0; _i < 2; ++_i) \
;         __builtin_amdgcn_global_load_lds((const unsigned*)((const char*)(gbase) + (voff)[_i]), (LAS unsigned*)(lds + (bufoff) + ldsw + _i * 8192), 16, 0, 0); } while (0)
; #define PG8_LDA(dst, b, h) do { _Pragma("unroll") for (int m = 0; m < 4; ++m) _Pragma("unroll") for (int k = 0; k < 2; ++k) dst[m][k] = *(const LAS bf16x8*)(lds + PG8_SA(b, h) + aoff + m * 2048 + k * 1024); } while (0)
; #define PG8_LDB(dst, b, h) do { _Pragma("unroll") for (int n = 0; n < 2; ++n) _Pragma("unroll") for (int k = 0; k < 2; ++k) dst[n][k] = *(const LAS bf16x8*)(lds + PG8_SB(b, h) + boff + n * 2048 + k * 1024); } while (0)
; #define PG8_MMA(ai, bj, At, Bt) do { __builtin_amdgcn_s_setprio(1); _Pragma("unroll") for (int m = 0; m < 4; ++m) _Pragma("unroll") for (int n = 0; n < 2; ++n) _Pragma("unroll") for (int k = 0; k < 2; ++k) \
;         acc[ai][bj][m][n] = __builtin_amdgcn_mfma_f32_16x16x32_bf16(Bt[n][k], At[m][k], acc[ai][bj][m][n], 0, 0, 0); __builtin_amdgcn_s_setprio(0); } while (0)
; #define PG8_WAIT_V(n) asm volatile("s_waitcnt vmcnt(" #n ")" ::: "memory")
; template <class Epi, bool ALIGN_EPI>
; __device__ __forceinline__ void gemm_phase(LAS unsigned char* lds, const Gemm g, const StaticOrder& S, const Epi& E, const int tid) {
;     ...
;             PG8_LDB(B0, 0, 0); PG8_LDB(B1, 0, 1); PG8_SCHED; PG8_LDA(At, 0, 0); PG8_STAGE(PG8_SA(1, 1), a1 + hstepA, voffA);
;             PG8_WAIT_V(8); PG8_WAIT_L(0); PG8_BAR; PG8_MMA(0, 0, At, B0); PG8_MMA(0, 1, At, B1); PG8_BAR; PG8_SCHED;
;             PG8_LDA(At, 0, 1); PG8_STAGE(PG8_SB(0, 0), b2, voffB); PG8_STAGE(PG8_SB(0, 1), b2 + hstepB, voffB); PG8_STAGE(PG8_SA(0, 0), a2, voffA);
;             PG8_WAIT_V(8); PG8_WAIT_L(0); PG8_BAR; PG8_MMA(1, 0, At, B0); PG8_MMA(1, 1, At, B1); PG8_BAR; PG8_SCHED;
;             PG8_LDB(B0, 1, 0); PG8_LDB(B1, 1, 1); PG8_SCHED; PG8_LDA(At, 1, 0); PG8_STAGE(PG8_SA(0, 1), a2 + hstepA, voffA);
;             PG8_WAIT_V(8); PG8_WAIT_L(0); PG8_BAR; PG8_MMA(0, 0, At, B0); PG8_MMA(0, 1, At, B1); PG8_BAR; PG8_SCHED;
;             PG8_LDA(At, 1, 1); PG8_STAGE(PG8_SB(1, 0), b3, voffB); PG8_STAGE(PG8_SB(1, 1), b3 + hstepB, voffB); PG8_STAGE(PG8_SA(1, 0), a3, voffA);
;             PG8_WAIT_V(8); PG8_WAIT_L(0); PG8_BAR; PG8_MMA(1, 0, At, B0); PG8_MMA(1, 1, At, B1); PG8_BAR; PG8_SCHED;
	v_mfma_f32_16x16x32_bf16 v[54:57], v[146:149], v[172:175], v[54:57]
	v_mfma_f32_16x16x32_bf16 v[66:69], v[154:157], v[172:175], v[66:69]
	v_mfma_f32_16x16x32_bf16 v[86:89], v[146:149], v[180:183], v[86:89]
	v_mfma_f32_16x16x32_bf16 v[94:97], v[154:157], v[180:183], v[94:97]
	v_mfma_f32_16x16x32_bf16 v[102:105], v[146:149], v[188:191], v[102:105]
	v_mfma_f32_16x16x32_bf16 v[110:113], v[154:157], v[188:191], v[110:113]
	v_mfma_f32_16x16x32_bf16 v[122:125], v[146:149], v[196:199], v[122:125]
	v_mfma_f32_16x16x32_bf16 v[114:117], v[154:157], v[196:199], v[114:117]
	v_mfma_f32_16x16x32_bf16 v[54:57], v[150:153], v[176:179], v[54:57]
	v_mfma_f32_16x16x32_bf16 v[66:69], v[164:167], v[176:179], v[66:69]
	v_mfma_f32_16x16x32_bf16 v[86:89], v[150:153], v[184:187], v[86:89]
	v_mfma_f32_16x16x32_bf16 v[94:97], v[164:167], v[184:187], v[94:97]
	v_mfma_f32_16x16x32_bf16 v[102:105], v[150:153], v[192:195], v[102:105]
	v_mfma_f32_16x16x32_bf16 v[110:113], v[164:167], v[192:195], v[110:113]
	v_mfma_f32_16x16x32_bf16 v[122:125], v[150:153], v[214:217], v[122:125]
	v_mfma_f32_16x16x32_bf16 v[114:117], v[164:167], v[214:217], v[114:117]
	s_nop 0
	s_barrier
	ds_read_b128 v[130:133], v222
	ds_read_b128 v[134:137], v222 offset:1024
	ds_read_b128 v[138:141], v222 offset:2048
	ds_read_b128 v[142:145], v222 offset:3072
	ds_read_b128 v[146:149], v223
	ds_read_b128 v[150:153], v223 offset:1024
	ds_read_b128 v[154:157], v223 offset:2048
	ds_read_b128 v[164:167], v223 offset:3072
	s_add_u32 s50, s50, 0x40180
	s_addc_u32 s51, s51, 0
	s_mov_b32 m0, s87
	v_lshl_add_u64 v[168:169], s[50:51], 0, v[162:163]
	ds_read_b128 v[172:175], v171
	ds_read_b128 v[176:179], v171 offset:1024
	ds_read_b128 v[180:183], v171 offset:2048
	ds_read_b128 v[184:187], v171 offset:3072
	ds_read_b128 v[188:191], v171 offset:4096
	ds_read_b128 v[192:195], v171 offset:5120
	ds_read_b128 v[196:199], v171 offset:6144
	ds_read_b128 v[214:217], v171 offset:7168
	global_load_lds_dwordx4 v[168:169], off
	v_lshl_add_u64 v[168:169], s[50:51], 0, v[160:161]
	s_mov_b32 m0, s43
	s_nop 0
	global_load_lds_dwordx4 v[168:169], off
	s_waitcnt vmcnt(8)
	s_waitcnt lgkmcnt(0)
	s_barrier
	s_nop 0
	s_waitcnt lgkmcnt(0)
	v_mfma_f32_16x16x32_bf16 v[30:33], v[130:133], v[180:183], v[30:33]
	v_mfma_f32_16x16x32_bf16 v[26:29], v[138:141], v[180:183], v[26:29]
	v_mfma_f32_16x16x32_bf16 v[42:45], v[130:133], v[188:191], v[42:45]
	v_mfma_f32_16x16x32_bf16 v[34:37], v[138:141], v[188:191], v[34:37]
	v_mfma_f32_16x16x32_bf16 v[70:73], v[130:133], v[196:199], v[70:73]
	v_mfma_f32_16x16x32_bf16 v[78:81], v[138:141], v[196:199], v[78:81]
	v_mfma_f32_16x16x32_bf16 v[14:17], v[130:133], v[172:175], v[14:17]
	v_mfma_f32_16x16x32_bf16 v[10:13], v[138:141], v[172:175], v[10:13]
	v_mfma_f32_16x16x32_bf16 v[30:33], v[134:137], v[184:187], v[30:33]
	v_mfma_f32_16x16x32_bf16 v[26:29], v[142:145], v[184:187], v[26:29]
	v_mfma_f32_16x16x32_bf16 v[42:45], v[134:137], v[192:195], v[42:45]
	v_mfma_f32_16x16x32_bf16 v[34:37], v[142:145], v[192:195], v[34:37]
	v_mfma_f32_16x16x32_bf16 v[70:73], v[134:137], v[214:217], v[70:73]
	v_mfma_f32_16x16x32_bf16 v[78:81], v[142:145], v[214:217], v[78:81]
	v_mfma_f32_16x16x32_bf16 v[14:17], v[134:137], v[176:179], v[14:17]
	v_mfma_f32_16x16x32_bf16 v[10:13], v[142:145], v[176:179], v[10:13]
	s_nop 1

; #define PG8_STAGE(bufoff, gbase, voff) do { _Pragma("unroll") for (int _i = 0; _i < 2; ++_i) \
;         __builtin_amdgcn_global_load_lds((const unsigned*)((const char*)(gbase) + (voff)[_i]), (LAS unsigned*)(lds + (bufoff) + ldsw + _i * 8192), 16, 0, 0); } while (0)
; #define PG8_LDA(dst, b, h) do { _Pragma("unroll") for (int m = 0; m < 4; ++m) _Pragma("unroll") for (int k = 0; k < 2; ++k) dst[m][k] = *(const LAS bf16x8*)(lds + PG8_SA(b, h) + aoff + m * 2048 + k * 1024); } while (0)
; #define PG8_MMA(ai, bj, At, Bt) do { __builtin_amdgcn_s_setprio(1); _Pragma("unroll") for (int m = 0; m < 4; ++m) _Pragma("unroll") for (int n = 0; n < 2; ++n) _Pragma("unroll") for (int k = 0; k < 2; ++k) \
;         acc[ai][bj][m][n] = __builtin_amdgcn_mfma_f32_16x16x32_bf16(Bt[n][k], At[m][k], acc[ai][bj][m][n], 0, 0, 0); __builtin_amdgcn_s_setprio(0); } while (0)
; #define PG8_WAIT_V(n) asm volatile("s_waitcnt vmcnt(" #n ")" ::: "memory")
; #define PG8_WAIT_L(n) asm volatile("s_waitcnt lgkmcnt(" #n ")" ::: "memory")
; #define PG8_BAR __builtin_amdgcn_s_barrier()
; #define PG8_SCHED __builtin_amdgcn_sched_barrier(0)
; template <class Epi, bool ALIGN_EPI>
; __device__ __forceinline__ void gemm_phase(LAS unsigned char* lds, const Gemm g, const StaticOrder& S, const Epi& E, const int tid) {
;     ...
;             PG8_WAIT_V(8); PG8_WAIT_L(0); PG8_BAR; PG8_MMA(0, 0, At, B0); PG8_MMA(0, 1, At, B1); PG8_BAR; PG8_SCHED;
;             PG8_LDA(At, 0, 1); PG8_STAGE(PG8_SB(0, 0), b2, voffB); PG8_STAGE(PG8_SB(0, 1), b2 + hstepB, voffB); PG8_STAGE(PG8_SA(0, 0), a2, voffA);
;             PG8_WAIT_V(8); PG8_WAIT_L(0); PG8_BAR; PG8_MMA(1, 0, At, B0); PG8_MMA(1, 1, At, B1); PG8_BAR; PG8_SCHED;
	v_mfma_f32_16x16x32_bf16 v[2:5], v[154:157], v[172:175], v[2:5]
	v_mfma_f32_16x16x32_bf16 v[6:9], v[146:149], v[172:175], v[6:9]
	v_mfma_f32_16x16x32_bf16 v[172:175], v[164:167], v[176:179], v[2:5]
	v_mfma_f32_16x16x32_bf16 v[2:5], v[146:149], v[180:183], v[22:25]
	v_mfma_f32_16x16x32_bf16 v[218:221], v[150:153], v[176:179], v[6:9]
	v_mfma_f32_16x16x32_bf16 v[176:179], v[150:153], v[184:187], v[2:5]
	v_mfma_f32_16x16x32_bf16 v[2:5], v[154:157], v[180:183], v[18:21]
	v_mfma_f32_16x16x32_bf16 v[180:183], v[164:167], v[184:187], v[2:5]
	v_mfma_f32_16x16x32_bf16 v[2:5], v[146:149], v[188:191], v[38:41]
	v_mfma_f32_16x16x32_bf16 v[38:41], v[150:153], v[192:195], v[2:5]
	v_mfma_f32_16x16x32_bf16 v[2:5], v[154:157], v[188:191], v[46:49]
	v_mfma_f32_16x16x32_bf16 v[46:49], v[164:167], v[192:195], v[2:5]
	v_mfma_f32_16x16x32_bf16 v[2:5], v[146:149], v[196:199], v[62:65]
	v_mfma_f32_16x16x32_bf16 v[62:65], v[150:153], v[214:217], v[2:5]
	v_mfma_f32_16x16x32_bf16 v[2:5], v[154:157], v[196:199], v[74:77]
	v_mfma_f32_16x16x32_bf16 v[74:77], v[164:167], v[214:217], v[2:5]
	s_nop 0
	s_barrier
	s_mov_b32 m0, s85
	v_lshl_add_u64 v[168:169], s[54:55], 0, v[0:1]
	s_add_u32 s50, s54, 0x10000
	s_nop 1
	ds_read_b128 v[2:5], v171 offset:16384
	ds_read_b128 v[6:9], v171 offset:17408
	ds_read_b128 v[18:21], v171 offset:18432
	ds_read_b128 v[22:25], v171 offset:19456
	ds_read_b128 v[184:187], v171 offset:20480
	ds_read_b128 v[188:191], v171 offset:21504
	ds_read_b128 v[192:195], v171 offset:22528
	ds_read_b128 v[196:199], v171 offset:23552
	global_load_lds_dwordx4 v[168:169], off
	v_lshl_add_u64 v[200:201], s[54:55], 0, v[158:159]
	s_mov_b32 m0, s45
	s_addc_u32 s51, s55, 0
	global_load_lds_dwordx4 v[200:201], off
	v_lshl_add_u64 v[210:211], s[50:51], 0, v[0:1]
	s_mov_b32 m0, s83
	v_lshl_add_u64 v[234:235], s[56:57], 0, v[160:161]
	global_load_lds_dwordx4 v[210:211], off
	v_lshl_add_u64 v[210:211], s[50:51], 0, v[158:159]
	s_mov_b32 m0, s84
	s_nop 0
	global_load_lds_dwordx4 v[210:211], off
	v_lshl_add_u64 v[210:211], s[56:57], 0, v[162:163]
	s_mov_b32 m0, s73
	s_nop 0
	global_load_lds_dwordx4 v[210:211], off
	s_mov_b32 m0, s74
	s_nop 0
	global_load_lds_dwordx4 v[234:235], off
	s_waitcnt vmcnt(8)
	s_waitcnt lgkmcnt(0)
	s_barrier
	s_nop 0
	s_waitcnt lgkmcnt(0)
	v_mfma_f32_16x16x32_bf16 v[50:53], v[130:133], v[2:5], v[50:53]
	v_mfma_f32_16x16x32_bf16 v[58:61], v[138:141], v[2:5], v[58:61]
	v_mfma_f32_16x16x32_bf16 v[82:85], v[130:133], v[18:21], v[82:85]
	v_mfma_f32_16x16x32_bf16 v[90:93], v[138:141], v[18:21], v[90:93]
	v_mfma_f32_16x16x32_bf16 v[98:101], v[130:133], v[184:187], v[98:101]
	v_mfma_f32_16x16x32_bf16 v[106:109], v[138:141], v[184:187], v[106:109]
	v_mfma_f32_16x16x32_bf16 v[118:121], v[130:133], v[192:195], v[118:121]
	v_mfma_f32_16x16x32_bf16 v[126:129], v[138:141], v[192:195], v[126:129]
	v_mfma_f32_16x16x32_bf16 v[50:53], v[134:137], v[6:9], v[50:53]
	v_mfma_f32_16x16x32_bf16 v[58:61], v[142:145], v[6:9], v[58:61]
	v_mfma_f32_16x16x32_bf16 v[82:85], v[134:137], v[22:25], v[82:85]
	v_mfma_f32_16x16x32_bf16 v[90:93], v[142:145], v[22:25], v[90:93]
	v_mfma_f32_16x16x32_bf16 v[98:101], v[134:137], v[188:191], v[98:101]
	v_mfma_f32_16x16x32_bf16 v[106:109], v[142:145], v[188:191], v[106:109]
	v_mfma_f32_16x16x32_bf16 v[118:121], v[134:137], v[196:199], v[118:121]
	v_mfma_f32_16x16x32_bf16 v[126:129], v[142:145], v[196:199], v[126:129]
	s_nop 1

; #define PG8_STAGE(bufoff, gbase, voff) do { _Pragma("unroll") for (int _i = 0; _i < 2; ++_i) \
;         __builtin_amdgcn_global_load_lds((const unsigned*)((const char*)(gbase) + (voff)[_i]), (LAS unsigned*)(lds + (bufoff) + ldsw + _i * 8192), 16, 0, 0); } while (0)
; #define PG8_LDA(dst, b, h) do { _Pragma("unroll") for (int m = 0; m < 4; ++m) _Pragma("unroll") for (int k = 0; k < 2; ++k) dst[m][k] = *(const LAS bf16x8*)(lds + PG8_SA(b, h) + aoff + m * 2048 + k * 1024); } while (0)
; #define PG8_LDB(dst, b, h) do { _Pragma("unroll") for (int n = 0; n < 2; ++n) _Pragma("unroll") for (int k = 0; k < 2; ++k) dst[n][k] = *(const LAS bf16x8*)(lds + PG8_SB(b, h) + boff + n * 2048 + k * 1024); } while (0)
; #define PG8_MMA(ai, bj, At, Bt) do { __builtin_amdgcn_s_setprio(1); _Pragma("unroll") for (int m = 0; m < 4; ++m) _Pragma("unroll") for (int n = 0; n < 2; ++n) _Pragma("unroll") for (int k = 0; k < 2; ++k) \
;         acc[ai][bj][m][n] = __builtin_amdgcn_mfma_f32_16x16x32_bf16(Bt[n][k], At[m][k], acc[ai][bj][m][n], 0, 0, 0); __builtin_amdgcn_s_setprio(0); } while (0)
; #define PG8_WAIT_V(n) asm volatile("s_waitcnt vmcnt(" #n ")" ::: "memory")
; #define PG8_WAIT_L(n) asm volatile("s_waitcnt lgkmcnt(" #n ")" ::: "memory")
; #define PG8_BAR __builtin_amdgcn_s_barrier()
; #define PG8_SCHED __builtin_amdgcn_sched_barrier(0)
; template <class Epi, bool ALIGN_EPI>
; __device__ __forceinline__ void gemm_phase(LAS unsigned char* lds, const Gemm g, const StaticOrder& S, const Epi& E, const int tid) {
;     ...
;             PG8_WAIT_V(8); PG8_WAIT_L(0); PG8_BAR; PG8_MMA(1, 0, At, B0); PG8_MMA(1, 1, At, B1); PG8_BAR; PG8_SCHED;
;             PG8_LDB(B0, 1, 0); PG8_LDB(B1, 1, 1); PG8_SCHED; PG8_LDA(At, 1, 0); PG8_STAGE(PG8_SA(0, 1), a2 + hstepA, voffA);
;             PG8_WAIT_V(8); PG8_WAIT_L(0); PG8_BAR; PG8_MMA(0, 0, At, B0); PG8_MMA(0, 1, At, B1); PG8_BAR; PG8_SCHED;
	v_mfma_f32_16x16x32_bf16 v[54:57], v[146:149], v[2:5], v[54:57]
	v_mfma_f32_16x16x32_bf16 v[2:5], v[154:157], v[2:5], v[66:69]
	v_mfma_f32_16x16x32_bf16 v[66:69], v[164:167], v[6:9], v[2:5]
	v_mfma_f32_16x16x32_bf16 v[2:5], v[146:149], v[18:21], v[86:89]
	v_mfma_f32_16x16x32_bf16 v[86:89], v[150:153], v[22:25], v[2:5]
	v_mfma_f32_16x16x32_bf16 v[2:5], v[154:157], v[18:21], v[94:97]
	v_mfma_f32_16x16x32_bf16 v[94:97], v[164:167], v[22:25], v[2:5]
	v_mfma_f32_16x16x32_bf16 v[2:5], v[146:149], v[184:187], v[102:105]
	v_mfma_f32_16x16x32_bf16 v[102:105], v[150:153], v[188:191], v[2:5]
	v_mfma_f32_16x16x32_bf16 v[2:5], v[154:157], v[184:187], v[110:113]
	v_mfma_f32_16x16x32_bf16 v[110:113], v[164:167], v[188:191], v[2:5]
	v_mfma_f32_16x16x32_bf16 v[2:5], v[146:149], v[192:195], v[122:125]
	v_mfma_f32_16x16x32_bf16 v[54:57], v[150:153], v[6:9], v[54:57]
	v_mfma_f32_16x16x32_bf16 v[122:125], v[150:153], v[196:199], v[2:5]
	v_mfma_f32_16x16x32_bf16 v[2:5], v[154:157], v[192:195], v[114:117]
	v_mfma_f32_16x16x32_bf16 v[130:133], v[164:167], v[196:199], v[2:5]
	s_nop 0
	s_barrier
	ds_read_b128 v[114:117], v224
	ds_read_b128 v[134:137], v224 offset:1024
	ds_read_b128 v[138:141], v224 offset:2048
	ds_read_b128 v[142:145], v224 offset:3072
	ds_read_b128 v[146:149], v225
	ds_read_b128 v[164:167], v225 offset:1024
	ds_read_b128 v[184:187], v225 offset:2048
	ds_read_b128 v[188:191], v225 offset:3072
	s_add_u32 s50, s56, 0x40000
	s_addc_u32 s51, s57, 0
	s_mov_b32 m0, s75
	v_lshl_add_u64 v[2:3], s[50:51], 0, v[162:163]
	ds_read_b128 v[150:153], v171 offset:32768
	ds_read_b128 v[154:157], v171 offset:33792
	ds_read_b128 v[192:195], v171 offset:34816
	ds_read_b128 v[196:199], v171 offset:35840
	ds_read_b128 v[214:217], v171 offset:36864
	ds_read_b128 v[222:225], v171 offset:37888
	ds_read_b128 v[226:229], v171 offset:38912
	ds_read_b128 v[230:233], v171 offset:39936
	global_load_lds_dwordx4 v[2:3], off
	v_lshl_add_u64 v[2:3], s[50:51], 0, v[160:161]
	s_mov_b32 m0, s76
	s_nop 0
	global_load_lds_dwordx4 v[2:3], off
	s_waitcnt vmcnt(8)
	s_waitcnt lgkmcnt(0)
	s_barrier
	s_nop 0
	s_waitcnt lgkmcnt(0)
	v_mfma_f32_16x16x32_bf16 v[6:9], v[138:141], v[150:153], v[10:13]
	v_mfma_f32_16x16x32_bf16 v[10:13], v[114:117], v[192:195], v[30:33]
	v_mfma_f32_16x16x32_bf16 v[18:21], v[134:137], v[196:199], v[10:13]
	v_mfma_f32_16x16x32_bf16 v[10:13], v[138:141], v[192:195], v[26:29]
	v_mfma_f32_16x16x32_bf16 v[22:25], v[142:145], v[196:199], v[10:13]
	v_mfma_f32_16x16x32_bf16 v[10:13], v[114:117], v[214:217], v[42:45]
	v_mfma_f32_16x16x32_bf16 v[42:45], v[134:137], v[222:225], v[10:13]
	v_mfma_f32_16x16x32_bf16 v[10:13], v[138:141], v[214:217], v[34:37]
	v_mfma_f32_16x16x32_bf16 v[34:37], v[142:145], v[222:225], v[10:13]
	v_mfma_f32_16x16x32_bf16 v[10:13], v[114:117], v[226:229], v[70:73]
	v_mfma_f32_16x16x32_bf16 v[2:5], v[114:117], v[150:153], v[14:17]
	v_mfma_f32_16x16x32_bf16 v[70:73], v[134:137], v[230:233], v[10:13]
	v_mfma_f32_16x16x32_bf16 v[10:13], v[138:141], v[226:229], v[78:81]
	v_mfma_f32_16x16x32_bf16 v[2:5], v[134:137], v[154:157], v[2:5]
	v_mfma_f32_16x16x32_bf16 v[6:9], v[142:145], v[154:157], v[6:9]
	v_mfma_f32_16x16x32_bf16 v[78:81], v[142:145], v[230:233], v[10:13]
	s_nop 1

; #define PG8_STAGE(bufoff, gbase, voff) do { _Pragma("unroll") for (int _i = 0; _i < 2; ++_i) \
;         __builtin_amdgcn_global_load_lds((const unsigned*)((const char*)(gbase) + (voff)[_i]), (LAS unsigned*)(lds + (bufoff) + ldsw + _i * 8192), 16, 0, 0); } while (0)
; #define PG8_LDA(dst, b, h) do { _Pragma("unroll") for (int m = 0; m < 4; ++m) _Pragma("unroll") for (int k = 0; k < 2; ++k) dst[m][k] = *(const LAS bf16x8*)(lds + PG8_SA(b, h) + aoff + m * 2048 + k * 1024); } while (0)
; #define PG8_MMA(ai, bj, At, Bt) do { __builtin_amdgcn_s_setprio(1); _Pragma("unroll") for (int m = 0; m < 4; ++m) _Pragma("unroll") for (int n = 0; n < 2; ++n) _Pragma("unroll") for (int k = 0; k < 2; ++k) \
;         acc[ai][bj][m][n] = __builtin_amdgcn_mfma_f32_16x16x32_bf16(Bt[n][k], At[m][k], acc[ai][bj][m][n], 0, 0, 0); __builtin_amdgcn_s_setprio(0); } while (0)
; #define PG8_WAIT_V(n) asm volatile("s_waitcnt vmcnt(" #n ")" ::: "memory")
; #define PG8_WAIT_L(n) asm volatile("s_waitcnt lgkmcnt(" #n ")" ::: "memory")
; #define PG8_BAR __builtin_amdgcn_s_barrier()
; #define PG8_SCHED __builtin_amdgcn_sched_barrier(0)
; template <class Epi, bool ALIGN_EPI>
; __device__ __forceinline__ void gemm_phase(LAS unsigned char* lds, const Gemm g, const StaticOrder& S, const Epi& E, const int tid) {
;     ...
;             PG8_WAIT_V(8); PG8_WAIT_L(0); PG8_BAR; PG8_MMA(0, 0, At, B0); PG8_MMA(0, 1, At, B1); PG8_BAR; PG8_SCHED;
;             PG8_LDA(At, 1, 1); PG8_STAGE(PG8_SB(1, 0), b3, voffB); PG8_STAGE(PG8_SB(1, 1), b3 + hstepB, voffB); PG8_STAGE(PG8_SA(1, 0), a3, voffA);
;             PG8_WAIT_V(8); PG8_WAIT_L(0); PG8_BAR; PG8_MMA(1, 0, At, B0); PG8_MMA(1, 1, At, B1); PG8_BAR; PG8_SCHED;
	v_mfma_f32_16x16x32_bf16 v[10:13], v[146:149], v[150:153], v[218:221]
	v_mfma_f32_16x16x32_bf16 v[26:29], v[164:167], v[154:157], v[10:13]
	v_mfma_f32_16x16x32_bf16 v[10:13], v[184:187], v[150:153], v[172:175]
	v_mfma_f32_16x16x32_bf16 v[30:33], v[188:191], v[154:157], v[10:13]
	v_mfma_f32_16x16x32_bf16 v[10:13], v[146:149], v[192:195], v[176:179]
	v_mfma_f32_16x16x32_bf16 v[150:153], v[164:167], v[196:199], v[10:13]
	v_mfma_f32_16x16x32_bf16 v[10:13], v[184:187], v[192:195], v[180:183]
	v_mfma_f32_16x16x32_bf16 v[154:157], v[188:191], v[196:199], v[10:13]
	v_mfma_f32_16x16x32_bf16 v[10:13], v[146:149], v[214:217], v[38:41]
	v_mfma_f32_16x16x32_bf16 v[38:41], v[164:167], v[222:225], v[10:13]
	v_mfma_f32_16x16x32_bf16 v[10:13], v[184:187], v[214:217], v[46:49]
	v_mfma_f32_16x16x32_bf16 v[46:49], v[188:191], v[222:225], v[10:13]
	v_mfma_f32_16x16x32_bf16 v[10:13], v[146:149], v[226:229], v[62:65]
	v_mfma_f32_16x16x32_bf16 v[62:65], v[164:167], v[230:233], v[10:13]
	v_mfma_f32_16x16x32_bf16 v[10:13], v[184:187], v[226:229], v[74:77]
	v_mfma_f32_16x16x32_bf16 v[74:77], v[188:191], v[230:233], v[10:13]
	s_nop 0
	s_barrier
	s_mov_b32 m0, s88
	v_lshl_add_u64 v[168:169], v[168:169], 0, s[6:7]
	s_add_u32 s50, s54, 0x10080
	s_nop 1
	ds_read_b128 v[10:13], v171 offset:49152
	ds_read_b128 v[14:17], v171 offset:50176
	ds_read_b128 v[172:175], v171 offset:51200
	ds_read_b128 v[176:179], v171 offset:52224
	ds_read_b128 v[180:183], v171 offset:53248
	ds_read_b128 v[192:195], v171 offset:54272
	ds_read_b128 v[196:199], v171 offset:55296
	ds_read_b128 v[214:217], v171 offset:56320
	global_load_lds_dwordx4 v[168:169], off
	v_lshl_add_u64 v[168:169], v[200:201], 0, s[6:7]
	s_mov_b32 m0, s86
	s_addc_u32 s51, s55, 0
	global_load_lds_dwordx4 v[168:169], off
	v_lshl_add_u64 v[168:169], s[50:51], 0, v[0:1]
	s_mov_b32 m0, s52
	s_nop 0
	global_load_lds_dwordx4 v[168:169], off
	v_lshl_add_u64 v[168:169], s[50:51], 0, v[158:159]
	s_mov_b32 m0, s53
	s_nop 0
	global_load_lds_dwordx4 v[168:169], off
	v_lshl_add_u64 v[168:169], v[210:211], 0, s[6:7]
	s_mov_b32 m0, s79
	s_nop 0
	global_load_lds_dwordx4 v[168:169], off
	v_lshl_add_u64 v[168:169], v[234:235], 0, s[6:7]
	s_mov_b32 m0, s80
	s_nop 0
	global_load_lds_dwordx4 v[168:169], off
	s_waitcnt vmcnt(8)
	s_waitcnt lgkmcnt(0)
	s_barrier
	s_nop 0
	s_waitcnt lgkmcnt(0)
	v_mfma_f32_16x16x32_bf16 v[50:53], v[114:117], v[10:13], v[50:53]
	v_mfma_f32_16x16x32_bf16 v[82:85], v[114:117], v[172:175], v[82:85]
	v_mfma_f32_16x16x32_bf16 v[98:101], v[114:117], v[180:183], v[98:101]
	v_mfma_f32_16x16x32_bf16 v[114:117], v[114:117], v[196:199], v[118:121]
	v_mfma_f32_16x16x32_bf16 v[58:61], v[138:141], v[10:13], v[58:61]
	v_mfma_f32_16x16x32_bf16 v[90:93], v[138:141], v[172:175], v[90:93]
	v_mfma_f32_16x16x32_bf16 v[106:109], v[138:141], v[180:183], v[106:109]
	v_mfma_f32_16x16x32_bf16 v[118:121], v[134:137], v[214:217], v[114:117]
	v_mfma_f32_16x16x32_bf16 v[114:117], v[138:141], v[196:199], v[126:129]
	v_mfma_f32_16x16x32_bf16 v[50:53], v[134:137], v[14:17], v[50:53]
	v_mfma_f32_16x16x32_bf16 v[58:61], v[142:145], v[14:17], v[58:61]
	v_mfma_f32_16x16x32_bf16 v[82:85], v[134:137], v[176:179], v[82:85]
	v_mfma_f32_16x16x32_bf16 v[90:93], v[142:145], v[176:179], v[90:93]
	v_mfma_f32_16x16x32_bf16 v[98:101], v[134:137], v[192:195], v[98:101]
	v_mfma_f32_16x16x32_bf16 v[106:109], v[142:145], v[192:195], v[106:109]
	v_mfma_f32_16x16x32_bf16 v[126:129], v[142:145], v[214:217], v[114:117]
	s_nop 1

; #define PG8_MMA(ai, bj, At, Bt) do { __builtin_amdgcn_s_setprio(1); _Pragma("unroll") for (int m = 0; m < 4; ++m) _Pragma("unroll") for (int n = 0; n < 2; ++n) _Pragma("unroll") for (int k = 0; k < 2; ++k) \
;         acc[ai][bj][m][n] = __builtin_amdgcn_mfma_f32_16x16x32_bf16(Bt[n][k], At[m][k], acc[ai][bj][m][n], 0, 0, 0); __builtin_amdgcn_s_setprio(0); } while (0)
; #define PG8_WAIT_V(n) asm volatile("s_waitcnt vmcnt(" #n ")" ::: "memory")
; #define PG8_WAIT_L(n) asm volatile("s_waitcnt lgkmcnt(" #n ")" ::: "memory")
; #define PG8_BAR __builtin_amdgcn_s_barrier()
; #define PG8_SCHED __builtin_amdgcn_sched_barrier(0)
; template <class Epi, bool ALIGN_EPI>
; __device__ __forceinline__ void gemm_phase(LAS unsigned char* lds, const Gemm g, const StaticOrder& S, const Epi& E, const int tid) {
;     ...
;             PG8_WAIT_V(8); PG8_WAIT_L(0); PG8_BAR; PG8_MMA(1, 0, At, B0); PG8_MMA(1, 1, At, B1); PG8_BAR; PG8_SCHED;
;         }
;         if constexpr (ALIGN_EPI) { if (wr == 0) PG8_BAR; }
;         E(acc, cur, wr, wc, lds, rs_pm);
;         if (!has_next) break;
;         cur = nxt; cA = nA; cB = nB; ++ui;
;         if constexpr (ALIGN_EPI) { if (wr == 1) PG8_BAR; }
	v_mfma_f32_16x16x32_bf16 v[54:57], v[146:149], v[10:13], v[54:57]
	v_mfma_f32_16x16x32_bf16 v[10:13], v[184:187], v[10:13], v[66:69]
	v_mfma_f32_16x16x32_bf16 v[66:69], v[188:191], v[14:17], v[10:13]
	v_mfma_f32_16x16x32_bf16 v[10:13], v[146:149], v[172:175], v[86:89]
	v_mfma_f32_16x16x32_bf16 v[86:89], v[164:167], v[176:179], v[10:13]
	v_mfma_f32_16x16x32_bf16 v[10:13], v[184:187], v[172:175], v[94:97]
	v_mfma_f32_16x16x32_bf16 v[94:97], v[188:191], v[176:179], v[10:13]
	v_mfma_f32_16x16x32_bf16 v[10:13], v[146:149], v[180:183], v[102:105]
	v_mfma_f32_16x16x32_bf16 v[102:105], v[164:167], v[192:195], v[10:13]
	v_mfma_f32_16x16x32_bf16 v[10:13], v[184:187], v[180:183], v[110:113]
	v_mfma_f32_16x16x32_bf16 v[110:113], v[188:191], v[192:195], v[10:13]
	v_mfma_f32_16x16x32_bf16 v[10:13], v[146:149], v[196:199], v[122:125]
	v_mfma_f32_16x16x32_bf16 v[114:117], v[164:167], v[214:217], v[10:13]
	v_mfma_f32_16x16x32_bf16 v[10:13], v[184:187], v[196:199], v[130:133]
	v_mfma_f32_16x16x32_bf16 v[54:57], v[164:167], v[14:17], v[54:57]
	v_mfma_f32_16x16x32_bf16 v[122:125], v[188:191], v[214:217], v[10:13]
	s_nop 0
	s_barrier
	s_andn2_b64 vcc, exec, s[34:35]
	s_cbranch_vccnz .LBB0_719
	s_barrier

; #define LAS __attribute__((address_space(3)))
; #define CONV_LOADA(e_, k_) do { const int xh_ = min(32 * (e_) + xa, L - 8); rh[k_] = *(const u32x4a4*)(Rc + xh_); asm volatile("" ::: "memory"); rl[k_] = *(const unsigned*)(Rc + xh_ - 2); } while (0)
; #define CONV_BLOCK(DO0, DO1) do { CONV_STEP(0, DO0, DO1); CONV_STEP(1, DO0, DO1); CONV_STEP(2, DO0, DO1); CONV_STEP(3, DO0, DO1); CONV_STEP(4, DO0, DO1); CONV_STEP(5, DO0, DO1); CONV_STEP(6, DO0, DO1); CONV_STEP(7, DO0, DO1); } while (0)
; template <bool PROMPT, int HALF>
; __device__ __forceinline__ void conv_item(unsigned char* ws, KArgs ka, int ib, int oct, int g, LAS unsigned char* lds, int tid, int lane, int wave) {
;     ...
;     { const bf16* Vg = (const bf16*)(ws + WS_VVT) + (size_t)c * T + (PROMPT ? 0 : TP + 4 * g * LS);
;       __syncthreads();
; #pragma unroll 4
;       for (int it = 0; it < 16; ++it) { const int s_ = (it * 64 + lane) * 8; *(LAS u32x4*)(vl + (s_ >> 8) * 528 + (s_ & 255) * 2) = *(const u32x4*)(Vg + s_); }
;       unsigned zz_ = 0u; asm volatile("" : "+v"(zz_));
;       if (lane < 33) *(LAS u32x4*)(vl + 32 * 528 + lane * 16) = (u32x4){zz_, zz_, zz_, zz_}; }
;     constexpr int NB = PROMPT ? 32 : 8, GS = PROMPT ? 16 : 4;
;     const int nbv = PROMPT ? nn : (nn >> 2);
;     LAS unsigned char* vcol = vl + 16 * kq + (PROMPT ? 0 : 8 * (nn & 3)) * 528;
;     const int zrow = PROMPT ? 32 : 32 - 8 * (nn & 3);
;     constexpr int W = (HALF == 2) ? 8 : 4, MO = (HALF == 1) ? 4 : 0;
;     f32x4 acc[2][W][2];
; #pragma unroll
;     for (int r = 0; r < 2; ++r)
; #pragma unroll
;         for (int q = 0; q < W; ++q)
; #pragma unroll
;             for (int gg = 0; gg < 2; ++gg) acc[r][q][gg] = (f32x4){0.f, 0.f, 0.f, 0.f};
;     constexpr int E0 = PROMPT ? -255 : -63, E1 = PROMPT ? -135 : -39, E2 = PROMPT ? 129 : 33, E3 = PROMPT ? 257 : 65;
;     static_assert((E1 - E0) % 8 == 0 && (E2 - E1) % 8 == 0 && (E3 - E2) % 8 == 0, "segments are whole 8-step blocks");
;     constexpr int DA = (HALF == 2) ? 2 : 4;
;     u32x4 rh[DA]; unsigned rl[DA];
;     u32x4 F0[W], F1[W];
;     ...
; #pragma unroll
;     for (int k = 0; k < DA; ++k) CONV_LOADA(E0 + k, k);
;     { unsigned zz_ = 0u; asm volatile("" : "+v"(zz_));
; #pragma unroll
;       for (int k = 0; k < W; ++k) F1[k] = (u32x4){zz_, zz_, zz_, zz_}; }
;     for (int e = E0; e < E1; e += 8) CONV_BLOCK(false, true);
.LBB0_728:
	v_add_u32_e32 v4, s23, v7
	v_ashrrev_i32_e32 v5, 31, v4
	v_lshl_add_u64 v[8:9], v[4:5], 1, s[10:11]
	global_load_dwordx4 v[8:11], v[8:9], off
	v_lshrrev_b32_e32 v3, 8, v4
	v_add_u32_e32 v12, 0x200, v4
	v_mad_i32_i24 v3, v3, s58, v2
	v_ashrrev_i32_e32 v13, 31, v12
	s_addk_i32 s23, 0x800
	s_cmpk_eq_i32 s23, 0x2000
	s_waitcnt vmcnt(0)
	ds_write_b128 v3, v[8:11]
	v_lshl_add_u64 v[8:9], v[12:13], 1, s[10:11]
	global_load_dwordx4 v[8:11], v[8:9], off
	v_lshrrev_b32_e32 v3, 8, v12
	v_add_u32_e32 v12, 0x400, v4
	v_mad_i32_i24 v3, v3, s58, v2
	v_ashrrev_i32_e32 v13, 31, v12
	v_add_u32_e32 v4, 0x600, v4
	v_ashrrev_i32_e32 v5, 31, v4
	s_waitcnt vmcnt(0)
	ds_write_b128 v3, v[8:11]
	v_lshl_add_u64 v[8:9], v[12:13], 1, s[10:11]
	global_load_dwordx4 v[8:11], v[8:9], off
	v_lshrrev_b32_e32 v3, 8, v12
	v_mad_i32_i24 v3, v3, s58, v2
	s_waitcnt vmcnt(0)
	ds_write_b128 v3, v[8:11]
	v_lshl_add_u64 v[8:9], v[4:5], 1, s[10:11]
	global_load_dwordx4 v[8:11], v[8:9], off
	v_lshrrev_b32_e32 v3, 8, v4
	v_mad_i32_i24 v3, v3, s58, v2
	s_waitcnt vmcnt(0)
	ds_write_b128 v3, v[8:11]
	s_cbranch_scc0 .LBB0_728
	v_mov_b32_e32 v2, v1
	v_cmp_gt_i32_e32 vcc, 33, v0
	s_and_saveexec_b64 s[10:11], vcc
	v_mov_b32_e32 v3, v2
	v_mov_b32_e32 v4, v2
	v_mov_b32_e32 v5, v2
	v_add_u32_e32 v6, s37, v6
	ds_write_b128 v6, v[2:5] offset:16896
	s_or_b64 exec, exec, s[10:11]
	v_lshrrev_b32_e32 v2, 1, v0
	v_and_b32_e32 v3, 15, v0
	v_lshlrev_b32_e32 v3, 1, v3
	v_and_b32_e32 v2, 56, v2
	v_sub_u32_e32 v215, v2, v3
	v_add_u32_e32 v2, 0xfffff820, v215
	s_add_u32 s10, s19, 0x53a01000
	v_min_i32_e32 v2, 0x7f8, v2
	s_addc_u32 s11, s22, 0
	v_ashrrev_i32_e32 v3, 31, v2
	v_add_u32_e32 v6, 0xfffff840, v215
	v_lshl_add_u64 v[8:9], v[2:3], 1, s[10:11]
	v_min_i32_e32 v10, 0x7f8, v6
	global_load_dwordx4 v[2:5], v[8:9], off
	v_ashrrev_i32_e32 v11, 31, v10
	v_lshl_add_u64 v[14:15], v[10:11], 1, s[10:11]
	global_load_dword v16, v[8:9], off offset:-4
	global_load_dwordx4 v[10:13], v[14:15], off
	v_add_u32_e32 v8, 0xfffff860, v215
	v_min_i32_e32 v8, 0x7f8, v8
	v_ashrrev_i32_e32 v9, 31, v8
	v_mov_b32_e32 v6, v1
	v_lshl_add_u64 v[8:9], v[8:9], 1, s[10:11]
	global_load_dword v20, v[14:15], off offset:-4
	global_load_dwordx4 v[22:25], v[8:9], off
	global_load_dword v46, v[8:9], off offset:-4
	v_and_b32_e32 v7, 24, v7
	v_and_b32_e32 v8, 0x70, v0
	v_bfe_u32 v216, v0, 2, 2
	v_mul_u32_u24_e32 v0, 0x210, v7
	v_sub_u32_e32 v214, 32, v7
	v_or_b32_e32 v217, 4, v216
	v_add3_u32 v0, s37, v8, v0
	v_mov_b32_e32 v7, v6
	v_mov_b32_e32 v8, v6
	v_mov_b32_e32 v9, v6
	s_waitcnt vmcnt(5)
	v_perm_b32 v15, v2, v3, s67
	v_perm_b32 v17, v4, v5, s67
	s_waitcnt vmcnt(4)
	v_perm_b32 v14, v16, v2, s67
	v_perm_b32 v16, v3, v4, s67
	s_nop 0
	v_add_u32_e32 v18, -3, v216
	v_cmp_gt_u32_e32 vcc, 8, v18
	v_mfma_f32_16x16x32_bf16 v[26:29], v[14:17], v[6:9], 0
	s_nop 0
	v_cndmask_b32_e32 v14, v214, v18, vcc
	v_mad_i32_i24 v102, v14, s58, v0
	ds_read_b128 v[14:17], v102 offset:64
	v_mfma_f32_16x16x32_bf16 v[2:5], v[2:5], v[6:9], 0
	s_nop 0
	v_add_u32_e32 v18, 0xfffff880, v215
	v_min_i32_e32 v18, 0x7f8, v18
	v_ashrrev_i32_e32 v19, 31, v18
	v_lshl_add_u64 v[18:19], v[18:19], 1, s[10:11]
	global_load_dwordx4 v[30:33], v[18:19], off
	global_load_dword v58, v[18:19], off offset:-4
	s_waitcnt vmcnt(4)
	v_perm_b32 v34, v20, v10, s67
	v_perm_b32 v35, v10, v11, s67
	v_perm_b32 v36, v11, v12, s67
	v_perm_b32 v37, v12, v13, s67
	s_nop 0
	ds_read_b128 v[18:21], v102 offset:128
	v_mfma_f32_16x16x32_bf16 v[38:41], v[34:37], v[6:9], v[26:29]
	v_mfma_f32_16x16x32_bf16 v[42:45], v[10:13], v[6:9], v[2:5]
	s_waitcnt lgkmcnt(1)
	v_mfma_f32_16x16x32_bf16 v[2:5], v[10:13], v[14:17], v[2:5]
	v_mfma_f32_16x16x32_bf16 v[10:13], v[34:37], v[14:17], v[26:29]
	s_nop 0
	s_nop 1
	v_add_u32_e32 v26, 0xfffff8a0, v215
	v_min_i32_e32 v26, 0x7f8, v26
	v_ashrrev_i32_e32 v27, 31, v26
	v_lshl_add_u64 v[26:27], v[26:27], 1, s[10:11]
	global_load_dwordx4 v[34:37], v[26:27], off
	global_load_dword v70, v[26:27], off offset:-4
	s_waitcnt vmcnt(4)
	v_perm_b32 v26, v46, v22, s67
	v_perm_b32 v27, v22, v23, s67
	v_perm_b32 v28, v23, v24, s67
	v_perm_b32 v29, v24, v25, s67
	s_nop 0
	v_mfma_f32_16x16x32_bf16 v[50:53], v[22:25], v[6:9], v[42:45]
	v_mfma_f32_16x16x32_bf16 v[42:45], v[22:25], v[14:17], v[42:45]
	s_waitcnt lgkmcnt(0)
	v_mfma_f32_16x16x32_bf16 v[2:5], v[22:25], v[18:21], v[2:5]
	ds_read_b128 v[22:25], v102 offset:192
	v_mfma_f32_16x16x32_bf16 v[46:49], v[26:29], v[6:9], v[38:41]
	v_mfma_f32_16x16x32_bf16 v[38:41], v[26:29], v[14:17], v[38:41]
	v_mfma_f32_16x16x32_bf16 v[10:13], v[26:29], v[18:21], v[10:13]
	s_nop 0
	v_add_u32_e32 v26, 0xfffff8c0, v215
	v_min_i32_e32 v26, 0x7f8, v26
	v_ashrrev_i32_e32 v27, 31, v26
	v_lshl_add_u64 v[26:27], v[26:27], 1, s[10:11]
	global_load_dwordx4 v[54:57], v[26:27], off
	global_load_dword v82, v[26:27], off offset:-4
	s_waitcnt vmcnt(4)
	v_perm_b32 v58, v58, v30, s67
	v_perm_b32 v59, v30, v31, s67
	v_perm_b32 v60, v31, v32, s67
	v_perm_b32 v61, v32, v33, s67
	s_nop 0
	ds_read_b128 v[26:29], v102 offset:256
	v_mfma_f32_16x16x32_bf16 v[62:65], v[58:61], v[6:9], v[46:49]
	v_mfma_f32_16x16x32_bf16 v[66:69], v[30:33], v[6:9], v[50:53]
	v_mfma_f32_16x16x32_bf16 v[50:53], v[30:33], v[14:17], v[50:53]
	v_mfma_f32_16x16x32_bf16 v[46:49], v[58:61], v[14:17], v[46:49]
	v_mfma_f32_16x16x32_bf16 v[42:45], v[30:33], v[18:21], v[42:45]
	v_mfma_f32_16x16x32_bf16 v[38:41], v[58:61], v[18:21], v[38:41]
	s_waitcnt lgkmcnt(1)
	v_mfma_f32_16x16x32_bf16 v[2:5], v[30:33], v[22:25], v[2:5]
	v_mfma_f32_16x16x32_bf16 v[10:13], v[58:61], v[22:25], v[10:13]
	s_nop 0
	v_add_u32_e32 v30, 0xfffff8e0, v215
	v_min_i32_e32 v30, 0x7f8, v30
	v_ashrrev_i32_e32 v31, 31, v30
	v_lshl_add_u64 v[30:31], v[30:31], 1, s[10:11]
	global_load_dwordx4 v[58:61], v[30:31], off
	global_load_dword v94, v[30:31], off offset:-4
	s_waitcnt vmcnt(4)
	v_perm_b32 v30, v70, v34, s67
	v_perm_b32 v31, v34, v35, s67
	v_perm_b32 v32, v35, v36, s67
	v_perm_b32 v33, v36, v37, s67
	s_nop 0
	v_mfma_f32_16x16x32_bf16 v[74:77], v[34:37], v[6:9], v[66:69]
	v_mfma_f32_16x16x32_bf16 v[66:69], v[34:37], v[14:17], v[66:69]
	v_mfma_f32_16x16x32_bf16 v[50:53], v[34:37], v[18:21], v[50:53]
	v_mfma_f32_16x16x32_bf16 v[42:45], v[34:37], v[22:25], v[42:45]
	s_waitcnt lgkmcnt(0)
	v_mfma_f32_16x16x32_bf16 v[2:5], v[34:37], v[26:29], v[2:5]
	ds_read_b128 v[34:37], v102 offset:320
	v_mfma_f32_16x16x32_bf16 v[70:73], v[30:33], v[6:9], v[62:65]
	v_mfma_f32_16x16x32_bf16 v[62:65], v[30:33], v[14:17], v[62:65]
	v_mfma_f32_16x16x32_bf16 v[46:49], v[30:33], v[18:21], v[46:49]
	v_mfma_f32_16x16x32_bf16 v[38:41], v[30:33], v[22:25], v[38:41]
	v_mfma_f32_16x16x32_bf16 v[10:13], v[30:33], v[26:29], v[10:13]
	s_nop 0
	v_add_u32_e32 v30, 0xfffff900, v215
	v_min_i32_e32 v30, 0x7f8, v30
	v_ashrrev_i32_e32 v31, 31, v30
	v_lshl_add_u64 v[30:31], v[30:31], 1, s[10:11]
	global_load_dwordx4 v[78:81], v[30:31], off
	global_load_dword v104, v[30:31], off offset:-4
	s_waitcnt vmcnt(4)
	v_perm_b32 v82, v82, v54, s67
	v_perm_b32 v83, v54, v55, s67
	v_perm_b32 v84, v55, v56, s67
	v_perm_b32 v85, v56, v57, s67
	s_nop 0
	ds_read_b128 v[30:33], v102 offset:384
	v_mfma_f32_16x16x32_bf16 v[86:89], v[82:85], v[6:9], v[70:73]
	v_mfma_f32_16x16x32_bf16 v[90:93], v[54:57], v[6:9], v[74:77]
	v_mfma_f32_16x16x32_bf16 v[74:77], v[54:57], v[14:17], v[74:77]
	v_mfma_f32_16x16x32_bf16 v[70:73], v[82:85], v[14:17], v[70:73]
	v_mfma_f32_16x16x32_bf16 v[66:69], v[54:57], v[18:21], v[66:69]
	v_mfma_f32_16x16x32_bf16 v[62:65], v[82:85], v[18:21], v[62:65]
	v_mfma_f32_16x16x32_bf16 v[50:53], v[54:57], v[22:25], v[50:53]
	v_mfma_f32_16x16x32_bf16 v[46:49], v[82:85], v[22:25], v[46:49]
	v_mfma_f32_16x16x32_bf16 v[42:45], v[54:57], v[26:29], v[42:45]
	v_mfma_f32_16x16x32_bf16 v[38:41], v[82:85], v[26:29], v[38:41]
	s_waitcnt lgkmcnt(1)
	v_mfma_f32_16x16x32_bf16 v[2:5], v[54:57], v[34:37], v[2:5]
	v_mfma_f32_16x16x32_bf16 v[10:13], v[82:85], v[34:37], v[10:13]
	s_nop 0
	v_add_u32_e32 v54, 0xfffff920, v215
	v_min_i32_e32 v54, 0x7f8, v54
	v_ashrrev_i32_e32 v55, 31, v54
	v_lshl_add_u64 v[82:83], v[54:55], 1, s[10:11]
	global_load_dwordx4 v[54:57], v[82:83], off
	global_load_dword v118, v[82:83], off offset:-4
	s_waitcnt vmcnt(4)
	v_perm_b32 v82, v94, v58, s67
	v_perm_b32 v83, v58, v59, s67
	v_perm_b32 v84, v59, v60, s67
	v_perm_b32 v85, v60, v61, s67
	s_nop 0
	v_mfma_f32_16x16x32_bf16 v[98:101], v[58:61], v[6:9], v[90:93]
	v_mfma_f32_16x16x32_bf16 v[90:93], v[58:61], v[14:17], v[90:93]
	v_mfma_f32_16x16x32_bf16 v[74:77], v[58:61], v[18:21], v[74:77]
	v_mfma_f32_16x16x32_bf16 v[66:69], v[58:61], v[22:25], v[66:69]
	v_mfma_f32_16x16x32_bf16 v[50:53], v[58:61], v[26:29], v[50:53]
	v_mfma_f32_16x16x32_bf16 v[42:45], v[58:61], v[34:37], v[42:45]
	s_waitcnt lgkmcnt(0)
	v_mfma_f32_16x16x32_bf16 v[58:61], v[58:61], v[30:33], v[2:5]
	s_nop 2
	ds_read_b128 v[2:5], v102 offset:448
	v_mfma_f32_16x16x32_bf16 v[94:97], v[82:85], v[6:9], v[86:89]
	v_mfma_f32_16x16x32_bf16 v[86:89], v[82:85], v[14:17], v[86:89]
	v_mfma_f32_16x16x32_bf16 v[70:73], v[82:85], v[18:21], v[70:73]
	v_mfma_f32_16x16x32_bf16 v[62:65], v[82:85], v[22:25], v[62:65]
	v_mfma_f32_16x16x32_bf16 v[46:49], v[82:85], v[26:29], v[46:49]
	v_mfma_f32_16x16x32_bf16 v[38:41], v[82:85], v[34:37], v[38:41]
	v_mfma_f32_16x16x32_bf16 v[10:13], v[82:85], v[30:33], v[10:13]
	s_nop 0
	v_add_u32_e32 v82, 0xfffff940, v215
	v_min_i32_e32 v82, 0x7f8, v82
	v_ashrrev_i32_e32 v83, 31, v82
	v_lshl_add_u64 v[102:103], v[82:83], 1, s[10:11]
	global_load_dwordx4 v[82:85], v[102:103], off
	global_load_dword v120, v[102:103], off offset:-4
	s_waitcnt vmcnt(4)
	v_perm_b32 v102, v104, v78, s67
	v_perm_b32 v103, v78, v79, s67
	v_perm_b32 v104, v79, v80, s67
	v_perm_b32 v105, v80, v81, s67
	s_nop 1

	v_mfma_f32_16x16x32_bf16 v[114:117], v[102:105], v[30:33], v[38:41]
	s_nop 2
	v_add_u32_e32 v38, -2, v216
	v_cmp_gt_u32_e32 vcc, 8, v38
	v_mfma_f32_16x16x32_bf16 v[106:109], v[102:105], v[6:9], v[94:97]
	s_nop 0
	v_cndmask_b32_e32 v38, v214, v38, vcc
	v_mad_i32_i24 v122, v38, s58, v0
	ds_read_b128 v[38:41], v122
	v_mfma_f32_16x16x32_bf16 v[110:113], v[78:81], v[14:17], v[98:101]
	v_mfma_f32_16x16x32_bf16 v[94:97], v[102:105], v[14:17], v[94:97]
	v_mfma_f32_16x16x32_bf16 v[90:93], v[78:81], v[18:21], v[90:93]
	v_mfma_f32_16x16x32_bf16 v[86:89], v[102:105], v[18:21], v[86:89]
	v_mfma_f32_16x16x32_bf16 v[74:77], v[78:81], v[22:25], v[74:77]
	v_mfma_f32_16x16x32_bf16 v[70:73], v[102:105], v[22:25], v[70:73]
	v_mfma_f32_16x16x32_bf16 v[66:69], v[78:81], v[26:29], v[66:69]
	v_mfma_f32_16x16x32_bf16 v[62:65], v[102:105], v[26:29], v[62:65]
	v_mfma_f32_16x16x32_bf16 v[50:53], v[78:81], v[34:37], v[50:53]
	v_mfma_f32_16x16x32_bf16 v[46:49], v[102:105], v[34:37], v[46:49]
	v_mfma_f32_16x16x32_bf16 v[42:45], v[78:81], v[30:33], v[42:45]
	s_waitcnt lgkmcnt(1)
	v_mfma_f32_16x16x32_bf16 v[58:61], v[78:81], v[2:5], v[58:61]
	v_mfma_f32_16x16x32_bf16 v[10:13], v[102:105], v[2:5], v[10:13]
	v_mfma_f32_16x16x32_bf16 v[78:81], v[78:81], v[6:9], v[98:101]
	s_nop 0
	v_add_u32_e32 v6, 0xfffff960, v215
	v_min_i32_e32 v6, 0x7f8, v6
	v_ashrrev_i32_e32 v7, 31, v6
	v_lshl_add_u64 v[6:7], v[6:7], 1, s[10:11]
	global_load_dwordx4 v[98:101], v[6:7], off
	global_load_dword v123, v[6:7], off offset:-4
	s_waitcnt vmcnt(4)
	v_perm_b32 v102, v118, v54, s67
	v_perm_b32 v103, v54, v55, s67
	v_perm_b32 v104, v55, v56, s67
	v_perm_b32 v105, v56, v57, s67
	s_nop 0
	ds_read_b128 v[6:9], v122 offset:64
	v_mfma_f32_16x16x32_bf16 v[106:109], v[102:105], v[14:17], v[106:109]
	v_mfma_f32_16x16x32_bf16 v[110:113], v[54:57], v[18:21], v[110:113]
	v_mfma_f32_16x16x32_bf16 v[94:97], v[102:105], v[18:21], v[94:97]
	v_mfma_f32_16x16x32_bf16 v[90:93], v[54:57], v[22:25], v[90:93]
	v_mfma_f32_16x16x32_bf16 v[86:89], v[102:105], v[22:25], v[86:89]
	v_mfma_f32_16x16x32_bf16 v[74:77], v[54:57], v[26:29], v[74:77]
	v_mfma_f32_16x16x32_bf16 v[70:73], v[102:105], v[26:29], v[70:73]
	v_mfma_f32_16x16x32_bf16 v[66:69], v[54:57], v[34:37], v[66:69]
	v_mfma_f32_16x16x32_bf16 v[62:65], v[102:105], v[34:37], v[62:65]
	v_mfma_f32_16x16x32_bf16 v[50:53], v[54:57], v[30:33], v[50:53]
	v_mfma_f32_16x16x32_bf16 v[46:49], v[102:105], v[30:33], v[46:49]
	v_mfma_f32_16x16x32_bf16 v[42:45], v[54:57], v[2:5], v[42:45]
	v_mfma_f32_16x16x32_bf16 v[114:117], v[102:105], v[2:5], v[114:117]
	s_waitcnt lgkmcnt(1)
	v_mfma_f32_16x16x32_bf16 v[58:61], v[54:57], v[38:41], v[58:61]
	v_mfma_f32_16x16x32_bf16 v[10:13], v[102:105], v[38:41], v[10:13]
	s_nop 0
	v_add_u32_e32 v102, 0xfffff980, v215
	v_min_i32_e32 v102, 0x7f8, v102
	v_ashrrev_i32_e32 v103, 31, v102
	v_lshl_add_u64 v[118:119], v[102:103], 1, s[10:11]
	global_load_dwordx4 v[102:105], v[118:119], off
	global_load_dword v124, v[118:119], off offset:-4
	s_waitcnt vmcnt(4)
	v_perm_b32 v118, v120, v82, s67
	v_perm_b32 v119, v82, v83, s67
	v_perm_b32 v120, v83, v84, s67
	v_perm_b32 v121, v84, v85, s67
	s_nop 1

	v_mfma_f32_16x16x32_bf16 v[106:109], v[118:121], v[18:21], v[106:109]
	v_mfma_f32_16x16x32_bf16 v[94:97], v[118:121], v[22:25], v[94:97]
	v_mfma_f32_16x16x32_bf16 v[86:89], v[118:121], v[26:29], v[86:89]
	v_mfma_f32_16x16x32_bf16 v[70:73], v[118:121], v[34:37], v[70:73]
	v_mfma_f32_16x16x32_bf16 v[62:65], v[118:121], v[30:33], v[62:65]
	v_mfma_f32_16x16x32_bf16 v[46:49], v[118:121], v[2:5], v[46:49]
	v_mfma_f32_16x16x32_bf16 v[114:117], v[118:121], v[38:41], v[114:117]
	s_waitcnt lgkmcnt(0)
	v_mfma_f32_16x16x32_bf16 v[118:121], v[118:121], v[6:9], v[10:13]
	s_nop 2
	ds_read_b128 v[10:13], v122 offset:128
	v_mfma_f32_16x16x32_bf16 v[110:113], v[82:85], v[22:25], v[110:113]
	v_mfma_f32_16x16x32_bf16 v[90:93], v[82:85], v[26:29], v[90:93]
	v_mfma_f32_16x16x32_bf16 v[74:77], v[82:85], v[34:37], v[74:77]
	v_mfma_f32_16x16x32_bf16 v[66:69], v[82:85], v[30:33], v[66:69]
	v_mfma_f32_16x16x32_bf16 v[50:53], v[82:85], v[2:5], v[50:53]
	v_mfma_f32_16x16x32_bf16 v[42:45], v[82:85], v[38:41], v[42:45]
	v_mfma_f32_16x16x32_bf16 v[58:61], v[82:85], v[6:9], v[58:61]
	v_mfma_f32_16x16x32_bf16 v[54:57], v[54:57], v[14:17], v[78:81]
	s_nop 0
	v_add_u32_e32 v14, 0xfffff9a0, v215
	v_min_i32_e32 v14, 0x7f8, v14
	v_ashrrev_i32_e32 v15, 31, v14
	v_lshl_add_u64 v[14:15], v[14:15], 1, s[10:11]
	global_load_dwordx4 v[78:81], v[14:15], off
	global_load_dword v125, v[14:15], off offset:-4
	s_waitcnt vmcnt(4)
	v_perm_b32 v14, v123, v98, s67
	v_perm_b32 v15, v98, v99, s67
	v_perm_b32 v16, v99, v100, s67
	v_perm_b32 v17, v100, v101, s67
	s_nop 1

	v_mfma_f32_16x16x32_bf16 v[106:109], v[14:17], v[22:25], v[106:109]
	v_mfma_f32_16x16x32_bf16 v[94:97], v[14:17], v[26:29], v[94:97]
	v_mfma_f32_16x16x32_bf16 v[86:89], v[14:17], v[34:37], v[86:89]
	v_mfma_f32_16x16x32_bf16 v[70:73], v[14:17], v[30:33], v[70:73]
	v_mfma_f32_16x16x32_bf16 v[62:65], v[14:17], v[2:5], v[62:65]
	v_mfma_f32_16x16x32_bf16 v[46:49], v[14:17], v[38:41], v[46:49]
	v_mfma_f32_16x16x32_bf16 v[114:117], v[14:17], v[6:9], v[114:117]
	s_waitcnt lgkmcnt(0)
	v_mfma_f32_16x16x32_bf16 v[118:121], v[14:17], v[10:13], v[118:121]
	ds_read_b128 v[14:17], v122 offset:192
	v_mfma_f32_16x16x32_bf16 v[110:113], v[98:101], v[26:29], v[110:113]
	v_mfma_f32_16x16x32_bf16 v[90:93], v[98:101], v[34:37], v[90:93]
	v_mfma_f32_16x16x32_bf16 v[74:77], v[98:101], v[30:33], v[74:77]
	v_mfma_f32_16x16x32_bf16 v[66:69], v[98:101], v[2:5], v[66:69]
	v_mfma_f32_16x16x32_bf16 v[50:53], v[98:101], v[38:41], v[50:53]
	v_mfma_f32_16x16x32_bf16 v[42:45], v[98:101], v[6:9], v[42:45]
	v_mfma_f32_16x16x32_bf16 v[58:61], v[98:101], v[10:13], v[58:61]
	v_mfma_f32_16x16x32_bf16 v[54:57], v[82:85], v[18:21], v[54:57]
	s_nop 0
	v_add_u32_e32 v18, 0xfffff9c0, v215
	v_min_i32_e32 v18, 0x7f8, v18
	v_ashrrev_i32_e32 v19, 31, v18
	v_lshl_add_u64 v[18:19], v[18:19], 1, s[10:11]
	global_load_dwordx4 v[82:85], v[18:19], off
	global_load_dword v123, v[18:19], off offset:-4
	s_waitcnt vmcnt(4)
	v_perm_b32 v18, v124, v102, s67
	v_perm_b32 v19, v102, v103, s67
	v_perm_b32 v20, v103, v104, s67
	v_perm_b32 v21, v104, v105, s67
	s_nop 1

	v_mfma_f32_16x16x32_bf16 v[106:109], v[18:21], v[26:29], v[106:109]
	v_mfma_f32_16x16x32_bf16 v[94:97], v[18:21], v[34:37], v[94:97]
	v_mfma_f32_16x16x32_bf16 v[86:89], v[18:21], v[30:33], v[86:89]
	v_mfma_f32_16x16x32_bf16 v[70:73], v[18:21], v[2:5], v[70:73]
	v_mfma_f32_16x16x32_bf16 v[62:65], v[18:21], v[38:41], v[62:65]
	v_mfma_f32_16x16x32_bf16 v[46:49], v[18:21], v[6:9], v[46:49]
	v_mfma_f32_16x16x32_bf16 v[114:117], v[18:21], v[10:13], v[114:117]
	s_waitcnt lgkmcnt(0)
	v_mfma_f32_16x16x32_bf16 v[118:121], v[18:21], v[14:17], v[118:121]
	ds_read_b128 v[18:21], v122 offset:256
	v_mfma_f32_16x16x32_bf16 v[110:113], v[102:105], v[34:37], v[110:113]
	v_mfma_f32_16x16x32_bf16 v[90:93], v[102:105], v[30:33], v[90:93]
	v_mfma_f32_16x16x32_bf16 v[74:77], v[102:105], v[2:5], v[74:77]
	v_mfma_f32_16x16x32_bf16 v[66:69], v[102:105], v[38:41], v[66:69]
	v_mfma_f32_16x16x32_bf16 v[50:53], v[102:105], v[6:9], v[50:53]
	v_mfma_f32_16x16x32_bf16 v[42:45], v[102:105], v[10:13], v[42:45]
	v_mfma_f32_16x16x32_bf16 v[58:61], v[102:105], v[14:17], v[58:61]
	v_mfma_f32_16x16x32_bf16 v[54:57], v[98:101], v[22:25], v[54:57]
	s_nop 0
	v_add_u32_e32 v22, 0xfffff9e0, v215
	v_min_i32_e32 v22, 0x7f8, v22
	v_ashrrev_i32_e32 v23, 31, v22
	v_lshl_add_u64 v[22:23], v[22:23], 1, s[10:11]
	global_load_dwordx4 v[98:101], v[22:23], off
	global_load_dword v124, v[22:23], off offset:-4
	s_waitcnt vmcnt(4)
	v_perm_b32 v22, v125, v78, s67
	v_perm_b32 v23, v78, v79, s67
	v_perm_b32 v24, v79, v80, s67
	v_perm_b32 v25, v80, v81, s67
	s_nop 1

	v_mfma_f32_16x16x32_bf16 v[106:109], v[22:25], v[34:37], v[106:109]
	v_mfma_f32_16x16x32_bf16 v[94:97], v[22:25], v[30:33], v[94:97]
	v_mfma_f32_16x16x32_bf16 v[86:89], v[22:25], v[2:5], v[86:89]
	v_mfma_f32_16x16x32_bf16 v[70:73], v[22:25], v[38:41], v[70:73]
	v_mfma_f32_16x16x32_bf16 v[62:65], v[22:25], v[6:9], v[62:65]
	v_mfma_f32_16x16x32_bf16 v[46:49], v[22:25], v[10:13], v[46:49]
	v_mfma_f32_16x16x32_bf16 v[114:117], v[22:25], v[14:17], v[114:117]
	s_waitcnt lgkmcnt(0)
	v_mfma_f32_16x16x32_bf16 v[118:121], v[22:25], v[18:21], v[118:121]
	ds_read_b128 v[22:25], v122 offset:320
	v_mfma_f32_16x16x32_bf16 v[110:113], v[78:81], v[30:33], v[110:113]
	v_mfma_f32_16x16x32_bf16 v[90:93], v[78:81], v[2:5], v[90:93]
	v_mfma_f32_16x16x32_bf16 v[74:77], v[78:81], v[38:41], v[74:77]
	v_mfma_f32_16x16x32_bf16 v[66:69], v[78:81], v[6:9], v[66:69]
	v_mfma_f32_16x16x32_bf16 v[50:53], v[78:81], v[10:13], v[50:53]
	v_mfma_f32_16x16x32_bf16 v[42:45], v[78:81], v[14:17], v[42:45]
	v_mfma_f32_16x16x32_bf16 v[58:61], v[78:81], v[18:21], v[58:61]
	v_mfma_f32_16x16x32_bf16 v[54:57], v[102:105], v[26:29], v[54:57]
	s_nop 0
	v_add_u32_e32 v26, 0xfffffa00, v215
	v_min_i32_e32 v26, 0x7f8, v26
	v_ashrrev_i32_e32 v27, 31, v26
	v_lshl_add_u64 v[26:27], v[26:27], 1, s[10:11]
	global_load_dwordx4 v[102:105], v[26:27], off
	global_load_dword v125, v[26:27], off offset:-4
	s_waitcnt vmcnt(4)
	v_perm_b32 v26, v123, v82, s67
	v_perm_b32 v27, v82, v83, s67
	v_perm_b32 v28, v83, v84, s67
	v_perm_b32 v29, v84, v85, s67
	s_nop 1

	v_mfma_f32_16x16x32_bf16 v[106:109], v[26:29], v[30:33], v[106:109]
	v_mfma_f32_16x16x32_bf16 v[94:97], v[26:29], v[2:5], v[94:97]
	v_mfma_f32_16x16x32_bf16 v[86:89], v[26:29], v[38:41], v[86:89]
	v_mfma_f32_16x16x32_bf16 v[70:73], v[26:29], v[6:9], v[70:73]
	v_mfma_f32_16x16x32_bf16 v[62:65], v[26:29], v[10:13], v[62:65]
	v_mfma_f32_16x16x32_bf16 v[46:49], v[26:29], v[14:17], v[46:49]
	v_mfma_f32_16x16x32_bf16 v[114:117], v[26:29], v[18:21], v[114:117]
	s_waitcnt lgkmcnt(0)
	v_mfma_f32_16x16x32_bf16 v[118:121], v[26:29], v[22:25], v[118:121]
	ds_read_b128 v[26:29], v122 offset:384
	v_mfma_f32_16x16x32_bf16 v[110:113], v[82:85], v[2:5], v[110:113]
	v_mfma_f32_16x16x32_bf16 v[90:93], v[82:85], v[38:41], v[90:93]
	v_mfma_f32_16x16x32_bf16 v[74:77], v[82:85], v[6:9], v[74:77]
	v_mfma_f32_16x16x32_bf16 v[66:69], v[82:85], v[10:13], v[66:69]
	v_mfma_f32_16x16x32_bf16 v[50:53], v[82:85], v[14:17], v[50:53]
	v_mfma_f32_16x16x32_bf16 v[42:45], v[82:85], v[18:21], v[42:45]
	v_mfma_f32_16x16x32_bf16 v[58:61], v[82:85], v[22:25], v[58:61]
	v_mfma_f32_16x16x32_bf16 v[54:57], v[78:81], v[34:37], v[54:57]
	s_nop 0
	v_add_u32_e32 v34, 0xfffffa20, v215
	v_min_i32_e32 v34, 0x7f8, v34
	v_ashrrev_i32_e32 v35, 31, v34
	v_lshl_add_u64 v[34:35], v[34:35], 1, s[10:11]
	global_load_dwordx4 v[78:81], v[34:35], off
	global_load_dword v126, v[34:35], off offset:-4
	s_waitcnt vmcnt(4)
	v_perm_b32 v34, v124, v98, s67
	v_perm_b32 v35, v98, v99, s67
	v_perm_b32 v36, v99, v100, s67
	v_perm_b32 v37, v100, v101, s67
	s_nop 1

	v_mfma_f32_16x16x32_bf16 v[106:109], v[34:37], v[2:5], v[106:109]
	v_mfma_f32_16x16x32_bf16 v[94:97], v[34:37], v[38:41], v[94:97]
	v_mfma_f32_16x16x32_bf16 v[86:89], v[34:37], v[6:9], v[86:89]
	v_mfma_f32_16x16x32_bf16 v[70:73], v[34:37], v[10:13], v[70:73]
	v_mfma_f32_16x16x32_bf16 v[62:65], v[34:37], v[14:17], v[62:65]
	v_mfma_f32_16x16x32_bf16 v[46:49], v[34:37], v[18:21], v[46:49]
	v_mfma_f32_16x16x32_bf16 v[114:117], v[34:37], v[22:25], v[114:117]
	s_waitcnt lgkmcnt(0)
	v_mfma_f32_16x16x32_bf16 v[118:121], v[34:37], v[26:29], v[118:121]
	ds_read_b128 v[34:37], v122 offset:448
	v_mfma_f32_16x16x32_bf16 v[110:113], v[98:101], v[38:41], v[110:113]
	v_mfma_f32_16x16x32_bf16 v[90:93], v[98:101], v[6:9], v[90:93]
	v_mfma_f32_16x16x32_bf16 v[74:77], v[98:101], v[10:13], v[74:77]
	v_mfma_f32_16x16x32_bf16 v[66:69], v[98:101], v[14:17], v[66:69]
	v_mfma_f32_16x16x32_bf16 v[50:53], v[98:101], v[18:21], v[50:53]
	v_mfma_f32_16x16x32_bf16 v[42:45], v[98:101], v[22:25], v[42:45]
	v_mfma_f32_16x16x32_bf16 v[58:61], v[98:101], v[26:29], v[58:61]
	v_mfma_f32_16x16x32_bf16 v[30:33], v[82:85], v[30:33], v[54:57]
	s_nop 0
	s_nop 1
	v_add_u32_e32 v54, 0xfffffa40, v215
	v_min_i32_e32 v54, 0x7f8, v54
	v_ashrrev_i32_e32 v55, 31, v54
	v_lshl_add_u64 v[82:83], v[54:55], 1, s[10:11]
	global_load_dwordx4 v[54:57], v[82:83], off
	global_load_dword v127, v[82:83], off offset:-4
	s_waitcnt vmcnt(4)
	v_perm_b32 v82, v125, v102, s67
	v_perm_b32 v83, v102, v103, s67
	v_perm_b32 v84, v103, v104, s67
	v_perm_b32 v85, v104, v105, s67
	s_nop 0
	v_mfma_f32_16x16x32_bf16 v[122:125], v[102:105], v[26:29], v[42:45]
	s_nop 2
	v_add_u32_e32 v42, -1, v216
	v_mfma_f32_16x16x32_bf16 v[2:5], v[98:101], v[2:5], v[30:33]
	v_cmp_gt_u32_e32 vcc, 8, v42
	s_nop 1
	v_cndmask_b32_e32 v30, v214, v42, vcc
	v_mad_i32_i24 v130, v30, s58, v0
	ds_read_b128 v[42:45], v130
	v_mfma_f32_16x16x32_bf16 v[106:109], v[82:85], v[38:41], v[106:109]
	v_mfma_f32_16x16x32_bf16 v[110:113], v[102:105], v[6:9], v[110:113]
	v_mfma_f32_16x16x32_bf16 v[94:97], v[82:85], v[6:9], v[94:97]
	v_mfma_f32_16x16x32_bf16 v[90:93], v[102:105], v[10:13], v[90:93]
	v_mfma_f32_16x16x32_bf16 v[86:89], v[82:85], v[10:13], v[86:89]
	v_mfma_f32_16x16x32_bf16 v[74:77], v[102:105], v[14:17], v[74:77]
	v_mfma_f32_16x16x32_bf16 v[70:73], v[82:85], v[14:17], v[70:73]
	v_mfma_f32_16x16x32_bf16 v[66:69], v[102:105], v[18:21], v[66:69]
	v_mfma_f32_16x16x32_bf16 v[62:65], v[82:85], v[18:21], v[62:65]
	v_mfma_f32_16x16x32_bf16 v[50:53], v[102:105], v[22:25], v[50:53]
	v_mfma_f32_16x16x32_bf16 v[46:49], v[82:85], v[22:25], v[46:49]
	v_mfma_f32_16x16x32_bf16 v[114:117], v[82:85], v[26:29], v[114:117]
	s_waitcnt lgkmcnt(1)
	v_mfma_f32_16x16x32_bf16 v[58:61], v[102:105], v[34:37], v[58:61]
	v_mfma_f32_16x16x32_bf16 v[82:85], v[82:85], v[34:37], v[118:121]
	v_mfma_f32_16x16x32_bf16 v[2:5], v[102:105], v[38:41], v[2:5]
	s_nop 0
	v_add_u32_e32 v30, 0xfffffa60, v215
	v_min_i32_e32 v30, 0x7f8, v30
	v_ashrrev_i32_e32 v31, 31, v30
	v_lshl_add_u64 v[38:39], v[30:31], 1, s[10:11]
	global_load_dwordx4 v[30:33], v[38:39], off
	global_load_dword v128, v[38:39], off offset:-4
	s_waitcnt vmcnt(4)
	v_perm_b32 v38, v126, v78, s67
	v_perm_b32 v39, v78, v79, s67
	v_perm_b32 v40, v79, v80, s67
	v_perm_b32 v41, v80, v81, s67
	s_nop 1

	v_mfma_f32_16x16x32_bf16 v[98:101], v[38:41], v[6:9], v[106:109]
	v_mfma_f32_16x16x32_bf16 v[106:109], v[78:81], v[18:21], v[74:77]
	s_nop 2
	ds_read_b128 v[74:77], v130 offset:64
	v_mfma_f32_16x16x32_bf16 v[102:105], v[78:81], v[10:13], v[110:113]
	v_mfma_f32_16x16x32_bf16 v[94:97], v[38:41], v[10:13], v[94:97]
	v_mfma_f32_16x16x32_bf16 v[90:93], v[78:81], v[14:17], v[90:93]
	v_mfma_f32_16x16x32_bf16 v[86:89], v[38:41], v[14:17], v[86:89]
	v_mfma_f32_16x16x32_bf16 v[70:73], v[38:41], v[18:21], v[70:73]
	v_mfma_f32_16x16x32_bf16 v[66:69], v[78:81], v[22:25], v[66:69]
	v_mfma_f32_16x16x32_bf16 v[62:65], v[38:41], v[22:25], v[62:65]
	v_mfma_f32_16x16x32_bf16 v[50:53], v[78:81], v[26:29], v[50:53]
	v_mfma_f32_16x16x32_bf16 v[46:49], v[38:41], v[26:29], v[46:49]
	v_mfma_f32_16x16x32_bf16 v[110:113], v[78:81], v[34:37], v[122:125]
	v_mfma_f32_16x16x32_bf16 v[114:117], v[38:41], v[34:37], v[114:117]
	s_waitcnt lgkmcnt(1)
	v_mfma_f32_16x16x32_bf16 v[58:61], v[78:81], v[42:45], v[58:61]
	v_mfma_f32_16x16x32_bf16 v[38:41], v[38:41], v[42:45], v[82:85]
	s_nop 0
	s_nop 1
	v_add_u32_e32 v82, 0xfffffa80, v215
	v_min_i32_e32 v82, 0x7f8, v82
	v_ashrrev_i32_e32 v83, 31, v82
	v_lshl_add_u64 v[82:83], v[82:83], 1, s[10:11]
	global_load_dwordx4 v[118:121], v[82:83], off
	global_load_dword v126, v[82:83], off offset:-4
	s_waitcnt vmcnt(4)
	v_perm_b32 v82, v127, v54, s67
	v_perm_b32 v83, v54, v55, s67
	v_perm_b32 v84, v55, v56, s67
	v_perm_b32 v85, v56, v57, s67
	s_nop 1

	v_mfma_f32_16x16x32_bf16 v[98:101], v[82:85], v[10:13], v[98:101]
	v_mfma_f32_16x16x32_bf16 v[94:97], v[82:85], v[14:17], v[94:97]
	v_mfma_f32_16x16x32_bf16 v[86:89], v[82:85], v[18:21], v[86:89]
	v_mfma_f32_16x16x32_bf16 v[70:73], v[82:85], v[22:25], v[70:73]
	v_mfma_f32_16x16x32_bf16 v[62:65], v[82:85], v[26:29], v[62:65]
	v_mfma_f32_16x16x32_bf16 v[46:49], v[82:85], v[34:37], v[46:49]
	v_mfma_f32_16x16x32_bf16 v[114:117], v[82:85], v[42:45], v[114:117]
	s_waitcnt lgkmcnt(0)
	v_mfma_f32_16x16x32_bf16 v[38:41], v[82:85], v[74:77], v[38:41]
	ds_read_b128 v[82:85], v130 offset:128
	v_mfma_f32_16x16x32_bf16 v[102:105], v[54:57], v[14:17], v[102:105]
	v_mfma_f32_16x16x32_bf16 v[90:93], v[54:57], v[18:21], v[90:93]
	v_mfma_f32_16x16x32_bf16 v[106:109], v[54:57], v[22:25], v[106:109]
	v_mfma_f32_16x16x32_bf16 v[66:69], v[54:57], v[26:29], v[66:69]
	v_mfma_f32_16x16x32_bf16 v[50:53], v[54:57], v[34:37], v[50:53]
	v_mfma_f32_16x16x32_bf16 v[110:113], v[54:57], v[42:45], v[110:113]
	v_mfma_f32_16x16x32_bf16 v[58:61], v[54:57], v[74:77], v[58:61]
	v_mfma_f32_16x16x32_bf16 v[2:5], v[78:81], v[6:9], v[2:5]
	s_nop 0
	v_add_u32_e32 v6, 0xfffffaa0, v215
	v_min_i32_e32 v6, 0x7f8, v6
	v_ashrrev_i32_e32 v7, 31, v6
	v_lshl_add_u64 v[78:79], v[6:7], 1, s[10:11]
	global_load_dwordx4 v[6:9], v[78:79], off
	global_load_dword v127, v[78:79], off offset:-4
	s_waitcnt vmcnt(4)
	v_perm_b32 v78, v128, v30, s67
	v_perm_b32 v79, v30, v31, s67
	v_perm_b32 v80, v31, v32, s67
	v_perm_b32 v81, v32, v33, s67
	s_nop 0
	v_mfma_f32_16x16x32_bf16 v[122:125], v[30:33], v[22:25], v[90:93]
	s_nop 2
	ds_read_b128 v[90:93], v130 offset:192
	v_mfma_f32_16x16x32_bf16 v[98:101], v[78:81], v[14:17], v[98:101]
	v_mfma_f32_16x16x32_bf16 v[102:105], v[30:33], v[18:21], v[102:105]
	v_mfma_f32_16x16x32_bf16 v[94:97], v[78:81], v[18:21], v[94:97]
	v_mfma_f32_16x16x32_bf16 v[86:89], v[78:81], v[22:25], v[86:89]
	v_mfma_f32_16x16x32_bf16 v[106:109], v[30:33], v[26:29], v[106:109]
	v_mfma_f32_16x16x32_bf16 v[70:73], v[78:81], v[26:29], v[70:73]
	v_mfma_f32_16x16x32_bf16 v[66:69], v[30:33], v[34:37], v[66:69]
	v_mfma_f32_16x16x32_bf16 v[62:65], v[78:81], v[34:37], v[62:65]
	v_mfma_f32_16x16x32_bf16 v[50:53], v[30:33], v[42:45], v[50:53]
	v_mfma_f32_16x16x32_bf16 v[46:49], v[78:81], v[42:45], v[46:49]
	v_mfma_f32_16x16x32_bf16 v[110:113], v[30:33], v[74:77], v[110:113]
	v_mfma_f32_16x16x32_bf16 v[114:117], v[78:81], v[74:77], v[114:117]
	s_waitcnt lgkmcnt(1)
	v_mfma_f32_16x16x32_bf16 v[58:61], v[30:33], v[82:85], v[58:61]
	v_mfma_f32_16x16x32_bf16 v[38:41], v[78:81], v[82:85], v[38:41]
	v_mfma_f32_16x16x32_bf16 v[2:5], v[54:57], v[10:13], v[2:5]
	s_nop 0
	v_add_u32_e32 v10, 0xfffffac0, v215
	v_min_i32_e32 v10, 0x7f8, v10
	v_ashrrev_i32_e32 v11, 31, v10
	v_lshl_add_u64 v[54:55], v[10:11], 1, s[10:11]
	global_load_dwordx4 v[10:13], v[54:55], off
	global_load_dword v131, v[54:55], off offset:-4
	s_waitcnt vmcnt(4)
	v_perm_b32 v54, v126, v118, s67
	v_perm_b32 v55, v118, v119, s67
	v_perm_b32 v56, v119, v120, s67
	v_perm_b32 v57, v120, v121, s67
	s_nop 1

	v_mfma_f32_16x16x32_bf16 v[78:81], v[54:57], v[18:21], v[98:101]
	v_mfma_f32_16x16x32_bf16 v[98:101], v[118:121], v[22:25], v[102:105]
	s_nop 2
	ds_read_b128 v[102:105], v130 offset:256
	v_mfma_f32_16x16x32_bf16 v[94:97], v[54:57], v[22:25], v[94:97]
	v_mfma_f32_16x16x32_bf16 v[122:125], v[118:121], v[26:29], v[122:125]
	v_mfma_f32_16x16x32_bf16 v[86:89], v[54:57], v[26:29], v[86:89]
	v_mfma_f32_16x16x32_bf16 v[106:109], v[118:121], v[34:37], v[106:109]
	v_mfma_f32_16x16x32_bf16 v[70:73], v[54:57], v[34:37], v[70:73]
	v_mfma_f32_16x16x32_bf16 v[66:69], v[118:121], v[42:45], v[66:69]
	v_mfma_f32_16x16x32_bf16 v[62:65], v[54:57], v[42:45], v[62:65]
	v_mfma_f32_16x16x32_bf16 v[50:53], v[118:121], v[74:77], v[50:53]
	v_mfma_f32_16x16x32_bf16 v[46:49], v[54:57], v[74:77], v[46:49]
	v_mfma_f32_16x16x32_bf16 v[110:113], v[118:121], v[82:85], v[110:113]
	v_mfma_f32_16x16x32_bf16 v[114:117], v[54:57], v[82:85], v[114:117]
	s_waitcnt lgkmcnt(1)
	v_mfma_f32_16x16x32_bf16 v[58:61], v[118:121], v[90:93], v[58:61]
	v_mfma_f32_16x16x32_bf16 v[38:41], v[54:57], v[90:93], v[38:41]
	v_mfma_f32_16x16x32_bf16 v[2:5], v[30:33], v[14:17], v[2:5]
	s_nop 0
	v_add_u32_e32 v14, 0xfffffae0, v215
	v_min_i32_e32 v14, 0x7f8, v14
	v_ashrrev_i32_e32 v15, 31, v14
	v_lshl_add_u64 v[14:15], v[14:15], 1, s[10:11]
	global_load_dwordx4 v[54:57], v[14:15], off
	global_load_dword v132, v[14:15], off offset:-4
	s_waitcnt vmcnt(4)
	v_perm_b32 v14, v127, v6, s67
	v_perm_b32 v15, v6, v7, s67
	v_perm_b32 v16, v7, v8, s67
	v_perm_b32 v17, v8, v9, s67
	s_nop 0
	ds_read_b128 v[126:129], v130 offset:320
	v_mfma_f32_16x16x32_bf16 v[30:33], v[14:17], v[22:25], v[78:81]
	v_mfma_f32_16x16x32_bf16 v[78:81], v[6:9], v[26:29], v[98:101]
	v_mfma_f32_16x16x32_bf16 v[94:97], v[14:17], v[26:29], v[94:97]
	v_mfma_f32_16x16x32_bf16 v[98:101], v[6:9], v[34:37], v[122:125]
	v_mfma_f32_16x16x32_bf16 v[86:89], v[14:17], v[34:37], v[86:89]
	v_mfma_f32_16x16x32_bf16 v[106:109], v[6:9], v[42:45], v[106:109]
	v_mfma_f32_16x16x32_bf16 v[70:73], v[14:17], v[42:45], v[70:73]
	v_mfma_f32_16x16x32_bf16 v[66:69], v[6:9], v[74:77], v[66:69]
	v_mfma_f32_16x16x32_bf16 v[62:65], v[14:17], v[74:77], v[62:65]
	v_mfma_f32_16x16x32_bf16 v[50:53], v[6:9], v[82:85], v[50:53]
	v_mfma_f32_16x16x32_bf16 v[46:49], v[14:17], v[82:85], v[46:49]
	v_mfma_f32_16x16x32_bf16 v[110:113], v[6:9], v[90:93], v[110:113]
	v_mfma_f32_16x16x32_bf16 v[114:117], v[14:17], v[90:93], v[114:117]
	s_waitcnt lgkmcnt(1)
	v_mfma_f32_16x16x32_bf16 v[58:61], v[6:9], v[102:105], v[58:61]
	v_mfma_f32_16x16x32_bf16 v[14:17], v[14:17], v[102:105], v[38:41]
	v_mfma_f32_16x16x32_bf16 v[2:5], v[118:121], v[18:21], v[2:5]
	s_nop 0
	v_add_u32_e32 v18, 0xfffffb00, v215
	v_min_i32_e32 v18, 0x7f8, v18
	v_ashrrev_i32_e32 v19, 31, v18
	v_lshl_add_u64 v[18:19], v[18:19], 1, s[10:11]
	global_load_dwordx4 v[38:41], v[18:19], off
	global_load_dword v118, v[18:19], off offset:-4
	s_waitcnt vmcnt(4)
	v_perm_b32 v18, v131, v10, s67
	v_perm_b32 v19, v10, v11, s67
	v_perm_b32 v20, v11, v12, s67
	v_perm_b32 v21, v12, v13, s67
	s_nop 0
	ds_read_b128 v[142:145], v130 offset:384
	v_mfma_f32_16x16x32_bf16 v[30:33], v[18:21], v[26:29], v[30:33]
	v_mfma_f32_16x16x32_bf16 v[78:81], v[10:13], v[34:37], v[78:81]
	v_mfma_f32_16x16x32_bf16 v[94:97], v[18:21], v[34:37], v[94:97]
	v_mfma_f32_16x16x32_bf16 v[98:101], v[10:13], v[42:45], v[98:101]
	v_mfma_f32_16x16x32_bf16 v[86:89], v[18:21], v[42:45], v[86:89]
	v_mfma_f32_16x16x32_bf16 v[106:109], v[10:13], v[74:77], v[106:109]
	v_mfma_f32_16x16x32_bf16 v[70:73], v[18:21], v[74:77], v[70:73]
	v_mfma_f32_16x16x32_bf16 v[66:69], v[10:13], v[82:85], v[66:69]
	v_mfma_f32_16x16x32_bf16 v[62:65], v[18:21], v[82:85], v[62:65]
	v_mfma_f32_16x16x32_bf16 v[50:53], v[10:13], v[90:93], v[50:53]
	v_mfma_f32_16x16x32_bf16 v[46:49], v[18:21], v[90:93], v[46:49]
	v_mfma_f32_16x16x32_bf16 v[110:113], v[10:13], v[102:105], v[110:113]
	v_mfma_f32_16x16x32_bf16 v[114:117], v[18:21], v[102:105], v[114:117]
	s_waitcnt lgkmcnt(1)
	v_mfma_f32_16x16x32_bf16 v[58:61], v[10:13], v[126:129], v[58:61]
	v_mfma_f32_16x16x32_bf16 v[14:17], v[18:21], v[126:129], v[14:17]
	v_mfma_f32_16x16x32_bf16 v[2:5], v[6:9], v[22:25], v[2:5]
	s_nop 0
	v_add_u32_e32 v6, 0xfffffb20, v215
	v_min_i32_e32 v6, 0x7f8, v6
	v_ashrrev_i32_e32 v7, 31, v6
	v_lshl_add_u64 v[6:7], v[6:7], 1, s[10:11]
	global_load_dwordx4 v[162:165], v[6:7], off
	global_load_dword v219, v[6:7], off offset:-4
	s_waitcnt vmcnt(4)
	v_perm_b32 v6, v132, v54, s67
	v_perm_b32 v7, v54, v55, s67
	v_perm_b32 v8, v55, v56, s67
	v_perm_b32 v9, v56, v57, s67
	s_nop 0
	ds_read_b128 v[150:153], v130 offset:448
	v_mfma_f32_16x16x32_bf16 v[18:21], v[6:9], v[34:37], v[30:33]
	v_mfma_f32_16x16x32_bf16 v[22:25], v[54:57], v[42:45], v[78:81]
	v_mfma_f32_16x16x32_bf16 v[30:33], v[6:9], v[42:45], v[94:97]
	v_mfma_f32_16x16x32_bf16 v[78:81], v[54:57], v[74:77], v[98:101]
	v_mfma_f32_16x16x32_bf16 v[86:89], v[6:9], v[74:77], v[86:89]
	v_mfma_f32_16x16x32_bf16 v[94:97], v[54:57], v[82:85], v[106:109]
	v_mfma_f32_16x16x32_bf16 v[70:73], v[6:9], v[82:85], v[70:73]
	v_mfma_f32_16x16x32_bf16 v[66:69], v[54:57], v[90:93], v[66:69]
	v_mfma_f32_16x16x32_bf16 v[62:65], v[6:9], v[90:93], v[62:65]
	v_mfma_f32_16x16x32_bf16 v[50:53], v[54:57], v[102:105], v[50:53]
	v_mfma_f32_16x16x32_bf16 v[46:49], v[6:9], v[102:105], v[46:49]
	v_mfma_f32_16x16x32_bf16 v[110:113], v[54:57], v[126:129], v[110:113]
	v_mfma_f32_16x16x32_bf16 v[134:137], v[6:9], v[126:129], v[114:117]
	s_waitcnt lgkmcnt(1)
; #define CONV_LOADA(e_, k_) do { const int xh_ = min(32 * (e_) + xa, L - 8); rh[k_] = *(const u32x4a4*)(Rc + xh_); asm volatile("" ::: "memory"); rl[k_] = *(const unsigned*)(Rc + xh_ - 2); } while (0)
; #define CONV_BLOCK(DO0, DO1) do { CONV_STEP(0, DO0, DO1); CONV_STEP(1, DO0, DO1); CONV_STEP(2, DO0, DO1); CONV_STEP(3, DO0, DO1); CONV_STEP(4, DO0, DO1); CONV_STEP(5, DO0, DO1); CONV_STEP(6, DO0, DO1); CONV_STEP(7, DO0, DO1); } while (0)
; template <bool PROMPT, int HALF>
; __device__ __forceinline__ void conv_item(unsigned char* ws, KArgs ka, int ib, int oct, int g, LAS unsigned char* lds, int tid, int lane, int wave) {
;     ...
; #pragma unroll
;     for (int k = 0; k < DA; ++k) CONV_LOADA(E0 + k, k);
;     { unsigned zz_ = 0u; asm volatile("" : "+v"(zz_));
; #pragma unroll
;       for (int k = 0; k < W; ++k) F1[k] = (u32x4){zz_, zz_, zz_, zz_}; }
;     for (int e = E0; e < E1; e += 8) CONV_BLOCK(false, true);
;     { unsigned zz_ = 0u; asm volatile("" : "+v"(zz_));
; #pragma unroll
;       for (int k = 0; k < W; ++k) F0[k] = (u32x4){zz_, zz_, zz_, zz_}; }
;     for (int e = E1; e < E2; e += 8) CONV_BLOCK(true, true);
	v_mfma_f32_16x16x32_bf16 v[58:61], v[54:57], v[142:145], v[58:61]
	v_mfma_f32_16x16x32_bf16 v[138:141], v[6:9], v[142:145], v[14:17]
	v_mfma_f32_16x16x32_bf16 v[146:149], v[10:13], v[26:29], v[2:5]
	s_nop 0
	s_nop 1
	v_add_u32_e32 v2, 0xfffffb40, v215
	v_min_i32_e32 v2, 0x7f8, v2
	v_ashrrev_i32_e32 v3, 31, v2
	v_lshl_add_u64 v[2:3], v[2:3], 1, s[10:11]
	global_load_dwordx4 v[166:169], v[2:3], off
	global_load_dword v220, v[2:3], off offset:-4
	s_waitcnt vmcnt(4)
	v_perm_b32 v2, v118, v38, s67
	v_perm_b32 v3, v38, v39, s67
	v_perm_b32 v4, v39, v40, s67
	v_perm_b32 v5, v40, v41, s67
	s_nop 0
	v_mfma_f32_16x16x32_bf16 v[34:37], v[54:57], v[34:37], v[146:149]
	v_mfma_f32_16x16x32_bf16 v[130:133], v[2:5], v[42:45], v[18:21]
	v_mfma_f32_16x16x32_bf16 v[18:21], v[2:5], v[126:129], v[46:49]
	s_nop 2
	v_mad_u32_u24 v46, v216, s58, v0
	ds_read_b128 v[158:161], v46
	v_mfma_f32_16x16x32_bf16 v[122:125], v[38:41], v[74:77], v[22:25]
	v_mfma_f32_16x16x32_bf16 v[118:121], v[2:5], v[74:77], v[30:33]
	v_mfma_f32_16x16x32_bf16 v[114:117], v[38:41], v[82:85], v[78:81]
	v_mfma_f32_16x16x32_bf16 v[106:109], v[2:5], v[82:85], v[86:89]
	v_mfma_f32_16x16x32_bf16 v[98:101], v[38:41], v[90:93], v[94:97]
	v_mfma_f32_16x16x32_bf16 v[94:97], v[2:5], v[90:93], v[70:73]
	v_mfma_f32_16x16x32_bf16 v[30:33], v[38:41], v[102:105], v[66:69]
	v_mfma_f32_16x16x32_bf16 v[26:29], v[2:5], v[102:105], v[62:65]
	v_mfma_f32_16x16x32_bf16 v[22:25], v[38:41], v[126:129], v[50:53]
	v_mfma_f32_16x16x32_bf16 v[14:17], v[38:41], v[142:145], v[110:113]
	v_mfma_f32_16x16x32_bf16 v[10:13], v[2:5], v[142:145], v[134:137]
	s_waitcnt lgkmcnt(1)
	v_mfma_f32_16x16x32_bf16 v[6:9], v[38:41], v[150:153], v[58:61]
	v_mfma_f32_16x16x32_bf16 v[2:5], v[2:5], v[150:153], v[138:141]
	v_mfma_f32_16x16x32_bf16 v[138:141], v[38:41], v[42:45], v[34:37]
	s_nop 0
	v_mov_b32_e32 v66, v1
	s_nop 0
	v_mov_b32_e32 v34, 0
	v_add_u32_e32 v218, 0xfffffb60, v215
	s_movk_i32 s19, 0xffd1
	s_movk_i32 s22, 0xf640
	v_mov_b32_e32 v35, v34
	v_mov_b32_e32 v36, v34
	v_mov_b32_e32 v37, v34
	v_mov_b32_e32 v38, v34
	v_mov_b32_e32 v39, v34
	v_mov_b32_e32 v40, v34
	v_mov_b32_e32 v41, v34
	v_mov_b32_e32 v46, v34
	v_mov_b32_e32 v47, v34
	v_mov_b32_e32 v48, v34
	v_mov_b32_e32 v49, v34
	v_mov_b32_e32 v54, v34
	v_mov_b32_e32 v55, v34
	v_mov_b32_e32 v56, v34
	v_mov_b32_e32 v57, v34
	v_mov_b32_e32 v170, v34
	v_mov_b32_e32 v171, v34
	v_mov_b32_e32 v172, v34
	v_mov_b32_e32 v173, v34
	v_mov_b32_e32 v174, v34
	v_mov_b32_e32 v175, v34
	v_mov_b32_e32 v176, v34
	v_mov_b32_e32 v177, v34
	v_mov_b32_e32 v182, v34
	v_mov_b32_e32 v183, v34
	v_mov_b32_e32 v184, v34
	v_mov_b32_e32 v185, v34
	v_mov_b32_e32 v190, v34
	v_mov_b32_e32 v191, v34
	v_mov_b32_e32 v192, v34
	v_mov_b32_e32 v193, v34
	v_mov_b32_e32 v42, v34
	v_mov_b32_e32 v43, v34
	v_mov_b32_e32 v44, v34
	v_mov_b32_e32 v45, v34
	v_mov_b32_e32 v50, v34
	v_mov_b32_e32 v51, v34
	v_mov_b32_e32 v52, v34
	v_mov_b32_e32 v53, v34
	v_mov_b32_e32 v58, v34
	v_mov_b32_e32 v59, v34
	v_mov_b32_e32 v60, v34
	v_mov_b32_e32 v61, v34
	v_mov_b32_e32 v62, v34
	v_mov_b32_e32 v63, v34
	v_mov_b32_e32 v64, v34
	v_mov_b32_e32 v65, v34
	v_mov_b32_e32 v178, v34
	v_mov_b32_e32 v179, v34
	v_mov_b32_e32 v180, v34
	v_mov_b32_e32 v181, v34
	v_mov_b32_e32 v186, v34
	v_mov_b32_e32 v187, v34
	v_mov_b32_e32 v188, v34
	v_mov_b32_e32 v189, v34
	v_mov_b32_e32 v198, v34
	v_mov_b32_e32 v199, v34
	v_mov_b32_e32 v200, v34
	v_mov_b32_e32 v201, v34
	v_mov_b32_e32 v194, v34
	v_mov_b32_e32 v195, v34
	v_mov_b32_e32 v196, v34
	v_mov_b32_e32 v197, v34
	v_mov_b32_e32 v67, v66
	v_mov_b32_e32 v68, v66
	v_mov_b32_e32 v69, v66
	v_mov_b32_e32 v70, v66
	v_mov_b32_e32 v71, v66
	v_mov_b32_e32 v72, v66
	v_mov_b32_e32 v73, v66
	v_mov_b32_e32 v78, v66
	v_mov_b32_e32 v79, v66
	v_mov_b32_e32 v80, v66
	v_mov_b32_e32 v81, v66
	v_mov_b32_e32 v86, v66
	v_mov_b32_e32 v87, v66
	v_mov_b32_e32 v88, v66
	v_mov_b32_e32 v89, v66
	v_mov_b32_e32 v110, v66
	v_mov_b32_e32 v111, v66
	v_mov_b32_e32 v112, v66
	v_mov_b32_e32 v113, v66
	v_mov_b32_e32 v134, v66
	v_mov_b32_e32 v135, v66
	v_mov_b32_e32 v136, v66
	v_mov_b32_e32 v137, v66
	v_mov_b32_e32 v146, v66
	v_mov_b32_e32 v147, v66
	v_mov_b32_e32 v148, v66
	v_mov_b32_e32 v149, v66
	v_mov_b32_e32 v154, v66
	v_mov_b32_e32 v155, v66
	v_mov_b32_e32 v156, v66
	v_mov_b32_e32 v157, v66
.LBB0_732:
	v_min_i32_e32 v210, 0x7f8, v218
	v_ashrrev_i32_e32 v211, 31, v210
	v_lshl_add_u64 v[210:211], v[210:211], 1, s[10:11]
	global_load_dwordx4 v[222:225], v[210:211], off
	global_load_dword v221, v[210:211], off offset:-4
	s_waitcnt vmcnt(4)
	v_perm_b32 v226, v219, v162, s67
	v_perm_b32 v227, v162, v163, s67
	v_perm_b32 v228, v163, v164, s67
	v_perm_b32 v229, v164, v165, s67
	s_nop 0
	s_add_i32 s23, s19, 16
	s_ashr_i32 s23, s23, 3
	v_mfma_f32_16x16x32_bf16 v[138:141], v[162:165], v[74:77], v[138:141]
	s_and_b32 s30, s22, 0x1c0
	v_mfma_f32_16x16x32_bf16 v[130:133], v[226:229], v[74:77], v[130:133]
	v_add_u32_e32 v74, s23, v216
	v_add_u32_e32 v75, s23, v217
	v_cmp_gt_u32_e32 vcc, 8, v74
	v_mfma_f32_16x16x32_bf16 v[194:197], v[162:165], v[154:157], v[194:197]
	s_nop 0
	v_cndmask_b32_e32 v74, v214, v74, vcc
	v_cmp_gt_u32_e32 vcc, 8, v75
	v_mul_lo_u32 v74, v74, s58
	v_add3_u32 v74, v0, v74, s30
	v_cndmask_b32_e32 v75, v214, v75, vcc
	v_mul_lo_u32 v75, v75, s58
	v_add3_u32 v75, v0, v75, s30
	v_mfma_f32_16x16x32_bf16 v[190:193], v[226:229], v[154:157], v[190:193]
	ds_read_b128 v[154:157], v74
	ds_read_b128 v[74:77], v75
	v_mfma_f32_16x16x32_bf16 v[198:201], v[162:165], v[146:149], v[198:201]
	v_mfma_f32_16x16x32_bf16 v[182:185], v[226:229], v[146:149], v[182:185]
	v_mfma_f32_16x16x32_bf16 v[122:125], v[162:165], v[82:85], v[122:125]
	v_mfma_f32_16x16x32_bf16 v[118:121], v[226:229], v[82:85], v[118:121]
	v_mfma_f32_16x16x32_bf16 v[186:189], v[162:165], v[134:137], v[186:189]
	v_mfma_f32_16x16x32_bf16 v[174:177], v[226:229], v[134:137], v[174:177]
	v_mfma_f32_16x16x32_bf16 v[114:117], v[162:165], v[90:93], v[114:117]
	v_mfma_f32_16x16x32_bf16 v[106:109], v[226:229], v[90:93], v[106:109]
	v_mfma_f32_16x16x32_bf16 v[178:181], v[162:165], v[110:113], v[178:181]
	v_mfma_f32_16x16x32_bf16 v[170:173], v[226:229], v[110:113], v[170:173]
	v_mfma_f32_16x16x32_bf16 v[98:101], v[162:165], v[102:105], v[98:101]
	v_mfma_f32_16x16x32_bf16 v[94:97], v[226:229], v[102:105], v[94:97]
	v_mfma_f32_16x16x32_bf16 v[62:65], v[162:165], v[86:89], v[62:65]
	v_mfma_f32_16x16x32_bf16 v[54:57], v[226:229], v[86:89], v[54:57]
	v_mfma_f32_16x16x32_bf16 v[30:33], v[162:165], v[126:129], v[30:33]
	v_mfma_f32_16x16x32_bf16 v[26:29], v[226:229], v[126:129], v[26:29]
	v_mfma_f32_16x16x32_bf16 v[58:61], v[162:165], v[78:81], v[58:61]
	v_mfma_f32_16x16x32_bf16 v[46:49], v[226:229], v[78:81], v[46:49]
	v_mfma_f32_16x16x32_bf16 v[22:25], v[162:165], v[142:145], v[22:25]
	v_mfma_f32_16x16x32_bf16 v[18:21], v[226:229], v[142:145], v[18:21]
	v_mfma_f32_16x16x32_bf16 v[50:53], v[162:165], v[70:73], v[50:53]
	v_mfma_f32_16x16x32_bf16 v[38:41], v[226:229], v[70:73], v[38:41]
	v_mfma_f32_16x16x32_bf16 v[14:17], v[162:165], v[150:153], v[14:17]
	v_mfma_f32_16x16x32_bf16 v[10:13], v[226:229], v[150:153], v[10:13]
	s_waitcnt lgkmcnt(3)
	v_mfma_f32_16x16x32_bf16 v[42:45], v[162:165], v[66:69], v[42:45]
	v_mfma_f32_16x16x32_bf16 v[34:37], v[226:229], v[66:69], v[34:37]
	s_waitcnt lgkmcnt(2)
	v_mfma_f32_16x16x32_bf16 v[6:9], v[162:165], v[158:161], v[6:9]
	v_mfma_f32_16x16x32_bf16 v[2:5], v[226:229], v[158:161], v[2:5]
	s_nop 0
	v_add_u32_e32 v162, 32, v218
	v_min_i32_e32 v162, 0x7f8, v162
	v_ashrrev_i32_e32 v163, 31, v162
	v_lshl_add_u64 v[210:211], v[162:163], 1, s[10:11]
	global_load_dwordx4 v[162:165], v[210:211], off
	global_load_dword v219, v[210:211], off offset:-4
	s_waitcnt vmcnt(4)
	v_perm_b32 v226, v220, v166, s67
	v_perm_b32 v227, v166, v167, s67
	v_perm_b32 v228, v167, v168, s67
	v_perm_b32 v229, v168, v169, s67
	s_nop 0
	s_add_i32 s23, s19, 17
	s_ashr_i32 s23, s23, 3
	v_mfma_f32_16x16x32_bf16 v[138:141], v[166:169], v[82:85], v[138:141]
	s_add_i32 s30, s22, 0x240
	s_and_b32 s30, s30, 0x1c0
	v_mfma_f32_16x16x32_bf16 v[130:133], v[226:229], v[82:85], v[130:133]
	v_add_u32_e32 v82, s23, v216
	v_add_u32_e32 v83, s23, v217
	v_cmp_gt_u32_e32 vcc, 8, v82
	v_mfma_f32_16x16x32_bf16 v[194:197], v[166:169], v[146:149], v[194:197]
	s_nop 0
	v_cndmask_b32_e32 v82, v214, v82, vcc
	v_cmp_gt_u32_e32 vcc, 8, v83
	v_mul_lo_u32 v82, v82, s58
	v_add3_u32 v82, v0, v82, s30
	v_cndmask_b32_e32 v83, v214, v83, vcc
	v_mul_lo_u32 v83, v83, s58
	v_add3_u32 v83, v0, v83, s30
	v_mfma_f32_16x16x32_bf16 v[190:193], v[226:229], v[146:149], v[190:193]
	ds_read_b128 v[146:149], v82
	ds_read_b128 v[82:85], v83
	v_mfma_f32_16x16x32_bf16 v[198:201], v[166:169], v[134:137], v[198:201]
	v_mfma_f32_16x16x32_bf16 v[182:185], v[226:229], v[134:137], v[182:185]
	v_mfma_f32_16x16x32_bf16 v[122:125], v[166:169], v[90:93], v[122:125]
	v_mfma_f32_16x16x32_bf16 v[118:121], v[226:229], v[90:93], v[118:121]
	v_mfma_f32_16x16x32_bf16 v[186:189], v[166:169], v[110:113], v[186:189]
	v_mfma_f32_16x16x32_bf16 v[174:177], v[226:229], v[110:113], v[174:177]
	v_mfma_f32_16x16x32_bf16 v[114:117], v[166:169], v[102:105], v[114:117]
	v_mfma_f32_16x16x32_bf16 v[106:109], v[226:229], v[102:105], v[106:109]
	v_mfma_f32_16x16x32_bf16 v[178:181], v[166:169], v[86:89], v[178:181]
	v_mfma_f32_16x16x32_bf16 v[170:173], v[226:229], v[86:89], v[170:173]
	v_mfma_f32_16x16x32_bf16 v[98:101], v[166:169], v[126:129], v[98:101]
	v_mfma_f32_16x16x32_bf16 v[94:97], v[226:229], v[126:129], v[94:97]
	v_mfma_f32_16x16x32_bf16 v[62:65], v[166:169], v[78:81], v[62:65]
	v_mfma_f32_16x16x32_bf16 v[54:57], v[226:229], v[78:81], v[54:57]
	v_mfma_f32_16x16x32_bf16 v[30:33], v[166:169], v[142:145], v[30:33]
	v_mfma_f32_16x16x32_bf16 v[26:29], v[226:229], v[142:145], v[26:29]
	v_mfma_f32_16x16x32_bf16 v[58:61], v[166:169], v[70:73], v[58:61]
	v_mfma_f32_16x16x32_bf16 v[46:49], v[226:229], v[70:73], v[46:49]
	v_mfma_f32_16x16x32_bf16 v[22:25], v[166:169], v[150:153], v[22:25]
	v_mfma_f32_16x16x32_bf16 v[18:21], v[226:229], v[150:153], v[18:21]
	v_mfma_f32_16x16x32_bf16 v[50:53], v[166:169], v[66:69], v[50:53]
	v_mfma_f32_16x16x32_bf16 v[38:41], v[226:229], v[66:69], v[38:41]
	v_mfma_f32_16x16x32_bf16 v[14:17], v[166:169], v[158:161], v[14:17]
	v_mfma_f32_16x16x32_bf16 v[10:13], v[226:229], v[158:161], v[10:13]
	s_waitcnt lgkmcnt(3)
	v_mfma_f32_16x16x32_bf16 v[42:45], v[166:169], v[154:157], v[42:45]
	v_mfma_f32_16x16x32_bf16 v[34:37], v[226:229], v[154:157], v[34:37]
	s_waitcnt lgkmcnt(2)
	v_mfma_f32_16x16x32_bf16 v[6:9], v[166:169], v[74:77], v[6:9]
	v_mfma_f32_16x16x32_bf16 v[2:5], v[226:229], v[74:77], v[2:5]
	s_nop 0
	v_add_u32_e32 v166, 64, v218
	v_min_i32_e32 v166, 0x7f8, v166
	v_ashrrev_i32_e32 v167, 31, v166
	v_lshl_add_u64 v[210:211], v[166:167], 1, s[10:11]
	global_load_dwordx4 v[166:169], v[210:211], off
	global_load_dword v230, v[210:211], off offset:-4
	s_waitcnt vmcnt(4)
	v_perm_b32 v226, v221, v222, s67
	v_perm_b32 v227, v222, v223, s67
	v_perm_b32 v228, v223, v224, s67
	v_perm_b32 v229, v224, v225, s67
	s_nop 0
	s_add_i32 s23, s19, 18
	s_ashr_i32 s23, s23, 3
	v_mfma_f32_16x16x32_bf16 v[138:141], v[222:225], v[90:93], v[138:141]
	s_add_i32 s30, s22, 0x280
	s_and_b32 s30, s30, 0x1c0
	v_mfma_f32_16x16x32_bf16 v[130:133], v[226:229], v[90:93], v[130:133]
	v_add_u32_e32 v90, s23, v216
	v_add_u32_e32 v91, s23, v217
	v_cmp_gt_u32_e32 vcc, 8, v90
	v_mfma_f32_16x16x32_bf16 v[194:197], v[222:225], v[134:137], v[194:197]
	s_nop 0
	v_cndmask_b32_e32 v90, v214, v90, vcc
	v_cmp_gt_u32_e32 vcc, 8, v91
	v_mul_lo_u32 v90, v90, s58
	v_add3_u32 v90, v0, v90, s30
	v_cndmask_b32_e32 v91, v214, v91, vcc
	v_mul_lo_u32 v91, v91, s58
	v_add3_u32 v91, v0, v91, s30
	v_mfma_f32_16x16x32_bf16 v[190:193], v[226:229], v[134:137], v[190:193]
	ds_read_b128 v[134:137], v90
	ds_read_b128 v[90:93], v91
	v_mfma_f32_16x16x32_bf16 v[198:201], v[222:225], v[110:113], v[198:201]
	v_mfma_f32_16x16x32_bf16 v[182:185], v[226:229], v[110:113], v[182:185]
	v_mfma_f32_16x16x32_bf16 v[122:125], v[222:225], v[102:105], v[122:125]
	v_mfma_f32_16x16x32_bf16 v[118:121], v[226:229], v[102:105], v[118:121]
	v_mfma_f32_16x16x32_bf16 v[186:189], v[222:225], v[86:89], v[186:189]
	v_mfma_f32_16x16x32_bf16 v[174:177], v[226:229], v[86:89], v[174:177]
	v_mfma_f32_16x16x32_bf16 v[114:117], v[222:225], v[126:129], v[114:117]
	v_mfma_f32_16x16x32_bf16 v[106:109], v[226:229], v[126:129], v[106:109]
	v_mfma_f32_16x16x32_bf16 v[178:181], v[222:225], v[78:81], v[178:181]
	v_mfma_f32_16x16x32_bf16 v[170:173], v[226:229], v[78:81], v[170:173]
	v_mfma_f32_16x16x32_bf16 v[98:101], v[222:225], v[142:145], v[98:101]
	v_mfma_f32_16x16x32_bf16 v[94:97], v[226:229], v[142:145], v[94:97]
	v_mfma_f32_16x16x32_bf16 v[62:65], v[222:225], v[70:73], v[62:65]
	v_mfma_f32_16x16x32_bf16 v[54:57], v[226:229], v[70:73], v[54:57]
	v_mfma_f32_16x16x32_bf16 v[30:33], v[222:225], v[150:153], v[30:33]
	v_mfma_f32_16x16x32_bf16 v[26:29], v[226:229], v[150:153], v[26:29]
	v_mfma_f32_16x16x32_bf16 v[58:61], v[222:225], v[66:69], v[58:61]
	v_mfma_f32_16x16x32_bf16 v[46:49], v[226:229], v[66:69], v[46:49]
	v_mfma_f32_16x16x32_bf16 v[22:25], v[222:225], v[158:161], v[22:25]
	v_mfma_f32_16x16x32_bf16 v[18:21], v[226:229], v[158:161], v[18:21]
	v_mfma_f32_16x16x32_bf16 v[50:53], v[222:225], v[154:157], v[50:53]
	v_mfma_f32_16x16x32_bf16 v[38:41], v[226:229], v[154:157], v[38:41]
	v_mfma_f32_16x16x32_bf16 v[14:17], v[222:225], v[74:77], v[14:17]
	v_mfma_f32_16x16x32_bf16 v[10:13], v[226:229], v[74:77], v[10:13]
	s_waitcnt lgkmcnt(3)
	v_mfma_f32_16x16x32_bf16 v[42:45], v[222:225], v[146:149], v[42:45]
	v_mfma_f32_16x16x32_bf16 v[34:37], v[226:229], v[146:149], v[34:37]
	s_waitcnt lgkmcnt(2)
	v_mfma_f32_16x16x32_bf16 v[6:9], v[222:225], v[82:85], v[6:9]
	v_mfma_f32_16x16x32_bf16 v[2:5], v[226:229], v[82:85], v[2:5]
	s_nop 0
	v_add_u32_e32 v210, 0x60, v218
	v_min_i32_e32 v210, 0x7f8, v210
	v_ashrrev_i32_e32 v211, 31, v210
	v_lshl_add_u64 v[210:211], v[210:211], 1, s[10:11]
	global_load_dwordx4 v[220:223], v[210:211], off
	global_load_dword v210, v[210:211], off offset:-4
	s_waitcnt vmcnt(4)
	v_perm_b32 v224, v219, v162, s67
	v_perm_b32 v225, v162, v163, s67
	v_perm_b32 v226, v163, v164, s67
	v_perm_b32 v227, v164, v165, s67
	s_nop 0
	s_add_i32 s23, s19, 19
	s_ashr_i32 s23, s23, 3
	v_mfma_f32_16x16x32_bf16 v[138:141], v[162:165], v[102:105], v[138:141]
	s_add_i32 s30, s22, 0x2c0
	s_and_b32 s30, s30, 0x1c0
	v_mfma_f32_16x16x32_bf16 v[130:133], v[224:227], v[102:105], v[130:133]
	v_add_u32_e32 v102, s23, v216
	v_add_u32_e32 v103, s23, v217
	v_cmp_gt_u32_e32 vcc, 8, v102
	v_mfma_f32_16x16x32_bf16 v[194:197], v[162:165], v[110:113], v[194:197]
	s_nop 0
	v_cndmask_b32_e32 v102, v214, v102, vcc
	v_cmp_gt_u32_e32 vcc, 8, v103
	v_mul_lo_u32 v102, v102, s58
	v_add3_u32 v102, v0, v102, s30
	v_cndmask_b32_e32 v103, v214, v103, vcc
	v_mul_lo_u32 v103, v103, s58
	v_add3_u32 v103, v0, v103, s30
	v_mfma_f32_16x16x32_bf16 v[190:193], v[224:227], v[110:113], v[190:193]
	ds_read_b128 v[110:113], v102
	ds_read_b128 v[102:105], v103
	v_mfma_f32_16x16x32_bf16 v[198:201], v[162:165], v[86:89], v[198:201]
	v_mfma_f32_16x16x32_bf16 v[182:185], v[224:227], v[86:89], v[182:185]
	v_mfma_f32_16x16x32_bf16 v[122:125], v[162:165], v[126:129], v[122:125]
	v_mfma_f32_16x16x32_bf16 v[118:121], v[224:227], v[126:129], v[118:121]
	v_mfma_f32_16x16x32_bf16 v[186:189], v[162:165], v[78:81], v[186:189]
	v_mfma_f32_16x16x32_bf16 v[174:177], v[224:227], v[78:81], v[174:177]
	v_mfma_f32_16x16x32_bf16 v[114:117], v[162:165], v[142:145], v[114:117]
	v_mfma_f32_16x16x32_bf16 v[106:109], v[224:227], v[142:145], v[106:109]
	v_mfma_f32_16x16x32_bf16 v[178:181], v[162:165], v[70:73], v[178:181]
	v_mfma_f32_16x16x32_bf16 v[170:173], v[224:227], v[70:73], v[170:173]
	v_mfma_f32_16x16x32_bf16 v[98:101], v[162:165], v[150:153], v[98:101]
	v_mfma_f32_16x16x32_bf16 v[94:97], v[224:227], v[150:153], v[94:97]
	v_mfma_f32_16x16x32_bf16 v[62:65], v[162:165], v[66:69], v[62:65]
	v_mfma_f32_16x16x32_bf16 v[54:57], v[224:227], v[66:69], v[54:57]
	v_mfma_f32_16x16x32_bf16 v[30:33], v[162:165], v[158:161], v[30:33]
	v_mfma_f32_16x16x32_bf16 v[26:29], v[224:227], v[158:161], v[26:29]
	v_mfma_f32_16x16x32_bf16 v[58:61], v[162:165], v[154:157], v[58:61]
	v_mfma_f32_16x16x32_bf16 v[46:49], v[224:227], v[154:157], v[46:49]
	v_mfma_f32_16x16x32_bf16 v[22:25], v[162:165], v[74:77], v[22:25]
	v_mfma_f32_16x16x32_bf16 v[18:21], v[224:227], v[74:77], v[18:21]
	v_mfma_f32_16x16x32_bf16 v[50:53], v[162:165], v[146:149], v[50:53]
	v_mfma_f32_16x16x32_bf16 v[38:41], v[224:227], v[146:149], v[38:41]
	v_mfma_f32_16x16x32_bf16 v[14:17], v[162:165], v[82:85], v[14:17]
	v_mfma_f32_16x16x32_bf16 v[10:13], v[224:227], v[82:85], v[10:13]
	s_waitcnt lgkmcnt(3)
	v_mfma_f32_16x16x32_bf16 v[42:45], v[162:165], v[134:137], v[42:45]
	v_mfma_f32_16x16x32_bf16 v[34:37], v[224:227], v[134:137], v[34:37]
	s_waitcnt lgkmcnt(2)
	v_mfma_f32_16x16x32_bf16 v[6:9], v[162:165], v[90:93], v[6:9]
	v_mfma_f32_16x16x32_bf16 v[2:5], v[224:227], v[90:93], v[2:5]
	s_nop 0
	v_add_u32_e32 v162, 0x80, v218
	v_min_i32_e32 v162, 0x7f8, v162
	v_ashrrev_i32_e32 v163, 31, v162
	v_lshl_add_u64 v[162:163], v[162:163], 1, s[10:11]
	global_load_dwordx4 v[224:227], v[162:163], off
	global_load_dword v211, v[162:163], off offset:-4
	s_waitcnt vmcnt(4)
	v_perm_b32 v162, v230, v166, s67
	v_perm_b32 v163, v166, v167, s67
	v_perm_b32 v164, v167, v168, s67
	v_perm_b32 v165, v168, v169, s67
	s_nop 0
	s_add_i32 s23, s19, 20
	s_ashr_i32 s23, s23, 3
	v_mfma_f32_16x16x32_bf16 v[194:197], v[166:169], v[86:89], v[194:197]
	s_add_i32 s30, s22, 0x300
	s_and_b32 s30, s30, 0x1c0
	v_mfma_f32_16x16x32_bf16 v[190:193], v[162:165], v[86:89], v[190:193]
	v_add_u32_e32 v86, s23, v216
	v_add_u32_e32 v87, s23, v217
	v_cmp_gt_u32_e32 vcc, 8, v86
	v_mfma_f32_16x16x32_bf16 v[138:141], v[166:169], v[126:129], v[138:141]
	s_nop 0
	v_cndmask_b32_e32 v86, v214, v86, vcc
	v_cmp_gt_u32_e32 vcc, 8, v87
	v_mul_lo_u32 v86, v86, s58
	v_mfma_f32_16x16x32_bf16 v[130:133], v[162:165], v[126:129], v[130:133]
	v_cndmask_b32_e32 v87, v214, v87, vcc
	v_mul_lo_u32 v87, v87, s58
	v_add3_u32 v86, v0, v86, s30
	v_add3_u32 v126, v0, v87, s30
	ds_read_b128 v[86:89], v86
	ds_read_b128 v[126:129], v126
	v_mfma_f32_16x16x32_bf16 v[198:201], v[166:169], v[78:81], v[198:201]
	v_mfma_f32_16x16x32_bf16 v[182:185], v[162:165], v[78:81], v[182:185]
	v_mfma_f32_16x16x32_bf16 v[122:125], v[166:169], v[142:145], v[122:125]
	v_mfma_f32_16x16x32_bf16 v[118:121], v[162:165], v[142:145], v[118:121]
	v_mfma_f32_16x16x32_bf16 v[186:189], v[166:169], v[70:73], v[186:189]
	v_mfma_f32_16x16x32_bf16 v[174:177], v[162:165], v[70:73], v[174:177]
	v_mfma_f32_16x16x32_bf16 v[114:117], v[166:169], v[150:153], v[114:117]
	v_mfma_f32_16x16x32_bf16 v[106:109], v[162:165], v[150:153], v[106:109]
	v_mfma_f32_16x16x32_bf16 v[178:181], v[166:169], v[66:69], v[178:181]
	v_mfma_f32_16x16x32_bf16 v[170:173], v[162:165], v[66:69], v[170:173]
	v_mfma_f32_16x16x32_bf16 v[98:101], v[166:169], v[158:161], v[98:101]
	v_mfma_f32_16x16x32_bf16 v[94:97], v[162:165], v[158:161], v[94:97]
	v_mfma_f32_16x16x32_bf16 v[62:65], v[166:169], v[154:157], v[62:65]
	v_mfma_f32_16x16x32_bf16 v[54:57], v[162:165], v[154:157], v[54:57]
	v_mfma_f32_16x16x32_bf16 v[30:33], v[166:169], v[74:77], v[30:33]
	v_mfma_f32_16x16x32_bf16 v[26:29], v[162:165], v[74:77], v[26:29]
	v_mfma_f32_16x16x32_bf16 v[58:61], v[166:169], v[146:149], v[58:61]
	v_mfma_f32_16x16x32_bf16 v[46:49], v[162:165], v[146:149], v[46:49]
	v_mfma_f32_16x16x32_bf16 v[22:25], v[166:169], v[82:85], v[22:25]
	v_mfma_f32_16x16x32_bf16 v[18:21], v[162:165], v[82:85], v[18:21]
	v_mfma_f32_16x16x32_bf16 v[50:53], v[166:169], v[134:137], v[50:53]
	v_mfma_f32_16x16x32_bf16 v[38:41], v[162:165], v[134:137], v[38:41]
	v_mfma_f32_16x16x32_bf16 v[14:17], v[166:169], v[90:93], v[14:17]
	v_mfma_f32_16x16x32_bf16 v[10:13], v[162:165], v[90:93], v[10:13]
	s_waitcnt lgkmcnt(3)
	v_mfma_f32_16x16x32_bf16 v[42:45], v[166:169], v[110:113], v[42:45]
	v_mfma_f32_16x16x32_bf16 v[34:37], v[162:165], v[110:113], v[34:37]
	s_waitcnt lgkmcnt(2)
	v_mfma_f32_16x16x32_bf16 v[6:9], v[166:169], v[102:105], v[6:9]
	v_mfma_f32_16x16x32_bf16 v[2:5], v[162:165], v[102:105], v[2:5]
	s_nop 0
	v_add_u32_e32 v162, 0xa0, v218
	v_min_i32_e32 v162, 0x7f8, v162
	v_ashrrev_i32_e32 v163, 31, v162
	v_lshl_add_u64 v[162:163], v[162:163], 1, s[10:11]
	global_load_dwordx4 v[228:231], v[162:163], off
	global_load_dword v236, v[162:163], off offset:-4
	s_waitcnt vmcnt(4)
	v_perm_b32 v162, v210, v220, s67
	v_perm_b32 v163, v220, v221, s67
	v_perm_b32 v164, v221, v222, s67
	v_perm_b32 v165, v222, v223, s67
	s_nop 0
	s_add_i32 s23, s19, 21
	s_ashr_i32 s23, s23, 3
	v_mfma_f32_16x16x32_bf16 v[166:169], v[220:223], v[78:81], v[194:197]
	s_add_i32 s30, s22, 0x340
	s_and_b32 s30, s30, 0x1c0
	v_mfma_f32_16x16x32_bf16 v[190:193], v[162:165], v[78:81], v[190:193]
	v_add_u32_e32 v78, s23, v216
	v_add_u32_e32 v79, s23, v217
	v_cmp_gt_u32_e32 vcc, 8, v78
	v_mfma_f32_16x16x32_bf16 v[138:141], v[220:223], v[142:145], v[138:141]
	s_nop 0
	v_cndmask_b32_e32 v78, v214, v78, vcc
	v_cmp_gt_u32_e32 vcc, 8, v79
	v_mul_lo_u32 v78, v78, s58
	v_mfma_f32_16x16x32_bf16 v[130:133], v[162:165], v[142:145], v[130:133]
	v_cndmask_b32_e32 v79, v214, v79, vcc
	v_mul_lo_u32 v79, v79, s58
	v_add3_u32 v78, v0, v78, s30
	v_add3_u32 v142, v0, v79, s30
	ds_read_b128 v[78:81], v78
	ds_read_b128 v[142:145], v142
	v_mfma_f32_16x16x32_bf16 v[194:197], v[220:223], v[70:73], v[198:201]
	v_mfma_f32_16x16x32_bf16 v[182:185], v[162:165], v[70:73], v[182:185]
	v_mfma_f32_16x16x32_bf16 v[122:125], v[220:223], v[150:153], v[122:125]
	v_mfma_f32_16x16x32_bf16 v[118:121], v[162:165], v[150:153], v[118:121]
	v_mfma_f32_16x16x32_bf16 v[186:189], v[220:223], v[66:69], v[186:189]
	v_mfma_f32_16x16x32_bf16 v[174:177], v[162:165], v[66:69], v[174:177]
	v_mfma_f32_16x16x32_bf16 v[114:117], v[220:223], v[158:161], v[114:117]
	v_mfma_f32_16x16x32_bf16 v[106:109], v[162:165], v[158:161], v[106:109]
	v_mfma_f32_16x16x32_bf16 v[178:181], v[220:223], v[154:157], v[178:181]
	v_mfma_f32_16x16x32_bf16 v[170:173], v[162:165], v[154:157], v[170:173]
	v_mfma_f32_16x16x32_bf16 v[98:101], v[220:223], v[74:77], v[98:101]
	v_mfma_f32_16x16x32_bf16 v[94:97], v[162:165], v[74:77], v[94:97]
	v_mfma_f32_16x16x32_bf16 v[62:65], v[220:223], v[146:149], v[62:65]
	v_mfma_f32_16x16x32_bf16 v[54:57], v[162:165], v[146:149], v[54:57]
	v_mfma_f32_16x16x32_bf16 v[30:33], v[220:223], v[82:85], v[30:33]
	v_mfma_f32_16x16x32_bf16 v[26:29], v[162:165], v[82:85], v[26:29]
	v_mfma_f32_16x16x32_bf16 v[58:61], v[220:223], v[134:137], v[58:61]
	v_mfma_f32_16x16x32_bf16 v[46:49], v[162:165], v[134:137], v[46:49]
	v_mfma_f32_16x16x32_bf16 v[22:25], v[220:223], v[90:93], v[22:25]
	v_mfma_f32_16x16x32_bf16 v[18:21], v[162:165], v[90:93], v[18:21]
	v_mfma_f32_16x16x32_bf16 v[50:53], v[220:223], v[110:113], v[50:53]
	v_mfma_f32_16x16x32_bf16 v[38:41], v[162:165], v[110:113], v[38:41]
	v_mfma_f32_16x16x32_bf16 v[14:17], v[220:223], v[102:105], v[14:17]
	v_mfma_f32_16x16x32_bf16 v[10:13], v[162:165], v[102:105], v[10:13]
	s_waitcnt lgkmcnt(3)
; #define CONV_LOADA(e_, k_) do { const int xh_ = min(32 * (e_) + xa, L - 8); rh[k_] = *(const u32x4a4*)(Rc + xh_); asm volatile("" ::: "memory"); rl[k_] = *(const unsigned*)(Rc + xh_ - 2); } while (0)
; #define CONV_BLOCK(DO0, DO1) do { CONV_STEP(0, DO0, DO1); CONV_STEP(1, DO0, DO1); CONV_STEP(2, DO0, DO1); CONV_STEP(3, DO0, DO1); CONV_STEP(4, DO0, DO1); CONV_STEP(5, DO0, DO1); CONV_STEP(6, DO0, DO1); CONV_STEP(7, DO0, DO1); } while (0)
; template <bool PROMPT, int HALF>
; __device__ __forceinline__ void conv_item(unsigned char* ws, KArgs ka, int ib, int oct, int g, LAS unsigned char* lds, int tid, int lane, int wave) {
;     ...
; #pragma unroll
;     for (int k = 0; k < DA; ++k) CONV_LOADA(E0 + k, k);
;     { unsigned zz_ = 0u; asm volatile("" : "+v"(zz_));
; #pragma unroll
;       for (int k = 0; k < W; ++k) F1[k] = (u32x4){zz_, zz_, zz_, zz_}; }
;     for (int e = E0; e < E1; e += 8) CONV_BLOCK(false, true);
;     { unsigned zz_ = 0u; asm volatile("" : "+v"(zz_));
; #pragma unroll
;       for (int k = 0; k < W; ++k) F0[k] = (u32x4){zz_, zz_, zz_, zz_}; }
;     for (int e = E1; e < E2; e += 8) CONV_BLOCK(true, true);
;     for (int e = E2; e < E3; e += 8) CONV_BLOCK(true, false);
	v_mfma_f32_16x16x32_bf16 v[42:45], v[220:223], v[86:89], v[42:45]
	v_mfma_f32_16x16x32_bf16 v[34:37], v[162:165], v[86:89], v[34:37]
	s_waitcnt lgkmcnt(2)
	v_mfma_f32_16x16x32_bf16 v[6:9], v[220:223], v[126:129], v[6:9]
	v_mfma_f32_16x16x32_bf16 v[2:5], v[162:165], v[126:129], v[2:5]
	s_nop 0
	v_add_u32_e32 v162, 0xc0, v218
	v_min_i32_e32 v162, 0x7f8, v162
	v_ashrrev_i32_e32 v163, 31, v162
	v_lshl_add_u64 v[198:199], v[162:163], 1, s[10:11]
	global_load_dwordx4 v[162:165], v[198:199], off
	global_load_dword v219, v[198:199], off offset:-4
	s_waitcnt vmcnt(4)
	v_perm_b32 v198, v211, v224, s67
	v_perm_b32 v199, v224, v225, s67
	v_perm_b32 v200, v225, v226, s67
	v_perm_b32 v201, v226, v227, s67
	s_nop 0
	s_add_i32 s23, s19, 22
	s_ashr_i32 s23, s23, 3
	v_mfma_f32_16x16x32_bf16 v[232:235], v[224:227], v[70:73], v[166:169]
	s_add_i32 s30, s22, 0x380
	s_and_b32 s30, s30, 0x1c0
	v_mfma_f32_16x16x32_bf16 v[190:193], v[198:201], v[70:73], v[190:193]
	v_add_u32_e32 v70, s23, v216
	v_add_u32_e32 v71, s23, v217
	v_cmp_gt_u32_e32 vcc, 8, v70
	v_mfma_f32_16x16x32_bf16 v[138:141], v[224:227], v[150:153], v[138:141]
	s_nop 0
	v_cndmask_b32_e32 v70, v214, v70, vcc
	v_cmp_gt_u32_e32 vcc, 8, v71
	v_mul_lo_u32 v70, v70, s58
	v_mfma_f32_16x16x32_bf16 v[130:133], v[198:201], v[150:153], v[130:133]
	v_cndmask_b32_e32 v71, v214, v71, vcc
	v_mul_lo_u32 v71, v71, s58
	v_add3_u32 v70, v0, v70, s30
	v_add3_u32 v150, v0, v71, s30
	ds_read_b128 v[70:73], v70
	ds_read_b128 v[150:153], v150
	v_mfma_f32_16x16x32_bf16 v[182:185], v[198:201], v[66:69], v[182:185]
	v_mfma_f32_16x16x32_bf16 v[122:125], v[224:227], v[158:161], v[122:125]
	v_mfma_f32_16x16x32_bf16 v[118:121], v[198:201], v[158:161], v[118:121]
	v_mfma_f32_16x16x32_bf16 v[186:189], v[224:227], v[154:157], v[186:189]
	v_mfma_f32_16x16x32_bf16 v[174:177], v[198:201], v[154:157], v[174:177]
	v_mfma_f32_16x16x32_bf16 v[114:117], v[224:227], v[74:77], v[114:117]
	v_mfma_f32_16x16x32_bf16 v[106:109], v[198:201], v[74:77], v[106:109]
	v_mfma_f32_16x16x32_bf16 v[178:181], v[224:227], v[146:149], v[178:181]
	v_mfma_f32_16x16x32_bf16 v[170:173], v[198:201], v[146:149], v[170:173]
	v_mfma_f32_16x16x32_bf16 v[98:101], v[224:227], v[82:85], v[98:101]
	v_mfma_f32_16x16x32_bf16 v[94:97], v[198:201], v[82:85], v[94:97]
	v_mfma_f32_16x16x32_bf16 v[62:65], v[224:227], v[134:137], v[62:65]
	v_mfma_f32_16x16x32_bf16 v[54:57], v[198:201], v[134:137], v[54:57]
	v_mfma_f32_16x16x32_bf16 v[30:33], v[224:227], v[90:93], v[30:33]
	v_mfma_f32_16x16x32_bf16 v[26:29], v[198:201], v[90:93], v[26:29]
	v_mfma_f32_16x16x32_bf16 v[58:61], v[224:227], v[110:113], v[58:61]
	v_mfma_f32_16x16x32_bf16 v[46:49], v[198:201], v[110:113], v[46:49]
	v_mfma_f32_16x16x32_bf16 v[22:25], v[224:227], v[102:105], v[22:25]
	v_mfma_f32_16x16x32_bf16 v[18:21], v[198:201], v[102:105], v[18:21]
	v_mfma_f32_16x16x32_bf16 v[50:53], v[224:227], v[86:89], v[50:53]
	v_mfma_f32_16x16x32_bf16 v[38:41], v[198:201], v[86:89], v[38:41]
	v_mfma_f32_16x16x32_bf16 v[14:17], v[224:227], v[126:129], v[14:17]
	v_mfma_f32_16x16x32_bf16 v[10:13], v[198:201], v[126:129], v[10:13]
	s_waitcnt lgkmcnt(3)
	v_mfma_f32_16x16x32_bf16 v[42:45], v[224:227], v[78:81], v[42:45]
	v_mfma_f32_16x16x32_bf16 v[34:37], v[198:201], v[78:81], v[34:37]
	s_waitcnt lgkmcnt(2)
	v_mfma_f32_16x16x32_bf16 v[6:9], v[224:227], v[142:145], v[6:9]
	v_mfma_f32_16x16x32_bf16 v[2:5], v[198:201], v[142:145], v[2:5]
	v_mfma_f32_16x16x32_bf16 v[242:245], v[224:227], v[66:69], v[194:197]
	s_nop 0
	v_add_u32_e32 v166, 0xe0, v218
	v_min_i32_e32 v166, 0x7f8, v166
	v_ashrrev_i32_e32 v167, 31, v166
	v_lshl_add_u64 v[194:195], v[166:167], 1, s[10:11]
	global_load_dwordx4 v[166:169], v[194:195], off
	global_load_dword v220, v[194:195], off offset:-4
	s_waitcnt vmcnt(4)
	v_perm_b32 v222, v236, v228, s67
	v_perm_b32 v223, v228, v229, s67
	v_perm_b32 v224, v229, v230, s67
	v_perm_b32 v225, v230, v231, s67
	s_nop 0
	s_add_i32 s23, s19, 23
	s_ashr_i32 s23, s23, 3
	v_mfma_f32_16x16x32_bf16 v[194:197], v[228:231], v[66:69], v[232:235]
	s_add_i32 s30, s22, 0x3c0
	s_and_b32 s30, s30, 0x1c0
	v_mfma_f32_16x16x32_bf16 v[190:193], v[222:225], v[66:69], v[190:193]
	v_add_u32_e32 v66, s23, v216
	v_add_u32_e32 v67, s23, v217
	v_cmp_gt_u32_e32 vcc, 8, v66
	v_mfma_f32_16x16x32_bf16 v[138:141], v[228:231], v[158:161], v[138:141]
	s_nop 0
	v_cndmask_b32_e32 v66, v214, v66, vcc
	v_cmp_gt_u32_e32 vcc, 8, v67
	v_mul_lo_u32 v66, v66, s58
	v_mfma_f32_16x16x32_bf16 v[130:133], v[222:225], v[158:161], v[130:133]
	v_cndmask_b32_e32 v67, v214, v67, vcc
	v_mul_lo_u32 v67, v67, s58
	v_add3_u32 v66, v0, v66, s30
	v_add3_u32 v158, v0, v67, s30
	ds_read_b128 v[66:69], v66
	ds_read_b128 v[158:161], v158
	v_mfma_f32_16x16x32_bf16 v[198:201], v[228:231], v[154:157], v[242:245]
	v_mfma_f32_16x16x32_bf16 v[182:185], v[222:225], v[154:157], v[182:185]
	v_mfma_f32_16x16x32_bf16 v[122:125], v[228:231], v[74:77], v[122:125]
	v_mfma_f32_16x16x32_bf16 v[118:121], v[222:225], v[74:77], v[118:121]
	v_mfma_f32_16x16x32_bf16 v[186:189], v[228:231], v[146:149], v[186:189]
	v_mfma_f32_16x16x32_bf16 v[174:177], v[222:225], v[146:149], v[174:177]
	v_mfma_f32_16x16x32_bf16 v[114:117], v[228:231], v[82:85], v[114:117]
	v_mfma_f32_16x16x32_bf16 v[106:109], v[222:225], v[82:85], v[106:109]
	v_mfma_f32_16x16x32_bf16 v[178:181], v[228:231], v[134:137], v[178:181]
	v_mfma_f32_16x16x32_bf16 v[170:173], v[222:225], v[134:137], v[170:173]
	v_mfma_f32_16x16x32_bf16 v[98:101], v[228:231], v[90:93], v[98:101]
	v_mfma_f32_16x16x32_bf16 v[94:97], v[222:225], v[90:93], v[94:97]
	v_mfma_f32_16x16x32_bf16 v[62:65], v[228:231], v[110:113], v[62:65]
	v_mfma_f32_16x16x32_bf16 v[54:57], v[222:225], v[110:113], v[54:57]
	v_mfma_f32_16x16x32_bf16 v[30:33], v[228:231], v[102:105], v[30:33]
	v_mfma_f32_16x16x32_bf16 v[26:29], v[222:225], v[102:105], v[26:29]
	v_mfma_f32_16x16x32_bf16 v[58:61], v[228:231], v[86:89], v[58:61]
	v_mfma_f32_16x16x32_bf16 v[46:49], v[222:225], v[86:89], v[46:49]
	v_mfma_f32_16x16x32_bf16 v[22:25], v[228:231], v[126:129], v[22:25]
	v_mfma_f32_16x16x32_bf16 v[18:21], v[222:225], v[126:129], v[18:21]
	v_mfma_f32_16x16x32_bf16 v[50:53], v[228:231], v[78:81], v[50:53]
	v_mfma_f32_16x16x32_bf16 v[38:41], v[222:225], v[78:81], v[38:41]
	v_mfma_f32_16x16x32_bf16 v[14:17], v[228:231], v[142:145], v[14:17]
	v_mfma_f32_16x16x32_bf16 v[10:13], v[222:225], v[142:145], v[10:13]
	s_waitcnt lgkmcnt(3)
	v_mfma_f32_16x16x32_bf16 v[42:45], v[228:231], v[70:73], v[42:45]
	v_mfma_f32_16x16x32_bf16 v[34:37], v[222:225], v[70:73], v[34:37]
	s_waitcnt lgkmcnt(2)
	v_mfma_f32_16x16x32_bf16 v[6:9], v[228:231], v[150:153], v[6:9]
	v_mfma_f32_16x16x32_bf16 v[2:5], v[222:225], v[150:153], v[2:5]
	s_nop 0
	s_add_i32 s19, s19, 8
	s_addk_i32 s22, 0x200
	s_cmp_lt_i32 s19, 25
	v_add_u32_e32 v218, 0x100, v218
	s_cbranch_scc1 .LBB0_732
	v_add_u32_e32 v90, 6, v216
	v_add_u32_e32 v91, 0x540, v215
	s_mov_b32 s19, 25
.LBB0_734:
	v_add_u32_e32 v74, 0xffffff20, v91
	v_min_i32_e32 v74, 0x7f8, v74
	v_ashrrev_i32_e32 v75, 31, v74
	v_lshl_add_u64 v[74:75], v[74:75], 1, s[10:11]
	global_load_dwordx4 v[102:105], v[74:75], off
	global_load_dword v210, v[74:75], off offset:-4
	s_waitcnt vmcnt(4)
	v_perm_b32 v82, v219, v162, s67
	v_perm_b32 v83, v162, v163, s67
	v_perm_b32 v84, v163, v164, s67
	v_perm_b32 v85, v164, v165, s67
	s_nop 0
	v_add_u32_e32 v74, -1, v90
	v_cmp_gt_u32_e32 vcc, 8, v74
	v_mfma_f32_16x16x32_bf16 v[174:177], v[82:85], v[134:137], v[174:177]
	s_nop 0
	v_cndmask_b32_e32 v74, v214, v74, vcc
	v_mad_u64_u32 v[92:93], s[22:23], v74, s58, v[0:1]
	v_mfma_f32_16x16x32_bf16 v[178:181], v[162:165], v[110:113], v[178:181]
	ds_read_b128 v[74:77], v92 offset:64
	v_mfma_f32_16x16x32_bf16 v[170:173], v[82:85], v[110:113], v[170:173]
	v_mfma_f32_16x16x32_bf16 v[62:65], v[162:165], v[86:89], v[62:65]
	v_mfma_f32_16x16x32_bf16 v[54:57], v[82:85], v[86:89], v[54:57]
	v_mfma_f32_16x16x32_bf16 v[58:61], v[162:165], v[78:81], v[58:61]
	v_mfma_f32_16x16x32_bf16 v[46:49], v[82:85], v[78:81], v[46:49]
	v_mfma_f32_16x16x32_bf16 v[50:53], v[162:165], v[70:73], v[50:53]
	v_mfma_f32_16x16x32_bf16 v[38:41], v[82:85], v[70:73], v[38:41]
	s_waitcnt lgkmcnt(2)
	v_mfma_f32_16x16x32_bf16 v[42:45], v[162:165], v[66:69], v[42:45]
	v_mfma_f32_16x16x32_bf16 v[34:37], v[82:85], v[66:69], v[34:37]
	v_mfma_f32_16x16x32_bf16 v[126:129], v[82:85], v[154:157], v[190:193]
	v_mfma_f32_16x16x32_bf16 v[142:145], v[162:165], v[146:149], v[198:201]
	v_mfma_f32_16x16x32_bf16 v[150:153], v[82:85], v[146:149], v[182:185]
	s_waitcnt lgkmcnt(1)
	v_mfma_f32_16x16x32_bf16 v[158:161], v[162:165], v[134:137], v[186:189]
	s_nop 0
	v_add_u32_e32 v82, 0xffffff40, v91
	v_min_i32_e32 v82, 0x7f8, v82
	v_ashrrev_i32_e32 v83, 31, v82
	v_lshl_add_u64 v[82:83], v[82:83], 1, s[10:11]
	global_load_dwordx4 v[182:185], v[82:83], off
	global_load_dword v93, v[82:83], off offset:-4
	s_waitcnt vmcnt(4)
	v_perm_b32 v82, v220, v166, s67
	v_perm_b32 v83, v166, v167, s67
	v_perm_b32 v84, v167, v168, s67
	v_perm_b32 v85, v168, v169, s67
	s_nop 1

	v_mfma_f32_16x16x32_bf16 v[126:129], v[82:85], v[146:149], v[126:129]
	v_mfma_f32_16x16x32_bf16 v[150:153], v[82:85], v[134:137], v[150:153]
	v_mfma_f32_16x16x32_bf16 v[174:177], v[82:85], v[110:113], v[174:177]
	v_mfma_f32_16x16x32_bf16 v[178:181], v[166:169], v[86:89], v[178:181]
	v_mfma_f32_16x16x32_bf16 v[170:173], v[82:85], v[86:89], v[170:173]
	v_mfma_f32_16x16x32_bf16 v[62:65], v[166:169], v[78:81], v[62:65]
	v_mfma_f32_16x16x32_bf16 v[54:57], v[82:85], v[78:81], v[54:57]
	v_mfma_f32_16x16x32_bf16 v[58:61], v[166:169], v[70:73], v[58:61]
	v_mfma_f32_16x16x32_bf16 v[46:49], v[82:85], v[70:73], v[46:49]
	v_mfma_f32_16x16x32_bf16 v[50:53], v[166:169], v[66:69], v[50:53]
	v_mfma_f32_16x16x32_bf16 v[38:41], v[82:85], v[66:69], v[38:41]
	s_waitcnt lgkmcnt(0)
	v_mfma_f32_16x16x32_bf16 v[42:45], v[166:169], v[74:77], v[42:45]
	v_mfma_f32_16x16x32_bf16 v[34:37], v[82:85], v[74:77], v[34:37]
	ds_read_b128 v[82:85], v92 offset:128
	v_mfma_f32_16x16x32_bf16 v[154:157], v[162:165], v[154:157], v[194:197]
	v_mfma_f32_16x16x32_bf16 v[142:145], v[166:169], v[134:137], v[142:145]
	v_mfma_f32_16x16x32_bf16 v[158:161], v[166:169], v[110:113], v[158:161]
	s_nop 0
	v_add_u32_e32 v162, 0xffffff60, v91
	v_min_i32_e32 v162, 0x7f8, v162
	v_ashrrev_i32_e32 v163, 31, v162
	v_lshl_add_u64 v[186:187], v[162:163], 1, s[10:11]
	global_load_dwordx4 v[162:165], v[186:187], off
	global_load_dword v190, v[186:187], off offset:-4
	s_waitcnt vmcnt(4)
	v_perm_b32 v186, v210, v102, s67
	v_perm_b32 v187, v102, v103, s67
	v_perm_b32 v188, v103, v104, s67
	v_perm_b32 v189, v104, v105, s67
	s_nop 1

	v_mfma_f32_16x16x32_bf16 v[174:177], v[186:189], v[86:89], v[174:177]
	ds_read_b128 v[222:225], v92 offset:192
	v_mfma_f32_16x16x32_bf16 v[178:181], v[102:105], v[78:81], v[178:181]
	v_mfma_f32_16x16x32_bf16 v[170:173], v[186:189], v[78:81], v[170:173]
	v_mfma_f32_16x16x32_bf16 v[62:65], v[102:105], v[70:73], v[62:65]
	v_mfma_f32_16x16x32_bf16 v[54:57], v[186:189], v[70:73], v[54:57]
	v_mfma_f32_16x16x32_bf16 v[58:61], v[102:105], v[66:69], v[58:61]
	v_mfma_f32_16x16x32_bf16 v[46:49], v[186:189], v[66:69], v[46:49]
	v_mfma_f32_16x16x32_bf16 v[50:53], v[102:105], v[74:77], v[50:53]
	v_mfma_f32_16x16x32_bf16 v[38:41], v[186:189], v[74:77], v[38:41]
	s_waitcnt lgkmcnt(1)
	v_mfma_f32_16x16x32_bf16 v[42:45], v[102:105], v[82:85], v[42:45]
	v_mfma_f32_16x16x32_bf16 v[34:37], v[186:189], v[82:85], v[34:37]
	v_mfma_f32_16x16x32_bf16 v[146:149], v[166:169], v[146:149], v[154:157]
	v_mfma_f32_16x16x32_bf16 v[126:129], v[186:189], v[134:137], v[126:129]
	v_mfma_f32_16x16x32_bf16 v[142:145], v[102:105], v[110:113], v[142:145]
	v_mfma_f32_16x16x32_bf16 v[150:153], v[186:189], v[110:113], v[150:153]
	v_mfma_f32_16x16x32_bf16 v[158:161], v[102:105], v[86:89], v[158:161]
	s_nop 0
	v_add_u32_e32 v154, 0xffffff80, v91
	v_min_i32_e32 v154, 0x7f8, v154
	v_ashrrev_i32_e32 v155, 31, v154
	v_lshl_add_u64 v[166:167], v[154:155], 1, s[10:11]
	global_load_dwordx4 v[154:157], v[166:167], off
	global_load_dword v186, v[166:167], off offset:-4
	s_waitcnt vmcnt(4)
	v_perm_b32 v166, v93, v182, s67
	v_perm_b32 v167, v182, v183, s67
	v_perm_b32 v168, v183, v184, s67
	v_perm_b32 v169, v184, v185, s67
	s_nop 1

	v_mfma_f32_16x16x32_bf16 v[174:177], v[166:169], v[78:81], v[174:177]
	ds_read_b128 v[226:229], v92 offset:256
	v_mfma_f32_16x16x32_bf16 v[178:181], v[182:185], v[70:73], v[178:181]
	v_mfma_f32_16x16x32_bf16 v[170:173], v[166:169], v[70:73], v[170:173]
	v_mfma_f32_16x16x32_bf16 v[62:65], v[182:185], v[66:69], v[62:65]
	v_mfma_f32_16x16x32_bf16 v[54:57], v[166:169], v[66:69], v[54:57]
	v_mfma_f32_16x16x32_bf16 v[58:61], v[182:185], v[74:77], v[58:61]
	v_mfma_f32_16x16x32_bf16 v[46:49], v[166:169], v[74:77], v[46:49]
	v_mfma_f32_16x16x32_bf16 v[50:53], v[182:185], v[82:85], v[50:53]
	v_mfma_f32_16x16x32_bf16 v[38:41], v[166:169], v[82:85], v[38:41]
	s_waitcnt lgkmcnt(1)
	v_mfma_f32_16x16x32_bf16 v[42:45], v[182:185], v[222:225], v[42:45]
	v_mfma_f32_16x16x32_bf16 v[34:37], v[166:169], v[222:225], v[34:37]
	v_mfma_f32_16x16x32_bf16 v[126:129], v[166:169], v[110:113], v[126:129]
	v_mfma_f32_16x16x32_bf16 v[142:145], v[182:185], v[86:89], v[142:145]
	v_mfma_f32_16x16x32_bf16 v[150:153], v[166:169], v[86:89], v[150:153]
	v_mfma_f32_16x16x32_bf16 v[158:161], v[182:185], v[78:81], v[158:161]
	v_mfma_f32_16x16x32_bf16 v[102:105], v[102:105], v[134:137], v[146:149]
	s_nop 0
	v_add_u32_e32 v93, 0xffffffa0, v91
	v_min_i32_e32 v134, 0x7f8, v93
	v_ashrrev_i32_e32 v135, 31, v134
	v_lshl_add_u64 v[146:147], v[134:135], 1, s[10:11]
	global_load_dwordx4 v[134:137], v[146:147], off
	global_load_dword v93, v[146:147], off offset:-4
	s_waitcnt vmcnt(4)
	v_perm_b32 v146, v190, v162, s67
	v_perm_b32 v147, v162, v163, s67
	v_perm_b32 v148, v163, v164, s67
	v_perm_b32 v149, v164, v165, s67
	s_nop 1

	v_mfma_f32_16x16x32_bf16 v[126:129], v[146:149], v[86:89], v[126:129]
	v_mfma_f32_16x16x32_bf16 v[150:153], v[146:149], v[78:81], v[150:153]
	v_mfma_f32_16x16x32_bf16 v[166:169], v[146:149], v[70:73], v[174:177]
	v_mfma_f32_16x16x32_bf16 v[170:173], v[146:149], v[66:69], v[170:173]
	v_mfma_f32_16x16x32_bf16 v[54:57], v[146:149], v[74:77], v[54:57]
	v_mfma_f32_16x16x32_bf16 v[46:49], v[146:149], v[82:85], v[46:49]
	v_mfma_f32_16x16x32_bf16 v[38:41], v[146:149], v[222:225], v[38:41]
	s_waitcnt lgkmcnt(0)
	v_mfma_f32_16x16x32_bf16 v[34:37], v[146:149], v[226:229], v[34:37]
	ds_read_b128 v[146:149], v92 offset:320
	v_mfma_f32_16x16x32_bf16 v[174:177], v[162:165], v[66:69], v[178:181]
	v_mfma_f32_16x16x32_bf16 v[62:65], v[162:165], v[74:77], v[62:65]
	v_mfma_f32_16x16x32_bf16 v[58:61], v[162:165], v[82:85], v[58:61]
	v_mfma_f32_16x16x32_bf16 v[50:53], v[162:165], v[222:225], v[50:53]
	v_mfma_f32_16x16x32_bf16 v[42:45], v[162:165], v[226:229], v[42:45]
	v_mfma_f32_16x16x32_bf16 v[142:145], v[162:165], v[78:81], v[142:145]
	v_mfma_f32_16x16x32_bf16 v[158:161], v[162:165], v[70:73], v[158:161]
	v_mfma_f32_16x16x32_bf16 v[102:105], v[182:185], v[110:113], v[102:105]
	s_nop 0
	v_subrev_u32_e32 v110, 64, v91
	v_min_i32_e32 v110, 0x7f8, v110
	v_ashrrev_i32_e32 v111, 31, v110
	v_lshl_add_u64 v[178:179], v[110:111], 1, s[10:11]
	global_load_dwordx4 v[110:113], v[178:179], off
	global_load_dword v182, v[178:179], off offset:-4
	s_waitcnt vmcnt(4)
	v_perm_b32 v178, v186, v154, s67
	v_perm_b32 v179, v154, v155, s67
	v_perm_b32 v180, v155, v156, s67
	v_perm_b32 v181, v156, v157, s67
	s_nop 1

	v_mfma_f32_16x16x32_bf16 v[166:169], v[178:181], v[66:69], v[166:169]
	ds_read_b128 v[230:233], v92 offset:384
	v_mfma_f32_16x16x32_bf16 v[174:177], v[154:157], v[74:77], v[174:177]
	v_mfma_f32_16x16x32_bf16 v[170:173], v[178:181], v[74:77], v[170:173]
	v_mfma_f32_16x16x32_bf16 v[62:65], v[154:157], v[82:85], v[62:65]
	v_mfma_f32_16x16x32_bf16 v[54:57], v[178:181], v[82:85], v[54:57]
	v_mfma_f32_16x16x32_bf16 v[58:61], v[154:157], v[222:225], v[58:61]
	v_mfma_f32_16x16x32_bf16 v[46:49], v[178:181], v[222:225], v[46:49]
	v_mfma_f32_16x16x32_bf16 v[50:53], v[154:157], v[226:229], v[50:53]
	v_mfma_f32_16x16x32_bf16 v[38:41], v[178:181], v[226:229], v[38:41]
	s_waitcnt lgkmcnt(1)
	v_mfma_f32_16x16x32_bf16 v[42:45], v[154:157], v[146:149], v[42:45]
	v_mfma_f32_16x16x32_bf16 v[34:37], v[178:181], v[146:149], v[34:37]
	v_mfma_f32_16x16x32_bf16 v[86:89], v[162:165], v[86:89], v[102:105]
	v_mfma_f32_16x16x32_bf16 v[126:129], v[178:181], v[78:81], v[126:129]
	v_mfma_f32_16x16x32_bf16 v[142:145], v[154:157], v[70:73], v[142:145]
	v_mfma_f32_16x16x32_bf16 v[150:153], v[178:181], v[70:73], v[150:153]
	v_mfma_f32_16x16x32_bf16 v[158:161], v[154:157], v[66:69], v[158:161]
	s_nop 0
	v_subrev_u32_e32 v102, 32, v91
	v_min_i32_e32 v102, 0x7f8, v102
	v_ashrrev_i32_e32 v103, 31, v102
	v_lshl_add_u64 v[102:103], v[102:103], 1, s[10:11]
	global_load_dwordx4 v[162:165], v[102:103], off
	global_load_dword v219, v[102:103], off offset:-4
	s_waitcnt vmcnt(4)
	v_perm_b32 v102, v93, v134, s67
	v_perm_b32 v103, v134, v135, s67
	v_perm_b32 v104, v135, v136, s67
	v_perm_b32 v105, v136, v137, s67
	s_nop 1

; #define CONV_LOADA(e_, k_) do { const int xh_ = min(32 * (e_) + xa, L - 8); rh[k_] = *(const u32x4a4*)(Rc + xh_); asm volatile("" ::: "memory"); rl[k_] = *(const unsigned*)(Rc + xh_ - 2); } while (0)
; #define CONV_BLOCK(DO0, DO1) do { CONV_STEP(0, DO0, DO1); CONV_STEP(1, DO0, DO1); CONV_STEP(2, DO0, DO1); CONV_STEP(3, DO0, DO1); CONV_STEP(4, DO0, DO1); CONV_STEP(5, DO0, DO1); CONV_STEP(6, DO0, DO1); CONV_STEP(7, DO0, DO1); } while (0)
; template <bool PROMPT, int HALF>
; __device__ __forceinline__ void conv_item(unsigned char* ws, KArgs ka, int ib, int oct, int g, LAS unsigned char* lds, int tid, int lane, int wave) {
;     ...
; #pragma unroll
;     for (int k = 0; k < DA; ++k) CONV_LOADA(E0 + k, k);
;     { unsigned zz_ = 0u; asm volatile("" : "+v"(zz_));
; #pragma unroll
;       for (int k = 0; k < W; ++k) F1[k] = (u32x4){zz_, zz_, zz_, zz_}; }
;     for (int e = E0; e < E1; e += 8) CONV_BLOCK(false, true);
;     { unsigned zz_ = 0u; asm volatile("" : "+v"(zz_));
; #pragma unroll
;       for (int k = 0; k < W; ++k) F0[k] = (u32x4){zz_, zz_, zz_, zz_}; }
;     for (int e = E1; e < E2; e += 8) CONV_BLOCK(true, true);
;     for (int e = E2; e < E3; e += 8) CONV_BLOCK(true, false);
;     ...
;     __syncthreads();
;     int lane2; { unsigned ones_ = ~0u; asm volatile("" : "+s"(ones_)); lane2 = (int)__builtin_amdgcn_mbcnt_hi(ones_, __builtin_amdgcn_mbcnt_lo(ones_, 0u)); }
;     const int nn2 = lane2 & 15, kq2 = lane2 >> 4;
;     float nsum = 0.f;
;     { const float* kq_ = (const float*)(ws + WS_KPART) + ((size_t)ib * 320 + (PROMPT ? 0 : 256)) * 2048; constexpr int ntile = PROMPT ? 256 : 64;
;       for (int q = lane2; q < ntile; q += 64) nsum += kq_[(size_t)q * 2048 + c] + kq_[(size_t)q * 2048 + 1024 + c];
	v_mfma_f32_16x16x32_bf16 v[126:129], v[102:105], v[70:73], v[126:129]
	v_mfma_f32_16x16x32_bf16 v[150:153], v[102:105], v[66:69], v[150:153]
	v_mfma_f32_16x16x32_bf16 v[178:181], v[102:105], v[74:77], v[166:169]
	v_mfma_f32_16x16x32_bf16 v[194:197], v[134:137], v[82:85], v[174:177]
	v_mfma_f32_16x16x32_bf16 v[170:173], v[102:105], v[82:85], v[170:173]
	v_mfma_f32_16x16x32_bf16 v[62:65], v[134:137], v[222:225], v[62:65]
	v_mfma_f32_16x16x32_bf16 v[54:57], v[102:105], v[222:225], v[54:57]
	v_mfma_f32_16x16x32_bf16 v[58:61], v[134:137], v[226:229], v[58:61]
	v_mfma_f32_16x16x32_bf16 v[46:49], v[102:105], v[226:229], v[46:49]
	v_mfma_f32_16x16x32_bf16 v[50:53], v[134:137], v[146:149], v[50:53]
	v_mfma_f32_16x16x32_bf16 v[38:41], v[102:105], v[146:149], v[38:41]
	s_waitcnt lgkmcnt(0)
	v_mfma_f32_16x16x32_bf16 v[42:45], v[134:137], v[230:233], v[42:45]
	v_mfma_f32_16x16x32_bf16 v[34:37], v[102:105], v[230:233], v[34:37]
	ds_read_b128 v[102:105], v92 offset:448
	v_mfma_f32_16x16x32_bf16 v[78:81], v[154:157], v[78:81], v[86:89]
	v_mfma_f32_16x16x32_bf16 v[142:145], v[134:137], v[66:69], v[142:145]
	v_mfma_f32_16x16x32_bf16 v[158:161], v[134:137], v[74:77], v[158:161]
	s_nop 0
	v_min_i32_e32 v86, 0x7f8, v91
	v_ashrrev_i32_e32 v87, 31, v86
	v_lshl_add_u64 v[86:87], v[86:87], 1, s[10:11]
	global_load_dwordx4 v[166:169], v[86:87], off
	global_load_dword v220, v[86:87], off offset:-4
	s_waitcnt vmcnt(4)
	v_perm_b32 v86, v182, v110, s67
	v_perm_b32 v87, v110, v111, s67
	v_perm_b32 v88, v111, v112, s67
	v_perm_b32 v89, v112, v113, s67
	s_nop 0
	v_cmp_gt_u32_e32 vcc, 8, v90
	v_mfma_f32_16x16x32_bf16 v[70:73], v[134:137], v[70:73], v[78:81]
	v_mfma_f32_16x16x32_bf16 v[190:193], v[86:89], v[66:69], v[126:129]
	v_mfma_f32_16x16x32_bf16 v[182:185], v[86:89], v[74:77], v[150:153]
	v_mfma_f32_16x16x32_bf16 v[174:177], v[86:89], v[82:85], v[178:181]
	v_mfma_f32_16x16x32_bf16 v[170:173], v[86:89], v[222:225], v[170:173]
	v_mfma_f32_16x16x32_bf16 v[54:57], v[86:89], v[226:229], v[54:57]
	v_mfma_f32_16x16x32_bf16 v[46:49], v[86:89], v[146:149], v[46:49]
	v_mfma_f32_16x16x32_bf16 v[38:41], v[86:89], v[230:233], v[38:41]
	s_waitcnt lgkmcnt(0)
	v_mfma_f32_16x16x32_bf16 v[34:37], v[86:89], v[102:105], v[34:37]
	v_cndmask_b32_e32 v86, v214, v90, vcc
	v_mad_u64_u32 v[78:79], s[22:23], v86, s58, v[0:1]
	ds_read_b128 v[78:81], v78
	v_mfma_f32_16x16x32_bf16 v[198:201], v[110:113], v[74:77], v[142:145]
	v_mfma_f32_16x16x32_bf16 v[186:189], v[110:113], v[82:85], v[158:161]
	v_mfma_f32_16x16x32_bf16 v[178:181], v[110:113], v[222:225], v[194:197]
	v_mfma_f32_16x16x32_bf16 v[62:65], v[110:113], v[226:229], v[62:65]
	v_mfma_f32_16x16x32_bf16 v[58:61], v[110:113], v[146:149], v[58:61]
	v_mfma_f32_16x16x32_bf16 v[50:53], v[110:113], v[230:233], v[50:53]
	v_mfma_f32_16x16x32_bf16 v[42:45], v[110:113], v[102:105], v[42:45]
	v_mfma_f32_16x16x32_bf16 v[194:197], v[110:113], v[66:69], v[70:73]
	s_nop 0
	s_waitcnt lgkmcnt(0)
	v_mov_b64_e32 v[66:67], v[78:79]
	v_mov_b64_e32 v[86:87], v[146:147]
	s_add_i32 s19, s19, 8
	v_mov_b64_e32 v[68:69], v[80:81]
	v_mov_b64_e32 v[70:71], v[102:103]
	v_mov_b64_e32 v[78:79], v[230:231]
	v_mov_b64_e32 v[88:89], v[148:149]
	v_mov_b64_e32 v[110:111], v[226:227]
	v_mov_b64_e32 v[134:135], v[222:223]
	v_mov_b64_e32 v[148:149], v[84:85]
	v_mov_b64_e32 v[156:157], v[76:77]
	v_add_u32_e32 v90, 1, v90
	v_add_u32_e32 v91, 0x100, v91
	s_cmp_gt_u32 s19, 56
	v_mov_b64_e32 v[72:73], v[104:105]
	v_mov_b64_e32 v[80:81], v[232:233]
	v_mov_b64_e32 v[112:113], v[228:229]
	v_mov_b64_e32 v[136:137], v[224:225]
	v_mov_b64_e32 v[146:147], v[82:83]
	v_mov_b64_e32 v[154:155], v[74:75]
	s_cbranch_scc0 .LBB0_734
	s_mov_b32 s10, -1
	s_barrier
	s_nop 0
	v_mbcnt_lo_u32_b32 v0, s10, 0
	v_mbcnt_hi_u32_b32 v74, s10, v0
	v_cmp_gt_i32_e32 vcc, 64, v74
	v_mov_b32_e32 v0, 0
	s_and_saveexec_b64 s[10:11], vcc
	s_cbranch_execz .LBB0_739
	s_lshl_b32 s19, s34, 2
	s_and_b32 s19, s19, -8
	v_readlane_b32 s22, v253, 4
	s_add_i32 s30, s22, s19
	s_lshl_b64 s[22:23], s[30:31], 2
	s_add_u32 s22, s49, s22
	v_lshlrev_b32_e32 v0, 13, v74
	s_addc_u32 s23, s50, s23
	v_subrev_u32_e32 v68, 64, v74
	v_lshl_add_u64 v[66:67], s[22:23], 0, v[0:1]
	v_mov_b32_e32 v0, 0
	s_mov_b64 s[22:23], 0

; #define CONV_LOADA(e_, k_) do { const int xh_ = min(32 * (e_) + xa, L - 8); rh[k_] = *(const u32x4a4*)(Rc + xh_); asm volatile("" ::: "memory"); rl[k_] = *(const unsigned*)(Rc + xh_ - 2); } while (0)
; #define CONV_BLOCK(DO0, DO1) do { CONV_STEP(0, DO0, DO1); CONV_STEP(1, DO0, DO1); CONV_STEP(2, DO0, DO1); CONV_STEP(3, DO0, DO1); CONV_STEP(4, DO0, DO1); CONV_STEP(5, DO0, DO1); CONV_STEP(6, DO0, DO1); CONV_STEP(7, DO0, DO1); } while (0)
; template <bool PROMPT, int HALF>
; __device__ __forceinline__ void conv_item(unsigned char* ws, KArgs ka, int ib, int oct, int g, LAS unsigned char* lds, int tid, int lane, int wave) {
;     ...
; #pragma unroll
;     for (int k = 0; k < DA; ++k) CONV_LOADA(E0 + k, k);
;     { unsigned zz_ = 0u; asm volatile("" : "+v"(zz_));
; #pragma unroll
;       for (int k = 0; k < W; ++k) F1[k] = (u32x4){zz_, zz_, zz_, zz_}; }
;     for (int e = E0; e < E1; e += 8) CONV_BLOCK(false, true);
.LBB0_751:
	v_min_i32_e32 v68, 0x1ff8, v66
	v_ashrrev_i32_e32 v69, 31, v68
	v_lshl_add_u64 v[72:73], v[68:69], 1, s[22:23]
	global_load_dwordx4 v[68:71], v[72:73], off
	global_load_dword v67, v[72:73], off offset:-4
	s_waitcnt vmcnt(8)
	v_perm_b32 v72, v125, v2, s67
	v_perm_b32 v73, v2, v3, s67
	v_perm_b32 v74, v3, v4, s67
	v_perm_b32 v75, v4, v5, s67
	s_nop 0
	s_add_i32 s43, s11, 16
	s_ashr_i32 s43, s43, 3
	v_add_u32_e32 v76, s43, v124
	v_min_u32_e32 v76, 32, v76
	v_mad_u32_u24 v76, v76, s58, v0
	v_mfma_f32_16x16x32_bf16 v[38:41], v[72:75], v[62:65], v[38:41]
	ds_read_b128 v[76:79], v76 offset:64
	v_mfma_f32_16x16x32_bf16 v[42:45], v[2:5], v[58:61], v[42:45]
	v_mfma_f32_16x16x32_bf16 v[34:37], v[72:75], v[58:61], v[34:37]
	v_mfma_f32_16x16x32_bf16 v[30:33], v[2:5], v[54:57], v[30:33]
	v_mfma_f32_16x16x32_bf16 v[26:29], v[72:75], v[54:57], v[26:29]
	s_waitcnt lgkmcnt(1)
	v_mfma_f32_16x16x32_bf16 v[22:25], v[2:5], v[50:53], v[22:25]
	v_mfma_f32_16x16x32_bf16 v[18:21], v[72:75], v[50:53], v[18:21]
	s_nop 0
	v_add_u32_e32 v72, 32, v66
	v_min_i32_e32 v72, 0x1ff8, v72
	v_ashrrev_i32_e32 v73, 31, v72
	v_lshl_add_u64 v[80:81], v[72:73], 1, s[22:23]
	global_load_dwordx4 v[72:75], v[80:81], off
	global_load_dword v96, v[80:81], off offset:-4
	s_waitcnt vmcnt(8)
	v_perm_b32 v80, v126, v6, s67
	v_perm_b32 v81, v6, v7, s67
	v_perm_b32 v82, v7, v8, s67
	v_perm_b32 v83, v8, v9, s67
	s_nop 0
	s_add_i32 s43, s11, 17
	s_ashr_i32 s43, s43, 3
	v_add_u32_e32 v84, s43, v124
	v_mfma_f32_16x16x32_bf16 v[38:41], v[80:83], v[58:61], v[38:41]
	v_mfma_f32_16x16x32_bf16 v[34:37], v[80:83], v[54:57], v[34:37]
	v_mfma_f32_16x16x32_bf16 v[26:29], v[80:83], v[50:53], v[26:29]
	s_waitcnt lgkmcnt(0)
	v_mfma_f32_16x16x32_bf16 v[18:21], v[80:83], v[76:79], v[18:21]
	v_min_u32_e32 v80, 32, v84
	v_mad_u32_u24 v80, v80, s58, v0
	ds_read_b128 v[80:83], v80 offset:128
	v_mfma_f32_16x16x32_bf16 v[42:45], v[6:9], v[54:57], v[42:45]
	v_mfma_f32_16x16x32_bf16 v[30:33], v[6:9], v[50:53], v[30:33]
	v_mfma_f32_16x16x32_bf16 v[22:25], v[6:9], v[76:79], v[22:25]
	v_mfma_f32_16x16x32_bf16 v[2:5], v[2:5], v[62:65], v[46:49]
	s_nop 0
	s_nop 1
	v_add_u32_e32 v46, 64, v66
	v_min_i32_e32 v46, 0x1ff8, v46
	v_ashrrev_i32_e32 v47, 31, v46
	v_lshl_add_u64 v[62:63], v[46:47], 1, s[22:23]
	global_load_dwordx4 v[46:49], v[62:63], off
	global_load_dword v97, v[62:63], off offset:-4
	s_waitcnt vmcnt(8)
	v_perm_b32 v62, v127, v10, s67
	v_perm_b32 v63, v10, v11, s67
	v_perm_b32 v64, v11, v12, s67
	v_perm_b32 v65, v12, v13, s67
	s_nop 0
	s_add_i32 s43, s11, 18
	s_ashr_i32 s43, s43, 3
	v_add_u32_e32 v84, s43, v124
	v_mfma_f32_16x16x32_bf16 v[38:41], v[62:65], v[54:57], v[38:41]
	v_mfma_f32_16x16x32_bf16 v[34:37], v[62:65], v[50:53], v[34:37]
	v_mfma_f32_16x16x32_bf16 v[26:29], v[62:65], v[76:79], v[26:29]
	s_waitcnt lgkmcnt(0)
	v_mfma_f32_16x16x32_bf16 v[18:21], v[62:65], v[80:83], v[18:21]
	v_min_u32_e32 v62, 32, v84
	v_mad_u32_u24 v62, v62, s58, v0
	ds_read_b128 v[84:87], v62 offset:192
	v_mfma_f32_16x16x32_bf16 v[42:45], v[10:13], v[50:53], v[42:45]
	v_mfma_f32_16x16x32_bf16 v[30:33], v[10:13], v[76:79], v[30:33]
	v_mfma_f32_16x16x32_bf16 v[22:25], v[10:13], v[80:83], v[22:25]
	v_mfma_f32_16x16x32_bf16 v[2:5], v[6:9], v[58:61], v[2:5]
	s_nop 0
	v_add_u32_e32 v6, 0x60, v66
	v_min_i32_e32 v6, 0x1ff8, v6
	v_ashrrev_i32_e32 v7, 31, v6
	v_lshl_add_u64 v[6:7], v[6:7], 1, s[22:23]
	global_load_dwordx4 v[88:91], v[6:7], off
	global_load_dword v98, v[6:7], off offset:-4
	s_waitcnt vmcnt(8)
	v_perm_b32 v6, v128, v14, s67
	v_perm_b32 v7, v14, v15, s67
	v_perm_b32 v8, v15, v16, s67
	v_perm_b32 v9, v16, v17, s67
	s_nop 0
	s_add_i32 s43, s11, 19
	s_ashr_i32 s43, s43, 3
	v_add_u32_e32 v58, s43, v124
	v_mfma_f32_16x16x32_bf16 v[38:41], v[6:9], v[50:53], v[38:41]
	v_mfma_f32_16x16x32_bf16 v[34:37], v[6:9], v[76:79], v[34:37]
	v_mfma_f32_16x16x32_bf16 v[26:29], v[6:9], v[80:83], v[26:29]
	s_waitcnt lgkmcnt(0)
	v_mfma_f32_16x16x32_bf16 v[6:9], v[6:9], v[84:87], v[18:21]
	s_nop 2
	v_min_u32_e32 v18, 32, v58
	v_mad_u32_u24 v18, v18, s58, v0
	v_mfma_f32_16x16x32_bf16 v[42:45], v[14:17], v[76:79], v[42:45]
	ds_read_b128 v[92:95], v18 offset:256
	v_mfma_f32_16x16x32_bf16 v[30:33], v[14:17], v[80:83], v[30:33]
	v_mfma_f32_16x16x32_bf16 v[22:25], v[14:17], v[84:87], v[22:25]
	v_mfma_f32_16x16x32_bf16 v[10:13], v[10:13], v[54:57], v[2:5]
	s_nop 0
	s_nop 1
	v_add_u32_e32 v2, 0x80, v66
	v_min_i32_e32 v2, 0x1ff8, v2
	v_ashrrev_i32_e32 v3, 31, v2
	v_lshl_add_u64 v[18:19], v[2:3], 1, s[22:23]
	global_load_dwordx4 v[2:5], v[18:19], off
	global_load_dword v125, v[18:19], off offset:-4
	s_waitcnt vmcnt(8)
	v_perm_b32 v18, v67, v68, s67
	v_perm_b32 v19, v68, v69, s67
	v_perm_b32 v20, v69, v70, s67
	v_perm_b32 v21, v70, v71, s67
	s_nop 0
	s_add_i32 s43, s11, 20
	s_ashr_i32 s43, s43, 3
	v_add_u32_e32 v54, s43, v124
	v_mfma_f32_16x16x32_bf16 v[38:41], v[18:21], v[76:79], v[38:41]
	v_mfma_f32_16x16x32_bf16 v[34:37], v[18:21], v[80:83], v[34:37]
	v_mfma_f32_16x16x32_bf16 v[26:29], v[18:21], v[84:87], v[26:29]
	s_waitcnt lgkmcnt(0)
	v_mfma_f32_16x16x32_bf16 v[18:21], v[18:21], v[92:95], v[6:9]
	s_nop 2
	v_min_u32_e32 v6, 32, v54
	v_mad_u32_u24 v6, v6, s58, v0
	ds_read_b128 v[62:65], v6 offset:320
	v_mfma_f32_16x16x32_bf16 v[42:45], v[68:71], v[80:83], v[42:45]
	v_mfma_f32_16x16x32_bf16 v[30:33], v[68:71], v[84:87], v[30:33]
	v_mfma_f32_16x16x32_bf16 v[22:25], v[68:71], v[92:95], v[22:25]
	v_mfma_f32_16x16x32_bf16 v[10:13], v[14:17], v[50:53], v[10:13]
	s_nop 0
	v_add_u32_e32 v6, 0xa0, v66
	v_min_i32_e32 v6, 0x1ff8, v6
	v_ashrrev_i32_e32 v7, 31, v6
	v_lshl_add_u64 v[14:15], v[6:7], 1, s[22:23]
	global_load_dwordx4 v[6:9], v[14:15], off
	global_load_dword v126, v[14:15], off offset:-4
	s_waitcnt vmcnt(8)
; #define CONV_LOADA(e_, k_) do { const int xh_ = min(32 * (e_) + xa, L - 8); rh[k_] = *(const u32x4a4*)(Rc + xh_); asm volatile("" ::: "memory"); rl[k_] = *(const unsigned*)(Rc + xh_ - 2); } while (0)
; #define CONV_BLOCK(DO0, DO1) do { CONV_STEP(0, DO0, DO1); CONV_STEP(1, DO0, DO1); CONV_STEP(2, DO0, DO1); CONV_STEP(3, DO0, DO1); CONV_STEP(4, DO0, DO1); CONV_STEP(5, DO0, DO1); CONV_STEP(6, DO0, DO1); CONV_STEP(7, DO0, DO1); } while (0)
; template <bool PROMPT, int HALF>
; __device__ __forceinline__ void conv_item(unsigned char* ws, KArgs ka, int ib, int oct, int g, LAS unsigned char* lds, int tid, int lane, int wave) {
;     ...
; #pragma unroll
;     for (int k = 0; k < DA; ++k) CONV_LOADA(E0 + k, k);
;     { unsigned zz_ = 0u; asm volatile("" : "+v"(zz_));
; #pragma unroll
;       for (int k = 0; k < W; ++k) F1[k] = (u32x4){zz_, zz_, zz_, zz_}; }
;     for (int e = E0; e < E1; e += 8) CONV_BLOCK(false, true);
;     { unsigned zz_ = 0u; asm volatile("" : "+v"(zz_));
; #pragma unroll
;       for (int k = 0; k < W; ++k) F0[k] = (u32x4){zz_, zz_, zz_, zz_}; }
;     for (int e = E1; e < E2; e += 8) CONV_BLOCK(true, true);
	v_perm_b32 v14, v96, v72, s67
	v_perm_b32 v15, v72, v73, s67
	v_perm_b32 v16, v73, v74, s67
	v_perm_b32 v17, v74, v75, s67
	s_nop 0
	s_add_i32 s43, s11, 21
	s_ashr_i32 s43, s43, 3
	v_add_u32_e32 v50, s43, v124
	v_mfma_f32_16x16x32_bf16 v[38:41], v[14:17], v[80:83], v[38:41]
	v_mfma_f32_16x16x32_bf16 v[34:37], v[14:17], v[84:87], v[34:37]
	v_mfma_f32_16x16x32_bf16 v[26:29], v[14:17], v[92:95], v[26:29]
	s_waitcnt lgkmcnt(0)
	v_mfma_f32_16x16x32_bf16 v[14:17], v[14:17], v[62:65], v[18:21]
	s_nop 2
	v_min_u32_e32 v18, 32, v50
	v_mad_u32_u24 v18, v18, s58, v0
	ds_read_b128 v[58:61], v18 offset:384
	v_mfma_f32_16x16x32_bf16 v[42:45], v[72:75], v[84:87], v[42:45]
	v_mfma_f32_16x16x32_bf16 v[30:33], v[72:75], v[92:95], v[30:33]
	v_mfma_f32_16x16x32_bf16 v[22:25], v[72:75], v[62:65], v[22:25]
	v_mfma_f32_16x16x32_bf16 v[18:21], v[68:71], v[76:79], v[10:13]
	s_nop 0
	s_nop 1
	v_add_u32_e32 v10, 0xc0, v66
	v_min_i32_e32 v10, 0x1ff8, v10
	v_ashrrev_i32_e32 v11, 31, v10
	v_lshl_add_u64 v[50:51], v[10:11], 1, s[22:23]
	global_load_dwordx4 v[10:13], v[50:51], off
	global_load_dword v127, v[50:51], off offset:-4
	s_waitcnt vmcnt(8)
	v_perm_b32 v50, v97, v46, s67
	v_perm_b32 v51, v46, v47, s67
	v_perm_b32 v52, v47, v48, s67
	v_perm_b32 v53, v48, v49, s67
	s_nop 0
	s_add_i32 s43, s11, 22
	s_ashr_i32 s43, s43, 3
	v_add_u32_e32 v54, s43, v124
	v_mfma_f32_16x16x32_bf16 v[38:41], v[50:53], v[84:87], v[38:41]
	v_mfma_f32_16x16x32_bf16 v[34:37], v[50:53], v[92:95], v[34:37]
	v_mfma_f32_16x16x32_bf16 v[26:29], v[50:53], v[62:65], v[26:29]
	s_waitcnt lgkmcnt(0)
	v_mfma_f32_16x16x32_bf16 v[50:53], v[50:53], v[58:61], v[14:17]
	s_nop 2
	v_min_u32_e32 v14, 32, v54
	v_mad_u32_u24 v14, v14, s58, v0
	ds_read_b128 v[54:57], v14 offset:448
	v_mfma_f32_16x16x32_bf16 v[42:45], v[46:49], v[92:95], v[42:45]
	v_mfma_f32_16x16x32_bf16 v[30:33], v[46:49], v[62:65], v[30:33]
	v_mfma_f32_16x16x32_bf16 v[22:25], v[46:49], v[58:61], v[22:25]
	v_mfma_f32_16x16x32_bf16 v[68:71], v[72:75], v[80:83], v[18:21]
	s_nop 0
	v_add_u32_e32 v14, 0xe0, v66
	v_min_i32_e32 v14, 0x1ff8, v14
	v_ashrrev_i32_e32 v15, 31, v14
	v_lshl_add_u64 v[18:19], v[14:15], 1, s[22:23]
	global_load_dwordx4 v[14:17], v[18:19], off
	global_load_dword v128, v[18:19], off offset:-4
	s_waitcnt vmcnt(8)
	v_perm_b32 v18, v98, v88, s67
	v_perm_b32 v19, v88, v89, s67
	v_perm_b32 v20, v89, v90, s67
	v_perm_b32 v21, v90, v91, s67
	s_nop 0
	s_add_i32 s43, s11, 23
	s_ashr_i32 s43, s43, 3
	v_mfma_f32_16x16x32_bf16 v[38:41], v[18:21], v[92:95], v[38:41]
	v_mfma_f32_16x16x32_bf16 v[34:37], v[18:21], v[62:65], v[34:37]
	v_mfma_f32_16x16x32_bf16 v[26:29], v[18:21], v[58:61], v[26:29]
	s_waitcnt lgkmcnt(0)
	v_mfma_f32_16x16x32_bf16 v[18:21], v[18:21], v[54:57], v[50:53]
	s_nop 2
	v_add_u32_e32 v50, s43, v124
	v_mfma_f32_16x16x32_bf16 v[46:49], v[46:49], v[84:87], v[68:71]
	v_min_u32_e32 v50, 32, v50
	v_mad_u32_u24 v50, v50, s58, v0
	ds_read_b128 v[50:53], v50
	v_mfma_f32_16x16x32_bf16 v[42:45], v[88:91], v[62:65], v[42:45]
	v_mfma_f32_16x16x32_bf16 v[30:33], v[88:91], v[58:61], v[30:33]
	v_mfma_f32_16x16x32_bf16 v[22:25], v[88:91], v[54:57], v[22:25]
	v_mfma_f32_16x16x32_bf16 v[46:49], v[88:91], v[92:95], v[46:49]
	s_nop 0
	s_add_i32 s11, s11, 8
	s_cmp_gt_u32 s11, 0xffffff70
	v_add_u32_e32 v66, 0x100, v66
	s_cbranch_scc0 .LBB0_751
	v_mov_b32_e32 v66, v1
	v_mov_b32_e32 v70, 0
	v_add_u32_e32 v129, 0xffffefa0, v123
	s_movk_i32 s11, 0xff71
	s_movk_i32 s43, 0xde40
	v_mov_b32_e32 v71, v70
	v_mov_b32_e32 v72, v70
	v_mov_b32_e32 v73, v70
	v_mov_b32_e32 v78, v70
	v_mov_b32_e32 v79, v70
	v_mov_b32_e32 v80, v70
	v_mov_b32_e32 v81, v70
	v_mov_b32_e32 v94, v70
	v_mov_b32_e32 v95, v70
	v_mov_b32_e32 v96, v70
	v_mov_b32_e32 v97, v70
	v_mov_b32_e32 v106, v70
	v_mov_b32_e32 v107, v70
	v_mov_b32_e32 v108, v70
	v_mov_b32_e32 v109, v70
	v_mov_b32_e32 v82, v70
	v_mov_b32_e32 v83, v70
	v_mov_b32_e32 v84, v70
	v_mov_b32_e32 v85, v70
	v_mov_b32_e32 v98, v70
	v_mov_b32_e32 v99, v70
	v_mov_b32_e32 v100, v70
	v_mov_b32_e32 v101, v70
	v_mov_b32_e32 v110, v70
	v_mov_b32_e32 v111, v70
	v_mov_b32_e32 v112, v70
	v_mov_b32_e32 v113, v70
	v_mov_b32_e32 v102, v70
	v_mov_b32_e32 v103, v70
	v_mov_b32_e32 v104, v70
	v_mov_b32_e32 v105, v70
	v_mov_b32_e32 v67, v66
	v_mov_b32_e32 v68, v66
	v_mov_b32_e32 v69, v66
	v_mov_b32_e32 v74, v66
	v_mov_b32_e32 v75, v66
	v_mov_b32_e32 v76, v66
	v_mov_b32_e32 v77, v66
	v_mov_b32_e32 v86, v66
	v_mov_b32_e32 v87, v66
	v_mov_b32_e32 v88, v66
	v_mov_b32_e32 v89, v66
	v_mov_b32_e32 v90, v66
	v_mov_b32_e32 v91, v66
	v_mov_b32_e32 v92, v66
	v_mov_b32_e32 v93, v66
.LBB0_753:
	v_min_i32_e32 v114, 0x1ff8, v129
	v_ashrrev_i32_e32 v115, 31, v114
	v_lshl_add_u64 v[114:115], v[114:115], 1, s[22:23]
	global_load_dwordx4 v[118:121], v[114:115], off
	global_load_dword v138, v[114:115], off offset:-4
	s_waitcnt vmcnt(8)
	v_perm_b32 v114, v125, v2, s67
	v_perm_b32 v115, v2, v3, s67
	v_perm_b32 v116, v3, v4, s67
	v_perm_b32 v117, v4, v5, s67
	s_nop 0
	s_add_i32 s54, s11, 16
	s_ashr_i32 s54, s54, 3
	v_mfma_f32_16x16x32_bf16 v[102:105], v[2:5], v[90:93], v[102:105]
	s_and_b32 s55, s43, 0x1c0
	v_mfma_f32_16x16x32_bf16 v[90:93], v[114:117], v[90:93], v[106:109]
	s_nop 2
	v_add_u32_e32 v106, s54, v122
	v_min_u32_e32 v106, 32, v106
	v_add_u32_e32 v107, s54, v124
	v_mul_u32_u24_e32 v106, 0x210, v106
	v_min_u32_e32 v107, 32, v107
	v_add3_u32 v106, v0, v106, s55
	v_mul_u32_u24_e32 v107, 0x210, v107
	v_mfma_f32_16x16x32_bf16 v[46:49], v[2:5], v[62:65], v[46:49]
	v_mfma_f32_16x16x32_bf16 v[38:41], v[114:117], v[62:65], v[38:41]
	v_mfma_f32_16x16x32_bf16 v[62:65], v[2:5], v[86:89], v[110:113]
	v_mfma_f32_16x16x32_bf16 v[42:45], v[2:5], v[58:61], v[42:45]
	v_mfma_f32_16x16x32_bf16 v[98:101], v[2:5], v[74:77], v[98:101]
	v_mfma_f32_16x16x32_bf16 v[30:33], v[2:5], v[54:57], v[30:33]
	s_waitcnt lgkmcnt(1)
	v_mfma_f32_16x16x32_bf16 v[82:85], v[2:5], v[66:69], v[82:85]
	s_waitcnt lgkmcnt(0)
	v_mfma_f32_16x16x32_bf16 v[2:5], v[2:5], v[50:53], v[22:25]
	s_nop 2
	v_add3_u32 v22, v0, v107, s55
	ds_read_b128 v[106:109], v106
	ds_read_b128 v[110:113], v22
	v_mfma_f32_16x16x32_bf16 v[94:97], v[114:117], v[86:89], v[94:97]
	v_mfma_f32_16x16x32_bf16 v[34:37], v[114:117], v[58:61], v[34:37]
	v_mfma_f32_16x16x32_bf16 v[78:81], v[114:117], v[74:77], v[78:81]
	v_mfma_f32_16x16x32_bf16 v[26:29], v[114:117], v[54:57], v[26:29]
	v_mfma_f32_16x16x32_bf16 v[70:73], v[114:117], v[66:69], v[70:73]
	v_mfma_f32_16x16x32_bf16 v[22:25], v[114:117], v[50:53], v[18:21]
	s_nop 0
	s_nop 1
	v_add_u32_e32 v18, 32, v129
	v_min_i32_e32 v18, 0x1ff8, v18
	v_ashrrev_i32_e32 v19, 31, v18
	v_lshl_add_u64 v[114:115], v[18:19], 1, s[22:23]
	global_load_dwordx4 v[18:21], v[114:115], off
	global_load_dword v139, v[114:115], off offset:-4
	s_waitcnt vmcnt(8)
	v_perm_b32 v114, v126, v6, s67
	v_perm_b32 v115, v6, v7, s67
	v_perm_b32 v116, v7, v8, s67
	v_perm_b32 v117, v8, v9, s67
	s_nop 0
	s_add_i32 s54, s11, 17
	s_ashr_i32 s54, s54, 3
	v_mfma_f32_16x16x32_bf16 v[46:49], v[6:9], v[58:61], v[46:49]
	s_add_i32 s55, s43, 0x240
	s_and_b32 s55, s55, 0x1c0
	v_mfma_f32_16x16x32_bf16 v[38:41], v[114:117], v[58:61], v[38:41]
	v_mfma_f32_16x16x32_bf16 v[58:61], v[6:9], v[74:77], v[62:65]
	v_mfma_f32_16x16x32_bf16 v[62:65], v[114:117], v[74:77], v[94:97]
	s_nop 2
	v_add_u32_e32 v94, s54, v122
	v_min_u32_e32 v94, 32, v94
	v_add_u32_e32 v95, s54, v124
	v_mul_u32_u24_e32 v94, 0x210, v94
	v_min_u32_e32 v95, 32, v95
	v_add3_u32 v94, v0, v94, s55
	v_mul_u32_u24_e32 v95, 0x210, v95
	v_mfma_f32_16x16x32_bf16 v[102:105], v[6:9], v[86:89], v[102:105]
	v_mfma_f32_16x16x32_bf16 v[86:89], v[114:117], v[86:89], v[90:93]
	v_mfma_f32_16x16x32_bf16 v[42:45], v[6:9], v[54:57], v[42:45]
	v_mfma_f32_16x16x32_bf16 v[90:93], v[6:9], v[66:69], v[98:101]
	v_mfma_f32_16x16x32_bf16 v[30:33], v[6:9], v[50:53], v[30:33]
	s_waitcnt lgkmcnt(1)
	v_mfma_f32_16x16x32_bf16 v[82:85], v[6:9], v[106:109], v[82:85]
	s_waitcnt lgkmcnt(0)
	v_mfma_f32_16x16x32_bf16 v[2:5], v[6:9], v[110:113], v[2:5]
	v_add3_u32 v6, v0, v95, s55
	ds_read_b128 v[94:97], v94
	ds_read_b128 v[98:101], v6
	v_mfma_f32_16x16x32_bf16 v[34:37], v[114:117], v[54:57], v[34:37]
	v_mfma_f32_16x16x32_bf16 v[78:81], v[114:117], v[66:69], v[78:81]
	v_mfma_f32_16x16x32_bf16 v[26:29], v[114:117], v[50:53], v[26:29]
	v_mfma_f32_16x16x32_bf16 v[70:73], v[114:117], v[106:109], v[70:73]
	v_mfma_f32_16x16x32_bf16 v[6:9], v[114:117], v[110:113], v[22:25]
	s_nop 0
	s_nop 1
	v_add_u32_e32 v22, 64, v129
	v_min_i32_e32 v22, 0x1ff8, v22
	v_ashrrev_i32_e32 v23, 31, v22
	v_lshl_add_u64 v[114:115], v[22:23], 1, s[22:23]
	global_load_dwordx4 v[22:25], v[114:115], off
	global_load_dword v140, v[114:115], off offset:-4
	s_waitcnt vmcnt(8)
	v_perm_b32 v114, v127, v10, s67
	v_perm_b32 v115, v10, v11, s67
	v_perm_b32 v116, v11, v12, s67
	v_perm_b32 v117, v12, v13, s67
	s_nop 0
	s_add_i32 s54, s11, 18
	s_ashr_i32 s54, s54, 3
	v_mfma_f32_16x16x32_bf16 v[102:105], v[10:13], v[74:77], v[102:105]
	s_add_i32 s55, s43, 0x280
	s_and_b32 s55, s55, 0x1c0
	v_mfma_f32_16x16x32_bf16 v[74:77], v[114:117], v[74:77], v[86:89]
	s_nop 2
	v_add_u32_e32 v86, s54, v122
	v_min_u32_e32 v86, 32, v86
	v_add_u32_e32 v87, s54, v124
	v_mul_u32_u24_e32 v86, 0x210, v86
	v_min_u32_e32 v87, 32, v87
	v_add3_u32 v86, v0, v86, s55
	v_mul_u32_u24_e32 v87, 0x210, v87
	v_mfma_f32_16x16x32_bf16 v[46:49], v[10:13], v[54:57], v[46:49]
	v_mfma_f32_16x16x32_bf16 v[38:41], v[114:117], v[54:57], v[38:41]
	v_mfma_f32_16x16x32_bf16 v[54:57], v[10:13], v[66:69], v[58:61]
	v_mfma_f32_16x16x32_bf16 v[58:61], v[114:117], v[66:69], v[62:65]
	v_mfma_f32_16x16x32_bf16 v[42:45], v[10:13], v[50:53], v[42:45]
	v_mfma_f32_16x16x32_bf16 v[62:65], v[10:13], v[106:109], v[90:93]
	v_mfma_f32_16x16x32_bf16 v[30:33], v[10:13], v[110:113], v[30:33]
	s_waitcnt lgkmcnt(1)
	v_mfma_f32_16x16x32_bf16 v[82:85], v[10:13], v[94:97], v[82:85]
	s_waitcnt lgkmcnt(0)
	v_mfma_f32_16x16x32_bf16 v[2:5], v[10:13], v[98:101], v[2:5]
	v_add3_u32 v10, v0, v87, s55
	ds_read_b128 v[130:133], v86
	ds_read_b128 v[134:137], v10
	v_mfma_f32_16x16x32_bf16 v[34:37], v[114:117], v[50:53], v[34:37]
	v_mfma_f32_16x16x32_bf16 v[78:81], v[114:117], v[106:109], v[78:81]
	v_mfma_f32_16x16x32_bf16 v[26:29], v[114:117], v[110:113], v[26:29]
	v_mfma_f32_16x16x32_bf16 v[70:73], v[114:117], v[94:97], v[70:73]
	v_mfma_f32_16x16x32_bf16 v[6:9], v[114:117], v[98:101], v[6:9]
	s_nop 0
	v_add_u32_e32 v10, 0x60, v129
	v_min_i32_e32 v10, 0x1ff8, v10
	v_ashrrev_i32_e32 v11, 31, v10
	v_lshl_add_u64 v[10:11], v[10:11], 1, s[22:23]
	global_load_dwordx4 v[114:117], v[10:11], off
	global_load_dword v142, v[10:11], off offset:-4
	s_waitcnt vmcnt(8)
; #define CONV_BLOCK(DO0, DO1) do { CONV_STEP(0, DO0, DO1); CONV_STEP(1, DO0, DO1); CONV_STEP(2, DO0, DO1); CONV_STEP(3, DO0, DO1); CONV_STEP(4, DO0, DO1); CONV_STEP(5, DO0, DO1); CONV_STEP(6, DO0, DO1); CONV_STEP(7, DO0, DO1); } while (0)
; template <bool PROMPT, int HALF>
; __device__ __forceinline__ void conv_item(unsigned char* ws, KArgs ka, int ib, int oct, int g, LAS unsigned char* lds, int tid, int lane, int wave) {
;     ...
;     for (int e = E1; e < E2; e += 8) CONV_BLOCK(true, true);
	v_perm_b32 v10, v128, v14, s67
	v_perm_b32 v11, v14, v15, s67
	v_perm_b32 v12, v15, v16, s67
	v_perm_b32 v13, v16, v17, s67
	s_nop 0
	s_add_i32 s54, s11, 19
	s_ashr_i32 s54, s54, 3
	v_mfma_f32_16x16x32_bf16 v[86:89], v[14:17], v[66:69], v[102:105]
	s_add_i32 s55, s43, 0x2c0
	s_and_b32 s55, s55, 0x1c0
	v_mfma_f32_16x16x32_bf16 v[66:69], v[10:13], v[66:69], v[74:77]
	s_nop 2
	v_add_u32_e32 v74, s54, v122
	v_mfma_f32_16x16x32_bf16 v[46:49], v[14:17], v[50:53], v[46:49]
	v_min_u32_e32 v74, 32, v74
	v_mfma_f32_16x16x32_bf16 v[38:41], v[10:13], v[50:53], v[38:41]
	v_mfma_f32_16x16x32_bf16 v[50:53], v[14:17], v[106:109], v[54:57]
	v_mfma_f32_16x16x32_bf16 v[54:57], v[10:13], v[106:109], v[58:61]
	v_mfma_f32_16x16x32_bf16 v[58:61], v[14:17], v[94:97], v[62:65]
	v_mfma_f32_16x16x32_bf16 v[62:65], v[10:13], v[94:97], v[78:81]
	s_nop 2
	v_add_u32_e32 v79, s54, v124
	v_mul_u32_u24_e32 v78, 0x210, v74
	v_min_u32_e32 v79, 32, v79
	v_add3_u32 v78, v0, v78, s55
	v_mul_u32_u24_e32 v79, 0x210, v79
	v_mfma_f32_16x16x32_bf16 v[42:45], v[14:17], v[110:113], v[42:45]
	v_mfma_f32_16x16x32_bf16 v[30:33], v[14:17], v[98:101], v[30:33]
	s_waitcnt lgkmcnt(1)
	v_mfma_f32_16x16x32_bf16 v[74:77], v[14:17], v[130:133], v[82:85]
	s_waitcnt lgkmcnt(0)
	v_mfma_f32_16x16x32_bf16 v[14:17], v[14:17], v[134:137], v[2:5]
	s_nop 2
	v_add3_u32 v2, v0, v79, s55
	ds_read_b128 v[78:81], v78
	ds_read_b128 v[82:85], v2
	v_mfma_f32_16x16x32_bf16 v[34:37], v[10:13], v[110:113], v[34:37]
	v_mfma_f32_16x16x32_bf16 v[26:29], v[10:13], v[98:101], v[26:29]
	v_mfma_f32_16x16x32_bf16 v[70:73], v[10:13], v[130:133], v[70:73]
	v_mfma_f32_16x16x32_bf16 v[6:9], v[10:13], v[134:137], v[6:9]
	s_nop 0
	v_add_u32_e32 v2, 0x80, v129
	v_min_i32_e32 v2, 0x1ff8, v2
	v_ashrrev_i32_e32 v3, 31, v2
	v_lshl_add_u64 v[10:11], v[2:3], 1, s[22:23]
	global_load_dwordx4 v[2:5], v[10:11], off
	global_load_dword v125, v[10:11], off offset:-4
	s_waitcnt vmcnt(8)
	v_perm_b32 v10, v138, v118, s67
	v_perm_b32 v11, v118, v119, s67
	v_perm_b32 v12, v119, v120, s67
	v_perm_b32 v13, v120, v121, s67
	s_nop 0
	s_add_i32 s54, s11, 20
	s_ashr_i32 s54, s54, 3
	v_mfma_f32_16x16x32_bf16 v[102:105], v[10:13], v[130:133], v[62:65]
	s_add_i32 s55, s43, 0x300
	s_and_b32 s55, s55, 0x1c0
	s_nop 0
	v_add_u32_e32 v62, s54, v122
	v_add_u32_e32 v63, s54, v124
	v_min_u32_e32 v62, 32, v62
	v_min_u32_e32 v63, 32, v63
	v_mul_u32_u24_e32 v62, 0x210, v62
	v_mul_u32_u24_e32 v63, 0x210, v63
	v_add3_u32 v62, v0, v62, s55
	v_add3_u32 v63, v0, v63, s55
	ds_read_b128 v[90:93], v62
	ds_read_b128 v[62:65], v63
	v_mfma_f32_16x16x32_bf16 v[86:89], v[118:121], v[106:109], v[86:89]
	v_mfma_f32_16x16x32_bf16 v[66:69], v[10:13], v[106:109], v[66:69]
	v_mfma_f32_16x16x32_bf16 v[46:49], v[118:121], v[110:113], v[46:49]
	v_mfma_f32_16x16x32_bf16 v[38:41], v[10:13], v[110:113], v[38:41]
	v_mfma_f32_16x16x32_bf16 v[50:53], v[118:121], v[94:97], v[50:53]
	v_mfma_f32_16x16x32_bf16 v[54:57], v[10:13], v[94:97], v[54:57]
	v_mfma_f32_16x16x32_bf16 v[42:45], v[118:121], v[98:101], v[42:45]
	v_mfma_f32_16x16x32_bf16 v[34:37], v[10:13], v[98:101], v[34:37]
	v_mfma_f32_16x16x32_bf16 v[58:61], v[118:121], v[130:133], v[58:61]
	v_mfma_f32_16x16x32_bf16 v[30:33], v[118:121], v[134:137], v[30:33]
	v_mfma_f32_16x16x32_bf16 v[26:29], v[10:13], v[134:137], v[26:29]
	s_waitcnt lgkmcnt(3)
	v_mfma_f32_16x16x32_bf16 v[74:77], v[118:121], v[78:81], v[74:77]
	v_mfma_f32_16x16x32_bf16 v[70:73], v[10:13], v[78:81], v[70:73]
	s_waitcnt lgkmcnt(2)
	v_mfma_f32_16x16x32_bf16 v[14:17], v[118:121], v[82:85], v[14:17]
	v_mfma_f32_16x16x32_bf16 v[10:13], v[10:13], v[82:85], v[6:9]
	s_nop 0
	s_nop 1
	v_add_u32_e32 v6, 0xa0, v129
	v_min_i32_e32 v6, 0x1ff8, v6
	v_ashrrev_i32_e32 v7, 31, v6
	v_lshl_add_u64 v[106:107], v[6:7], 1, s[22:23]
	global_load_dwordx4 v[6:9], v[106:107], off
	global_load_dword v126, v[106:107], off offset:-4
	s_waitcnt vmcnt(8)
	v_perm_b32 v106, v139, v18, s67
	v_perm_b32 v107, v18, v19, s67
	v_perm_b32 v108, v19, v20, s67
	v_perm_b32 v109, v20, v21, s67
	s_nop 0
	s_add_i32 s54, s11, 21
	s_ashr_i32 s54, s54, 3
	v_mfma_f32_16x16x32_bf16 v[110:113], v[18:21], v[94:97], v[86:89]
	s_add_i32 s55, s43, 0x340
	s_and_b32 s55, s55, 0x1c0
	v_mfma_f32_16x16x32_bf16 v[66:69], v[106:109], v[94:97], v[66:69]
	v_mfma_f32_16x16x32_bf16 v[94:97], v[18:21], v[78:81], v[58:61]
	s_nop 2
	v_add_u32_e32 v58, s54, v122
	v_min_u32_e32 v58, 32, v58
	v_add_u32_e32 v59, s54, v124
	v_mul_u32_u24_e32 v58, 0x210, v58
	v_min_u32_e32 v59, 32, v59
	v_add3_u32 v58, v0, v58, s55
	v_mul_u32_u24_e32 v59, 0x210, v59
	v_mfma_f32_16x16x32_bf16 v[46:49], v[18:21], v[98:101], v[46:49]
	v_mfma_f32_16x16x32_bf16 v[50:53], v[18:21], v[130:133], v[50:53]
	v_mfma_f32_16x16x32_bf16 v[42:45], v[18:21], v[134:137], v[42:45]
	v_mfma_f32_16x16x32_bf16 v[30:33], v[18:21], v[82:85], v[30:33]
	s_waitcnt lgkmcnt(1)
	v_mfma_f32_16x16x32_bf16 v[74:77], v[18:21], v[90:93], v[74:77]
	s_waitcnt lgkmcnt(0)
	v_mfma_f32_16x16x32_bf16 v[14:17], v[18:21], v[62:65], v[14:17]
	v_add3_u32 v18, v0, v59, s55
	ds_read_b128 v[86:89], v58
	ds_read_b128 v[58:61], v18
	v_mfma_f32_16x16x32_bf16 v[38:41], v[106:109], v[98:101], v[38:41]
	v_mfma_f32_16x16x32_bf16 v[54:57], v[106:109], v[130:133], v[54:57]
	v_mfma_f32_16x16x32_bf16 v[34:37], v[106:109], v[134:137], v[34:37]
	v_mfma_f32_16x16x32_bf16 v[98:101], v[106:109], v[78:81], v[102:105]
	v_mfma_f32_16x16x32_bf16 v[26:29], v[106:109], v[82:85], v[26:29]
	v_mfma_f32_16x16x32_bf16 v[70:73], v[106:109], v[90:93], v[70:73]
	v_mfma_f32_16x16x32_bf16 v[18:21], v[106:109], v[62:65], v[10:13]
	s_nop 0
	s_nop 1
	v_add_u32_e32 v10, 0xc0, v129
	v_min_i32_e32 v10, 0x1ff8, v10
	v_ashrrev_i32_e32 v11, 31, v10
	v_lshl_add_u64 v[102:103], v[10:11], 1, s[22:23]
	global_load_dwordx4 v[10:13], v[102:103], off
	global_load_dword v127, v[102:103], off offset:-4
	s_waitcnt vmcnt(8)
; #define CONV_LOADA(e_, k_) do { const int xh_ = min(32 * (e_) + xa, L - 8); rh[k_] = *(const u32x4a4*)(Rc + xh_); asm volatile("" ::: "memory"); rl[k_] = *(const unsigned*)(Rc + xh_ - 2); } while (0)
; #define CONV_BLOCK(DO0, DO1) do { CONV_STEP(0, DO0, DO1); CONV_STEP(1, DO0, DO1); CONV_STEP(2, DO0, DO1); CONV_STEP(3, DO0, DO1); CONV_STEP(4, DO0, DO1); CONV_STEP(5, DO0, DO1); CONV_STEP(6, DO0, DO1); CONV_STEP(7, DO0, DO1); } while (0)
; template <bool PROMPT, int HALF>
; __device__ __forceinline__ void conv_item(unsigned char* ws, KArgs ka, int ib, int oct, int g, LAS unsigned char* lds, int tid, int lane, int wave) {
;     ...
; #pragma unroll
;     for (int k = 0; k < DA; ++k) CONV_LOADA(E0 + k, k);
;     { unsigned zz_ = 0u; asm volatile("" : "+v"(zz_));
; #pragma unroll
;       for (int k = 0; k < W; ++k) F1[k] = (u32x4){zz_, zz_, zz_, zz_}; }
;     for (int e = E0; e < E1; e += 8) CONV_BLOCK(false, true);
;     { unsigned zz_ = 0u; asm volatile("" : "+v"(zz_));
; #pragma unroll
;       for (int k = 0; k < W; ++k) F0[k] = (u32x4){zz_, zz_, zz_, zz_}; }
;     for (int e = E1; e < E2; e += 8) CONV_BLOCK(true, true);
;     for (int e = E2; e < E3; e += 8) CONV_BLOCK(true, false);
	v_perm_b32 v102, v140, v22, s67
	v_perm_b32 v103, v22, v23, s67
	v_perm_b32 v104, v23, v24, s67
	v_perm_b32 v105, v24, v25, s67
	s_nop 0
	s_add_i32 s54, s11, 22
	s_ashr_i32 s54, s54, 3
	v_mfma_f32_16x16x32_bf16 v[118:121], v[102:105], v[78:81], v[54:57]
	s_add_i32 s55, s43, 0x380
	s_and_b32 s55, s55, 0x1c0
	s_nop 0
	v_add_u32_e32 v54, s54, v122
	v_min_u32_e32 v54, 32, v54
	v_add_u32_e32 v55, s54, v124
	v_mul_u32_u24_e32 v54, 0x210, v54
	v_min_u32_e32 v55, 32, v55
	v_add3_u32 v54, v0, v54, s55
	v_mul_u32_u24_e32 v55, 0x210, v55
	v_mfma_f32_16x16x32_bf16 v[106:109], v[22:25], v[130:133], v[110:113]
	v_mfma_f32_16x16x32_bf16 v[66:69], v[102:105], v[130:133], v[66:69]
	v_mfma_f32_16x16x32_bf16 v[46:49], v[22:25], v[134:137], v[46:49]
	v_mfma_f32_16x16x32_bf16 v[50:53], v[22:25], v[78:81], v[50:53]
	v_mfma_f32_16x16x32_bf16 v[42:45], v[22:25], v[82:85], v[42:45]
	v_mfma_f32_16x16x32_bf16 v[130:133], v[22:25], v[90:93], v[94:97]
	v_mfma_f32_16x16x32_bf16 v[30:33], v[22:25], v[62:65], v[30:33]
	s_waitcnt lgkmcnt(1)
	v_mfma_f32_16x16x32_bf16 v[138:141], v[22:25], v[86:89], v[74:77]
	s_waitcnt lgkmcnt(0)
	v_mfma_f32_16x16x32_bf16 v[22:25], v[22:25], v[58:61], v[14:17]
	s_nop 2
	v_add3_u32 v14, v0, v55, s55
	ds_read_b128 v[74:77], v54
	ds_read_b128 v[54:57], v14
	v_mfma_f32_16x16x32_bf16 v[38:41], v[102:105], v[134:137], v[38:41]
	v_mfma_f32_16x16x32_bf16 v[34:37], v[102:105], v[82:85], v[34:37]
	v_mfma_f32_16x16x32_bf16 v[26:29], v[102:105], v[62:65], v[26:29]
	v_mfma_f32_16x16x32_bf16 v[70:73], v[102:105], v[86:89], v[70:73]
	v_mfma_f32_16x16x32_bf16 v[18:21], v[102:105], v[58:61], v[18:21]
	v_mfma_f32_16x16x32_bf16 v[134:137], v[102:105], v[90:93], v[98:101]
	s_nop 0
	v_add_u32_e32 v14, 0xe0, v129
	v_min_i32_e32 v14, 0x1ff8, v14
	v_ashrrev_i32_e32 v15, 31, v14
	v_lshl_add_u64 v[94:95], v[14:15], 1, s[22:23]
	global_load_dwordx4 v[14:17], v[94:95], off
	global_load_dword v128, v[94:95], off offset:-4
	s_waitcnt vmcnt(8)
	v_perm_b32 v142, v142, v114, s67
	v_perm_b32 v143, v114, v115, s67
	v_perm_b32 v144, v115, v116, s67
	v_perm_b32 v145, v116, v117, s67
	s_nop 0
	s_add_i32 s54, s11, 23
	s_ashr_i32 s54, s54, 3
	v_mfma_f32_16x16x32_bf16 v[110:113], v[114:117], v[90:93], v[50:53]
	s_add_i32 s55, s43, 0x3c0
	s_and_b32 s55, s55, 0x1c0
	s_nop 0
	v_add_u32_e32 v50, s54, v122
	v_add_u32_e32 v51, s54, v124
	v_min_u32_e32 v50, 32, v50
	v_min_u32_e32 v51, 32, v51
	v_mul_u32_u24_e32 v50, 0x210, v50
	v_mul_u32_u24_e32 v51, 0x210, v51
	v_add3_u32 v50, v0, v50, s55
	v_add3_u32 v51, v0, v51, s55
	v_mfma_f32_16x16x32_bf16 v[102:105], v[114:117], v[78:81], v[106:109]
	v_mfma_f32_16x16x32_bf16 v[106:109], v[142:145], v[78:81], v[66:69]
	s_nop 2
	ds_read_b128 v[66:69], v50
	ds_read_b128 v[50:53], v51
	v_mfma_f32_16x16x32_bf16 v[46:49], v[114:117], v[82:85], v[46:49]
	v_mfma_f32_16x16x32_bf16 v[38:41], v[142:145], v[82:85], v[38:41]
	v_mfma_f32_16x16x32_bf16 v[94:97], v[142:145], v[90:93], v[118:121]
	v_mfma_f32_16x16x32_bf16 v[42:45], v[114:117], v[62:65], v[42:45]
	v_mfma_f32_16x16x32_bf16 v[34:37], v[142:145], v[62:65], v[34:37]
	v_mfma_f32_16x16x32_bf16 v[98:101], v[114:117], v[86:89], v[130:133]
	v_mfma_f32_16x16x32_bf16 v[78:81], v[142:145], v[86:89], v[134:137]
	v_mfma_f32_16x16x32_bf16 v[30:33], v[114:117], v[58:61], v[30:33]
	v_mfma_f32_16x16x32_bf16 v[26:29], v[142:145], v[58:61], v[26:29]
	s_waitcnt lgkmcnt(3)
	v_mfma_f32_16x16x32_bf16 v[82:85], v[114:117], v[74:77], v[138:141]
	v_mfma_f32_16x16x32_bf16 v[70:73], v[142:145], v[74:77], v[70:73]
	s_waitcnt lgkmcnt(2)
	v_mfma_f32_16x16x32_bf16 v[22:25], v[114:117], v[54:57], v[22:25]
	v_mfma_f32_16x16x32_bf16 v[18:21], v[142:145], v[54:57], v[18:21]
	s_nop 0
	s_add_i32 s11, s11, 8
	s_addk_i32 s43, 0x200
	s_cmpk_lt_i32 s11, 0x79
	v_add_u32_e32 v129, 0x100, v129
	s_cbranch_scc1 .LBB0_753
	s_waitcnt lgkmcnt(0)
	v_add_u32_e32 v50, 18, v122
	v_add_u32_e32 v51, 0x1180, v123
	s_movk_i32 s11, 0x79
.LBB0_755:
	v_add_u32_e32 v52, 0xffffff20, v51
	v_min_i32_e32 v52, 0x1ff8, v52
	v_ashrrev_i32_e32 v53, 31, v52
	v_lshl_add_u64 v[56:57], v[52:53], 1, s[22:23]
	global_load_dwordx4 v[52:55], v[56:57], off
	global_load_dword v122, v[56:57], off offset:-4
	s_waitcnt vmcnt(8)
	v_perm_b32 v56, v125, v2, s67
	v_perm_b32 v57, v2, v3, s67
	v_perm_b32 v58, v3, v4, s67
	v_perm_b32 v59, v4, v5, s67
	s_nop 0
	v_add_u32_e32 v64, -1, v50
	v_min_u32_e32 v64, 32, v64
	v_mad_u32_u24 v123, v64, s58, v0
	v_mfma_f32_16x16x32_bf16 v[60:63], v[56:59], v[90:93], v[106:109]
	v_mfma_f32_16x16x32_bf16 v[106:109], v[2:5], v[86:89], v[110:113]
	s_nop 2
	ds_read_b128 v[110:113], v123 offset:64
	v_mfma_f32_16x16x32_bf16 v[94:97], v[56:59], v[86:89], v[94:97]
	v_mfma_f32_16x16x32_bf16 v[98:101], v[2:5], v[74:77], v[98:101]
	v_mfma_f32_16x16x32_bf16 v[78:81], v[56:59], v[74:77], v[78:81]
	s_waitcnt lgkmcnt(1)
	v_mfma_f32_16x16x32_bf16 v[82:85], v[2:5], v[66:69], v[82:85]
	v_mfma_f32_16x16x32_bf16 v[56:59], v[56:59], v[66:69], v[70:73]
	s_nop 0
	v_add_u32_e32 v64, 0xffffff40, v51
	v_min_i32_e32 v64, 0x1ff8, v64
	v_ashrrev_i32_e32 v65, 31, v64
	v_lshl_add_u64 v[64:65], v[64:65], 1, s[22:23]
	global_load_dwordx4 v[70:73], v[64:65], off
	global_load_dword v124, v[64:65], off offset:-4
	s_waitcnt vmcnt(8)
	v_perm_b32 v114, v126, v6, s67
	v_perm_b32 v115, v6, v7, s67
	v_perm_b32 v116, v7, v8, s67
	v_perm_b32 v117, v8, v9, s67
	s_nop 1

	v_mfma_f32_16x16x32_bf16 v[60:63], v[114:117], v[86:89], v[60:63]
	v_mfma_f32_16x16x32_bf16 v[106:109], v[6:9], v[74:77], v[106:109]
	v_mfma_f32_16x16x32_bf16 v[94:97], v[114:117], v[74:77], v[94:97]
	v_mfma_f32_16x16x32_bf16 v[98:101], v[6:9], v[66:69], v[98:101]
	v_mfma_f32_16x16x32_bf16 v[78:81], v[114:117], v[66:69], v[78:81]
	s_waitcnt lgkmcnt(0)
	v_mfma_f32_16x16x32_bf16 v[82:85], v[6:9], v[110:113], v[82:85]
	v_mfma_f32_16x16x32_bf16 v[56:59], v[114:117], v[110:113], v[56:59]
	ds_read_b128 v[114:117], v123 offset:128
	v_mfma_f32_16x16x32_bf16 v[2:5], v[2:5], v[90:93], v[102:105]
	s_nop 0
	v_add_u32_e32 v64, 0xffffff60, v51
	v_min_i32_e32 v64, 0x1ff8, v64
	v_ashrrev_i32_e32 v65, 31, v64
	v_lshl_add_u64 v[64:65], v[64:65], 1, s[22:23]
	global_load_dwordx4 v[102:105], v[64:65], off
	global_load_dword v129, v[64:65], off offset:-4
	s_waitcnt vmcnt(8)
	v_perm_b32 v90, v127, v10, s67
	v_perm_b32 v91, v10, v11, s67
	v_perm_b32 v92, v11, v12, s67
	v_perm_b32 v93, v12, v13, s67
	s_nop 0
	v_mfma_f32_16x16x32_bf16 v[106:109], v[10:13], v[66:69], v[106:109]
	ds_read_b128 v[118:121], v123 offset:192
	v_mfma_f32_16x16x32_bf16 v[94:97], v[90:93], v[66:69], v[94:97]
	v_mfma_f32_16x16x32_bf16 v[98:101], v[10:13], v[110:113], v[98:101]
	v_mfma_f32_16x16x32_bf16 v[78:81], v[90:93], v[110:113], v[78:81]
	s_waitcnt lgkmcnt(1)
	v_mfma_f32_16x16x32_bf16 v[82:85], v[10:13], v[114:117], v[82:85]
	v_mfma_f32_16x16x32_bf16 v[2:5], v[6:9], v[86:89], v[2:5]
	v_mfma_f32_16x16x32_bf16 v[60:63], v[90:93], v[74:77], v[60:63]
	v_mfma_f32_16x16x32_bf16 v[56:59], v[90:93], v[114:117], v[56:59]
	s_nop 0
	v_add_u32_e32 v6, 0xffffff80, v51
	v_min_i32_e32 v6, 0x1ff8, v6
	v_ashrrev_i32_e32 v7, 31, v6
	v_lshl_add_u64 v[6:7], v[6:7], 1, s[22:23]
	global_load_dwordx4 v[130:133], v[6:7], off
	global_load_dword v142, v[6:7], off offset:-4
	s_waitcnt vmcnt(8)
	v_perm_b32 v6, v128, v14, s67
	v_perm_b32 v7, v14, v15, s67
	v_perm_b32 v8, v15, v16, s67
	v_perm_b32 v9, v16, v17, s67
	s_nop 1

	v_mfma_f32_16x16x32_bf16 v[60:63], v[6:9], v[66:69], v[60:63]
	v_mfma_f32_16x16x32_bf16 v[86:89], v[14:17], v[110:113], v[106:109]
	v_mfma_f32_16x16x32_bf16 v[90:93], v[6:9], v[110:113], v[94:97]
	v_mfma_f32_16x16x32_bf16 v[94:97], v[14:17], v[114:117], v[98:101]
	v_mfma_f32_16x16x32_bf16 v[78:81], v[6:9], v[114:117], v[78:81]
	s_waitcnt lgkmcnt(0)
	v_mfma_f32_16x16x32_bf16 v[82:85], v[14:17], v[118:121], v[82:85]
	v_mfma_f32_16x16x32_bf16 v[6:9], v[6:9], v[118:121], v[56:59]
	s_nop 2
	ds_read_b128 v[56:59], v123 offset:256
	v_mfma_f32_16x16x32_bf16 v[10:13], v[10:13], v[74:77], v[2:5]
	s_nop 0
	s_nop 1
	v_add_u32_e32 v2, 0xffffffa0, v51
	v_min_i32_e32 v2, 0x1ff8, v2
	v_ashrrev_i32_e32 v3, 31, v2
	v_lshl_add_u64 v[64:65], v[2:3], 1, s[22:23]
	global_load_dwordx4 v[2:5], v[64:65], off
	global_load_dword v125, v[64:65], off offset:-4
	s_waitcnt vmcnt(8)
	v_perm_b32 v74, v122, v52, s67
	v_perm_b32 v75, v52, v53, s67
	v_perm_b32 v76, v53, v54, s67
	v_perm_b32 v77, v54, v55, s67
	s_nop 1

	v_mfma_f32_16x16x32_bf16 v[98:101], v[74:77], v[114:117], v[90:93]
	s_nop 2
	ds_read_b128 v[90:93], v123 offset:320
	v_mfma_f32_16x16x32_bf16 v[60:63], v[74:77], v[110:113], v[60:63]
	v_mfma_f32_16x16x32_bf16 v[86:89], v[52:55], v[114:117], v[86:89]
	v_mfma_f32_16x16x32_bf16 v[94:97], v[52:55], v[118:121], v[94:97]
	v_mfma_f32_16x16x32_bf16 v[78:81], v[74:77], v[118:121], v[78:81]
	s_waitcnt lgkmcnt(1)
	v_mfma_f32_16x16x32_bf16 v[82:85], v[52:55], v[56:59], v[82:85]
	v_mfma_f32_16x16x32_bf16 v[74:77], v[74:77], v[56:59], v[6:9]
	v_mfma_f32_16x16x32_bf16 v[10:13], v[14:17], v[66:69], v[10:13]
	s_nop 0
	s_nop 0
	v_subrev_u32_e32 v6, 64, v51
	v_min_i32_e32 v6, 0x1ff8, v6
	v_ashrrev_i32_e32 v7, 31, v6
	v_lshl_add_u64 v[14:15], v[6:7], 1, s[22:23]
	global_load_dwordx4 v[6:9], v[14:15], off
	global_load_dword v126, v[14:15], off offset:-4
	s_waitcnt vmcnt(8)
	v_perm_b32 v14, v124, v70, s67
	v_perm_b32 v15, v70, v71, s67
	v_perm_b32 v16, v71, v72, s67
	v_perm_b32 v17, v72, v73, s67
	s_nop 0
	v_mfma_f32_16x16x32_bf16 v[64:67], v[70:73], v[118:121], v[86:89]
	s_nop 2
	ds_read_b128 v[86:89], v123 offset:384
	v_mfma_f32_16x16x32_bf16 v[60:63], v[14:17], v[114:117], v[60:63]
	v_mfma_f32_16x16x32_bf16 v[98:101], v[14:17], v[118:121], v[98:101]
	v_mfma_f32_16x16x32_bf16 v[94:97], v[70:73], v[56:59], v[94:97]
	v_mfma_f32_16x16x32_bf16 v[78:81], v[14:17], v[56:59], v[78:81]
	s_waitcnt lgkmcnt(1)
	v_mfma_f32_16x16x32_bf16 v[82:85], v[70:73], v[90:93], v[82:85]
	v_mfma_f32_16x16x32_bf16 v[14:17], v[14:17], v[90:93], v[74:77]
	v_mfma_f32_16x16x32_bf16 v[52:55], v[52:55], v[110:113], v[10:13]
	s_nop 0
	s_nop 1
	v_subrev_u32_e32 v10, 32, v51
	v_min_i32_e32 v10, 0x1ff8, v10
	v_ashrrev_i32_e32 v11, 31, v10
	v_lshl_add_u64 v[68:69], v[10:11], 1, s[22:23]
	global_load_dwordx4 v[10:13], v[68:69], off
	global_load_dword v127, v[68:69], off offset:-4
	s_waitcnt vmcnt(8)
	v_perm_b32 v74, v129, v102, s67
	v_perm_b32 v75, v102, v103, s67
	v_perm_b32 v76, v103, v104, s67
	v_perm_b32 v77, v104, v105, s67
	s_nop 1

; #define CONV_LOADA(e_, k_) do { const int xh_ = min(32 * (e_) + xa, L - 8); rh[k_] = *(const u32x4a4*)(Rc + xh_); asm volatile("" ::: "memory"); rl[k_] = *(const unsigned*)(Rc + xh_ - 2); } while (0)
; #define CONV_BLOCK(DO0, DO1) do { CONV_STEP(0, DO0, DO1); CONV_STEP(1, DO0, DO1); CONV_STEP(2, DO0, DO1); CONV_STEP(3, DO0, DO1); CONV_STEP(4, DO0, DO1); CONV_STEP(5, DO0, DO1); CONV_STEP(6, DO0, DO1); CONV_STEP(7, DO0, DO1); } while (0)
; template <bool PROMPT, int HALF>
; __device__ __forceinline__ void conv_item(unsigned char* ws, KArgs ka, int ib, int oct, int g, LAS unsigned char* lds, int tid, int lane, int wave) {
;     ...
; #pragma unroll
;     for (int k = 0; k < DA; ++k) CONV_LOADA(E0 + k, k);
;     { unsigned zz_ = 0u; asm volatile("" : "+v"(zz_));
; #pragma unroll
;       for (int k = 0; k < W; ++k) F1[k] = (u32x4){zz_, zz_, zz_, zz_}; }
;     for (int e = E0; e < E1; e += 8) CONV_BLOCK(false, true);
;     { unsigned zz_ = 0u; asm volatile("" : "+v"(zz_));
; #pragma unroll
;       for (int k = 0; k < W; ++k) F0[k] = (u32x4){zz_, zz_, zz_, zz_}; }
;     for (int e = E1; e < E2; e += 8) CONV_BLOCK(true, true);
;     for (int e = E2; e < E3; e += 8) CONV_BLOCK(true, false);
;     ...
;     __syncthreads();
;     int lane2; { unsigned ones_ = ~0u; asm volatile("" : "+s"(ones_)); lane2 = (int)__builtin_amdgcn_mbcnt_hi(ones_, __builtin_amdgcn_mbcnt_lo(ones_, 0u)); }
;     const int nn2 = lane2 & 15, kq2 = lane2 >> 4;
;     float nsum = 0.f;
;     { const float* kq_ = (const float*)(ws + WS_KPART) + ((size_t)ib * 320 + (PROMPT ? 0 : 256)) * 2048; constexpr int ntile = PROMPT ? 256 : 64;
;       for (int q = lane2; q < ntile; q += 64) nsum += kq_[(size_t)q * 2048 + c] + kq_[(size_t)q * 2048 + 1024 + c];
	v_mfma_f32_16x16x32_bf16 v[60:63], v[74:77], v[118:121], v[60:63]
	v_mfma_f32_16x16x32_bf16 v[98:101], v[74:77], v[56:59], v[98:101]
	v_mfma_f32_16x16x32_bf16 v[78:81], v[74:77], v[90:93], v[78:81]
	s_waitcnt lgkmcnt(0)
	v_mfma_f32_16x16x32_bf16 v[138:141], v[74:77], v[86:89], v[14:17]
	ds_read_b128 v[74:77], v123 offset:448
	v_mfma_f32_16x16x32_bf16 v[64:67], v[102:105], v[56:59], v[64:67]
	v_mfma_f32_16x16x32_bf16 v[82:85], v[102:105], v[86:89], v[82:85]
	v_mfma_f32_16x16x32_bf16 v[134:137], v[102:105], v[90:93], v[94:97]
	v_mfma_f32_16x16x32_bf16 v[52:55], v[70:73], v[114:117], v[52:55]
	s_nop 0
	v_min_i32_e32 v14, 0x1ff8, v51
	v_ashrrev_i32_e32 v15, 31, v14
	v_lshl_add_u64 v[68:69], v[14:15], 1, s[22:23]
	global_load_dwordx4 v[14:17], v[68:69], off
	global_load_dword v128, v[68:69], off offset:-4
	s_waitcnt vmcnt(8)
	v_perm_b32 v68, v142, v130, s67
	v_perm_b32 v69, v130, v131, s67
	v_perm_b32 v70, v131, v132, s67
	v_perm_b32 v71, v132, v133, s67
	s_nop 0
	v_mfma_f32_16x16x32_bf16 v[52:55], v[102:105], v[118:121], v[52:55]
	v_mfma_f32_16x16x32_bf16 v[106:109], v[68:71], v[56:59], v[60:63]
	s_nop 2
	v_min_u32_e32 v60, 32, v50
	v_mad_u32_u24 v60, v60, s58, v0
	v_mfma_f32_16x16x32_bf16 v[110:113], v[130:133], v[90:93], v[64:67]
	v_mfma_f32_16x16x32_bf16 v[94:97], v[68:71], v[90:93], v[98:101]
	v_mfma_f32_16x16x32_bf16 v[78:81], v[68:71], v[86:89], v[78:81]
	s_waitcnt lgkmcnt(0)
	v_mfma_f32_16x16x32_bf16 v[70:73], v[68:71], v[74:77], v[138:141]
	ds_read_b128 v[66:69], v60
	v_mfma_f32_16x16x32_bf16 v[98:101], v[130:133], v[86:89], v[134:137]
	v_mfma_f32_16x16x32_bf16 v[82:85], v[130:133], v[74:77], v[82:85]
	v_mfma_f32_16x16x32_bf16 v[102:105], v[130:133], v[56:59], v[52:55]
	s_nop 0
	s_add_i32 s11, s11, 8
	v_add_u32_e32 v50, 1, v50
	s_cmpk_gt_u32 s11, 0xf8
	v_add_u32_e32 v51, 0x100, v51
	s_cbranch_scc0 .LBB0_755
	s_mov_b32 s11, -1
	s_waitcnt lgkmcnt(0)
	s_barrier
	s_nop 0
	v_mbcnt_lo_u32_b32 v0, s11, 0
	s_waitcnt vmcnt(3)
	v_mbcnt_hi_u32_b32 v12, s11, v0
	s_movk_i32 s11, 0x100
	v_cmp_gt_i32_e32 vcc, s11, v12
	v_mov_b32_e32 v0, 0
	s_and_saveexec_b64 s[22:23], vcc
	s_cbranch_execz .LBB0_760
	s_lshl_b64 s[18:19], s[18:19], 2
	s_add_u32 s18, s51, s18
	v_lshlrev_b32_e32 v0, 13, v12
	s_addc_u32 s19, s52, s19
	v_subrev_u32_e32 v4, 64, v12
	v_lshl_add_u64 v[2:3], s[18:19], 0, v[0:1]
	v_mov_b32_e32 v0, 0
	s_mov_b64 s[18:19], 0

; #define CONV_LOADA(e_, k_) do { const int xh_ = min(32 * (e_) + xa, L - 8); rh[k_] = *(const u32x4a4*)(Rc + xh_); asm volatile("" ::: "memory"); rl[k_] = *(const unsigned*)(Rc + xh_ - 2); } while (0)
; #define CONV_BLOCK(DO0, DO1) do { CONV_STEP(0, DO0, DO1); CONV_STEP(1, DO0, DO1); CONV_STEP(2, DO0, DO1); CONV_STEP(3, DO0, DO1); CONV_STEP(4, DO0, DO1); CONV_STEP(5, DO0, DO1); CONV_STEP(6, DO0, DO1); CONV_STEP(7, DO0, DO1); } while (0)
; template <bool PROMPT, int HALF>
; __device__ __forceinline__ void conv_item(unsigned char* ws, KArgs ka, int ib, int oct, int g, LAS unsigned char* lds, int tid, int lane, int wave) {
;     ...
; #pragma unroll
;     for (int k = 0; k < DA; ++k) CONV_LOADA(E0 + k, k);
;     { unsigned zz_ = 0u; asm volatile("" : "+v"(zz_));
; #pragma unroll
;       for (int k = 0; k < W; ++k) F1[k] = (u32x4){zz_, zz_, zz_, zz_}; }
;     for (int e = E0; e < E1; e += 8) CONV_BLOCK(false, true);
.LBB0_769:
	v_min_i32_e32 v68, 0x1ff8, v66
	v_ashrrev_i32_e32 v69, 31, v68
	v_lshl_add_u64 v[72:73], v[68:69], 1, s[18:19]
	global_load_dwordx4 v[68:71], v[72:73], off
	global_load_dword v67, v[72:73], off offset:-4
	s_add_i32 s22, s11, 12
	s_waitcnt vmcnt(8)
	v_perm_b32 v72, v125, v2, s67
	v_perm_b32 v73, v2, v3, s67
	v_perm_b32 v74, v3, v4, s67
	v_perm_b32 v75, v4, v5, s67
	s_nop 0
	s_ashr_i32 s22, s22, 3
	v_add_u32_e32 v76, s22, v124
	v_min_u32_e32 v76, 32, v76
	v_mad_u32_u24 v76, v76, s58, v0
	v_mfma_f32_16x16x32_bf16 v[42:45], v[72:75], v[62:65], v[42:45]
	ds_read_b128 v[76:79], v76 offset:320
	v_mfma_f32_16x16x32_bf16 v[38:41], v[2:5], v[58:61], v[38:41]
	v_mfma_f32_16x16x32_bf16 v[34:37], v[72:75], v[58:61], v[34:37]
	v_mfma_f32_16x16x32_bf16 v[30:33], v[2:5], v[54:57], v[30:33]
	v_mfma_f32_16x16x32_bf16 v[26:29], v[72:75], v[54:57], v[26:29]
	s_waitcnt lgkmcnt(1)
	v_mfma_f32_16x16x32_bf16 v[22:25], v[2:5], v[50:53], v[22:25]
	v_mfma_f32_16x16x32_bf16 v[18:21], v[72:75], v[50:53], v[18:21]
	s_nop 0
	v_add_u32_e32 v72, 32, v66
	v_min_i32_e32 v72, 0x1ff8, v72
	v_ashrrev_i32_e32 v73, 31, v72
	v_lshl_add_u64 v[80:81], v[72:73], 1, s[18:19]
	global_load_dwordx4 v[72:75], v[80:81], off
	global_load_dword v96, v[80:81], off offset:-4
	s_add_i32 s22, s11, 13
	s_waitcnt vmcnt(8)
	v_perm_b32 v80, v126, v6, s67
	v_perm_b32 v81, v6, v7, s67
	v_perm_b32 v82, v7, v8, s67
	v_perm_b32 v83, v8, v9, s67
	s_nop 0
	s_ashr_i32 s22, s22, 3
	v_add_u32_e32 v84, s22, v124
	v_mfma_f32_16x16x32_bf16 v[42:45], v[80:83], v[58:61], v[42:45]
	v_mfma_f32_16x16x32_bf16 v[34:37], v[80:83], v[54:57], v[34:37]
	v_mfma_f32_16x16x32_bf16 v[26:29], v[80:83], v[50:53], v[26:29]
	s_waitcnt lgkmcnt(0)
	v_mfma_f32_16x16x32_bf16 v[18:21], v[80:83], v[76:79], v[18:21]
	v_min_u32_e32 v80, 32, v84
	v_mad_u32_u24 v80, v80, s58, v0
	ds_read_b128 v[80:83], v80 offset:384
	v_mfma_f32_16x16x32_bf16 v[38:41], v[6:9], v[54:57], v[38:41]
	v_mfma_f32_16x16x32_bf16 v[30:33], v[6:9], v[50:53], v[30:33]
	v_mfma_f32_16x16x32_bf16 v[22:25], v[6:9], v[76:79], v[22:25]
	v_mfma_f32_16x16x32_bf16 v[2:5], v[2:5], v[62:65], v[46:49]
	s_nop 0
	s_nop 1
	v_add_u32_e32 v46, 64, v66
	v_min_i32_e32 v46, 0x1ff8, v46
	v_ashrrev_i32_e32 v47, 31, v46
	v_lshl_add_u64 v[62:63], v[46:47], 1, s[18:19]
	global_load_dwordx4 v[46:49], v[62:63], off
	global_load_dword v97, v[62:63], off offset:-4
	s_waitcnt vmcnt(8)
	v_perm_b32 v62, v127, v10, s67
	v_perm_b32 v63, v10, v11, s67
	v_perm_b32 v64, v11, v12, s67
	v_perm_b32 v65, v12, v13, s67
	s_add_i32 s22, s11, 14
	s_nop 0
	s_ashr_i32 s22, s22, 3
	v_add_u32_e32 v84, s22, v124
	v_mfma_f32_16x16x32_bf16 v[42:45], v[62:65], v[54:57], v[42:45]
	v_mfma_f32_16x16x32_bf16 v[34:37], v[62:65], v[50:53], v[34:37]
	v_mfma_f32_16x16x32_bf16 v[26:29], v[62:65], v[76:79], v[26:29]
	s_waitcnt lgkmcnt(0)
	v_mfma_f32_16x16x32_bf16 v[18:21], v[62:65], v[80:83], v[18:21]
	v_min_u32_e32 v62, 32, v84
	v_mad_u32_u24 v62, v62, s58, v0
	ds_read_b128 v[84:87], v62 offset:448
	v_mfma_f32_16x16x32_bf16 v[38:41], v[10:13], v[50:53], v[38:41]
	v_mfma_f32_16x16x32_bf16 v[30:33], v[10:13], v[76:79], v[30:33]
	v_mfma_f32_16x16x32_bf16 v[22:25], v[10:13], v[80:83], v[22:25]
	v_mfma_f32_16x16x32_bf16 v[2:5], v[6:9], v[58:61], v[2:5]
	s_nop 0
	v_add_u32_e32 v6, 0x60, v66
	v_min_i32_e32 v6, 0x1ff8, v6
	v_ashrrev_i32_e32 v7, 31, v6
	v_lshl_add_u64 v[6:7], v[6:7], 1, s[18:19]
	global_load_dwordx4 v[88:91], v[6:7], off
	global_load_dword v98, v[6:7], off offset:-4
	s_waitcnt vmcnt(8)
	v_perm_b32 v6, v128, v14, s67
	v_perm_b32 v7, v14, v15, s67
	v_perm_b32 v8, v15, v16, s67
	v_perm_b32 v9, v16, v17, s67
	s_add_i32 s22, s11, 15
	s_nop 0
	s_ashr_i32 s22, s22, 3
	v_add_u32_e32 v58, s22, v124
	v_mfma_f32_16x16x32_bf16 v[42:45], v[6:9], v[50:53], v[42:45]
	v_mfma_f32_16x16x32_bf16 v[34:37], v[6:9], v[76:79], v[34:37]
	v_mfma_f32_16x16x32_bf16 v[26:29], v[6:9], v[80:83], v[26:29]
	s_waitcnt lgkmcnt(0)
	v_mfma_f32_16x16x32_bf16 v[6:9], v[6:9], v[84:87], v[18:21]
	s_nop 2
	v_min_u32_e32 v18, 32, v58
	v_mad_u32_u24 v18, v18, s58, v0
	v_mfma_f32_16x16x32_bf16 v[38:41], v[14:17], v[76:79], v[38:41]
	ds_read_b128 v[92:95], v18
	v_mfma_f32_16x16x32_bf16 v[30:33], v[14:17], v[80:83], v[30:33]
	v_mfma_f32_16x16x32_bf16 v[22:25], v[14:17], v[84:87], v[22:25]
	v_mfma_f32_16x16x32_bf16 v[10:13], v[10:13], v[54:57], v[2:5]
	s_nop 0
	s_nop 1
	v_add_u32_e32 v2, 0x80, v66
	v_min_i32_e32 v2, 0x1ff8, v2
	v_ashrrev_i32_e32 v3, 31, v2
	v_lshl_add_u64 v[18:19], v[2:3], 1, s[18:19]
	global_load_dwordx4 v[2:5], v[18:19], off
	global_load_dword v125, v[18:19], off offset:-4
	s_waitcnt vmcnt(8)
	v_perm_b32 v18, v67, v68, s67
	v_perm_b32 v19, v68, v69, s67
	v_perm_b32 v20, v69, v70, s67
	v_perm_b32 v21, v70, v71, s67
	s_add_i32 s22, s11, 16
	s_nop 0
	s_ashr_i32 s22, s22, 3
	v_add_u32_e32 v54, s22, v124
	v_mfma_f32_16x16x32_bf16 v[42:45], v[18:21], v[76:79], v[42:45]
	v_mfma_f32_16x16x32_bf16 v[34:37], v[18:21], v[80:83], v[34:37]
	v_mfma_f32_16x16x32_bf16 v[26:29], v[18:21], v[84:87], v[26:29]
	s_waitcnt lgkmcnt(0)
	v_mfma_f32_16x16x32_bf16 v[18:21], v[18:21], v[92:95], v[6:9]
	s_nop 2
	v_min_u32_e32 v6, 32, v54
	v_mad_u32_u24 v6, v6, s58, v0
	ds_read_b128 v[62:65], v6 offset:64
	v_mfma_f32_16x16x32_bf16 v[38:41], v[68:71], v[80:83], v[38:41]
	v_mfma_f32_16x16x32_bf16 v[30:33], v[68:71], v[84:87], v[30:33]
	v_mfma_f32_16x16x32_bf16 v[22:25], v[68:71], v[92:95], v[22:25]
	v_mfma_f32_16x16x32_bf16 v[10:13], v[14:17], v[50:53], v[10:13]
	s_nop 0
	v_add_u32_e32 v6, 0xa0, v66
	v_min_i32_e32 v6, 0x1ff8, v6
	v_ashrrev_i32_e32 v7, 31, v6
	v_lshl_add_u64 v[14:15], v[6:7], 1, s[18:19]
	global_load_dwordx4 v[6:9], v[14:15], off
	global_load_dword v126, v[14:15], off offset:-4
	s_waitcnt vmcnt(8)
; #define CONV_LOADA(e_, k_) do { const int xh_ = min(32 * (e_) + xa, L - 8); rh[k_] = *(const u32x4a4*)(Rc + xh_); asm volatile("" ::: "memory"); rl[k_] = *(const unsigned*)(Rc + xh_ - 2); } while (0)
; #define CONV_BLOCK(DO0, DO1) do { CONV_STEP(0, DO0, DO1); CONV_STEP(1, DO0, DO1); CONV_STEP(2, DO0, DO1); CONV_STEP(3, DO0, DO1); CONV_STEP(4, DO0, DO1); CONV_STEP(5, DO0, DO1); CONV_STEP(6, DO0, DO1); CONV_STEP(7, DO0, DO1); } while (0)
; template <bool PROMPT, int HALF>
; __device__ __forceinline__ void conv_item(unsigned char* ws, KArgs ka, int ib, int oct, int g, LAS unsigned char* lds, int tid, int lane, int wave) {
;     ...
; #pragma unroll
;     for (int k = 0; k < DA; ++k) CONV_LOADA(E0 + k, k);
;     { unsigned zz_ = 0u; asm volatile("" : "+v"(zz_));
; #pragma unroll
;       for (int k = 0; k < W; ++k) F1[k] = (u32x4){zz_, zz_, zz_, zz_}; }
;     for (int e = E0; e < E1; e += 8) CONV_BLOCK(false, true);
;     { unsigned zz_ = 0u; asm volatile("" : "+v"(zz_));
; #pragma unroll
;       for (int k = 0; k < W; ++k) F0[k] = (u32x4){zz_, zz_, zz_, zz_}; }
;     for (int e = E1; e < E2; e += 8) CONV_BLOCK(true, true);
	v_perm_b32 v14, v96, v72, s67
	v_perm_b32 v15, v72, v73, s67
	v_perm_b32 v16, v73, v74, s67
	v_perm_b32 v17, v74, v75, s67
	s_add_i32 s22, s11, 17
	s_nop 0
	s_ashr_i32 s22, s22, 3
	v_add_u32_e32 v50, s22, v124
	v_mfma_f32_16x16x32_bf16 v[42:45], v[14:17], v[80:83], v[42:45]
	v_mfma_f32_16x16x32_bf16 v[34:37], v[14:17], v[84:87], v[34:37]
	v_mfma_f32_16x16x32_bf16 v[26:29], v[14:17], v[92:95], v[26:29]
	s_waitcnt lgkmcnt(0)
	v_mfma_f32_16x16x32_bf16 v[14:17], v[14:17], v[62:65], v[18:21]
	s_nop 2
	v_min_u32_e32 v18, 32, v50
	v_mad_u32_u24 v18, v18, s58, v0
	ds_read_b128 v[58:61], v18 offset:128
	v_mfma_f32_16x16x32_bf16 v[38:41], v[72:75], v[84:87], v[38:41]
	v_mfma_f32_16x16x32_bf16 v[30:33], v[72:75], v[92:95], v[30:33]
	v_mfma_f32_16x16x32_bf16 v[22:25], v[72:75], v[62:65], v[22:25]
	v_mfma_f32_16x16x32_bf16 v[18:21], v[68:71], v[76:79], v[10:13]
	s_nop 0
	s_nop 1
	v_add_u32_e32 v10, 0xc0, v66
	v_min_i32_e32 v10, 0x1ff8, v10
	v_ashrrev_i32_e32 v11, 31, v10
	v_lshl_add_u64 v[50:51], v[10:11], 1, s[18:19]
	global_load_dwordx4 v[10:13], v[50:51], off
	global_load_dword v127, v[50:51], off offset:-4
	s_waitcnt vmcnt(8)
	v_perm_b32 v50, v97, v46, s67
	v_perm_b32 v51, v46, v47, s67
	v_perm_b32 v52, v47, v48, s67
	v_perm_b32 v53, v48, v49, s67
	s_add_i32 s22, s11, 18
	s_nop 0
	s_ashr_i32 s22, s22, 3
	v_add_u32_e32 v54, s22, v124
	v_mfma_f32_16x16x32_bf16 v[42:45], v[50:53], v[84:87], v[42:45]
	v_mfma_f32_16x16x32_bf16 v[34:37], v[50:53], v[92:95], v[34:37]
	v_mfma_f32_16x16x32_bf16 v[26:29], v[50:53], v[62:65], v[26:29]
	s_waitcnt lgkmcnt(0)
	v_mfma_f32_16x16x32_bf16 v[50:53], v[50:53], v[58:61], v[14:17]
	s_nop 2
	v_min_u32_e32 v14, 32, v54
	v_mad_u32_u24 v14, v14, s58, v0
	ds_read_b128 v[54:57], v14 offset:192
	v_mfma_f32_16x16x32_bf16 v[38:41], v[46:49], v[92:95], v[38:41]
	v_mfma_f32_16x16x32_bf16 v[30:33], v[46:49], v[62:65], v[30:33]
	v_mfma_f32_16x16x32_bf16 v[22:25], v[46:49], v[58:61], v[22:25]
	v_mfma_f32_16x16x32_bf16 v[68:71], v[72:75], v[80:83], v[18:21]
	s_nop 0
	v_add_u32_e32 v14, 0xe0, v66
	v_min_i32_e32 v14, 0x1ff8, v14
	v_ashrrev_i32_e32 v15, 31, v14
	v_lshl_add_u64 v[18:19], v[14:15], 1, s[18:19]
	global_load_dwordx4 v[14:17], v[18:19], off
	global_load_dword v128, v[18:19], off offset:-4
	s_waitcnt vmcnt(8)
	v_perm_b32 v18, v98, v88, s67
	v_perm_b32 v19, v88, v89, s67
	v_perm_b32 v20, v89, v90, s67
	v_perm_b32 v21, v90, v91, s67
	s_add_i32 s22, s11, 19
	s_nop 0
	s_ashr_i32 s22, s22, 3
	v_mfma_f32_16x16x32_bf16 v[42:45], v[18:21], v[92:95], v[42:45]
	v_mfma_f32_16x16x32_bf16 v[34:37], v[18:21], v[62:65], v[34:37]
	v_mfma_f32_16x16x32_bf16 v[26:29], v[18:21], v[58:61], v[26:29]
	s_waitcnt lgkmcnt(0)
	v_mfma_f32_16x16x32_bf16 v[18:21], v[18:21], v[54:57], v[50:53]
	s_nop 2
	v_add_u32_e32 v50, s22, v124
	v_mfma_f32_16x16x32_bf16 v[46:49], v[46:49], v[84:87], v[68:71]
	v_min_u32_e32 v50, 32, v50
	v_mad_u32_u24 v50, v50, s58, v0
	ds_read_b128 v[50:53], v50 offset:256
	v_mfma_f32_16x16x32_bf16 v[38:41], v[88:91], v[62:65], v[38:41]
	v_mfma_f32_16x16x32_bf16 v[30:33], v[88:91], v[58:61], v[30:33]
	v_mfma_f32_16x16x32_bf16 v[22:25], v[88:91], v[54:57], v[22:25]
	v_mfma_f32_16x16x32_bf16 v[46:49], v[88:91], v[92:95], v[46:49]
	s_nop 0
	s_add_i32 s11, s11, 8
	s_cmp_gt_u32 s11, 0xffffff70
	v_add_u32_e32 v66, 0x100, v66
	s_cbranch_scc0 .LBB0_769
	v_mov_b32_e32 v66, v1
	v_mov_b32_e32 v70, 0
	v_add_u32_e32 v129, 0xffffefa0, v123
	s_movk_i32 s11, 0xff71
	s_movk_i32 s22, 0xde40
	v_mov_b32_e32 v71, v70
	v_mov_b32_e32 v72, v70
	v_mov_b32_e32 v73, v70
	v_mov_b32_e32 v86, v70
	v_mov_b32_e32 v87, v70
	v_mov_b32_e32 v88, v70
	v_mov_b32_e32 v89, v70
	v_mov_b32_e32 v94, v70
	v_mov_b32_e32 v95, v70
	v_mov_b32_e32 v96, v70
	v_mov_b32_e32 v97, v70
	v_mov_b32_e32 v110, v70
	v_mov_b32_e32 v111, v70
	v_mov_b32_e32 v112, v70
	v_mov_b32_e32 v113, v70
	v_mov_b32_e32 v78, v70
	v_mov_b32_e32 v79, v70
	v_mov_b32_e32 v80, v70
	v_mov_b32_e32 v81, v70
	v_mov_b32_e32 v98, v70
	v_mov_b32_e32 v99, v70
	v_mov_b32_e32 v100, v70
	v_mov_b32_e32 v101, v70
	v_mov_b32_e32 v106, v70
	v_mov_b32_e32 v107, v70
	v_mov_b32_e32 v108, v70
	v_mov_b32_e32 v109, v70
	v_mov_b32_e32 v102, v70
	v_mov_b32_e32 v103, v70
	v_mov_b32_e32 v104, v70
	v_mov_b32_e32 v105, v70
	v_mov_b32_e32 v67, v66
	v_mov_b32_e32 v68, v66
	v_mov_b32_e32 v69, v66
	v_mov_b32_e32 v74, v66
	v_mov_b32_e32 v75, v66
	v_mov_b32_e32 v76, v66
	v_mov_b32_e32 v77, v66
	v_mov_b32_e32 v82, v66
	v_mov_b32_e32 v83, v66
	v_mov_b32_e32 v84, v66
	v_mov_b32_e32 v85, v66
	v_mov_b32_e32 v90, v66
	v_mov_b32_e32 v91, v66
	v_mov_b32_e32 v92, v66
	v_mov_b32_e32 v93, v66
.LBB0_771:
	v_min_i32_e32 v114, 0x1ff8, v129
	v_ashrrev_i32_e32 v115, 31, v114
	v_lshl_add_u64 v[118:119], v[114:115], 1, s[18:19]
	global_load_dwordx4 v[114:117], v[118:119], off
	global_load_dword v138, v[118:119], off offset:-4
	s_add_i32 s23, s11, 12
	s_waitcnt vmcnt(8)
	v_perm_b32 v118, v125, v2, s67
	v_perm_b32 v119, v2, v3, s67
	v_perm_b32 v120, v3, v4, s67
	v_perm_b32 v121, v4, v5, s67
	s_nop 0
	s_ashr_i32 s23, s23, 3
	v_mfma_f32_16x16x32_bf16 v[46:49], v[2:5], v[62:65], v[46:49]
	s_add_i32 s30, s22, 0x100
	s_and_b32 s30, s30, 0x1c0
	v_mfma_f32_16x16x32_bf16 v[42:45], v[118:121], v[62:65], v[42:45]
	v_mfma_f32_16x16x32_bf16 v[62:65], v[2:5], v[82:85], v[106:109]
	s_nop 2
	v_add_u32_e32 v106, s23, v122
	v_min_u32_e32 v106, 32, v106
	v_add_u32_e32 v107, s23, v124
	v_mul_u32_u24_e32 v106, 0x210, v106
	v_min_u32_e32 v107, 32, v107
	v_add3_u32 v106, v0, v106, s30
	v_mul_u32_u24_e32 v107, 0x210, v107
	v_mfma_f32_16x16x32_bf16 v[102:105], v[2:5], v[90:93], v[102:105]
	v_mfma_f32_16x16x32_bf16 v[90:93], v[118:121], v[90:93], v[110:113]
	v_mfma_f32_16x16x32_bf16 v[38:41], v[2:5], v[58:61], v[38:41]
	v_mfma_f32_16x16x32_bf16 v[98:101], v[2:5], v[74:77], v[98:101]
	v_mfma_f32_16x16x32_bf16 v[30:33], v[2:5], v[54:57], v[30:33]
	s_waitcnt lgkmcnt(1)
	v_mfma_f32_16x16x32_bf16 v[78:81], v[2:5], v[66:69], v[78:81]
	s_waitcnt lgkmcnt(0)
	v_mfma_f32_16x16x32_bf16 v[2:5], v[2:5], v[50:53], v[22:25]
	s_nop 2
	v_add3_u32 v22, v0, v107, s30
	ds_read_b128 v[106:109], v106
	ds_read_b128 v[110:113], v22
	v_mfma_f32_16x16x32_bf16 v[94:97], v[118:121], v[82:85], v[94:97]
	v_mfma_f32_16x16x32_bf16 v[34:37], v[118:121], v[58:61], v[34:37]
	v_mfma_f32_16x16x32_bf16 v[86:89], v[118:121], v[74:77], v[86:89]
	v_mfma_f32_16x16x32_bf16 v[26:29], v[118:121], v[54:57], v[26:29]
	v_mfma_f32_16x16x32_bf16 v[70:73], v[118:121], v[66:69], v[70:73]
	v_mfma_f32_16x16x32_bf16 v[22:25], v[118:121], v[50:53], v[18:21]
	s_nop 0
	s_nop 1
	v_add_u32_e32 v18, 32, v129
	v_min_i32_e32 v18, 0x1ff8, v18
	v_ashrrev_i32_e32 v19, 31, v18
	v_lshl_add_u64 v[118:119], v[18:19], 1, s[18:19]
	global_load_dwordx4 v[18:21], v[118:119], off
	global_load_dword v139, v[118:119], off offset:-4
	s_add_i32 s23, s11, 13
	s_waitcnt vmcnt(8)
	v_perm_b32 v118, v126, v6, s67
	v_perm_b32 v119, v6, v7, s67
	v_perm_b32 v120, v7, v8, s67
	v_perm_b32 v121, v8, v9, s67
	s_nop 0
	s_ashr_i32 s23, s23, 3
	v_mfma_f32_16x16x32_bf16 v[46:49], v[6:9], v[58:61], v[46:49]
	s_add_i32 s30, s22, 0x140
	s_and_b32 s30, s30, 0x1c0
	v_mfma_f32_16x16x32_bf16 v[42:45], v[118:121], v[58:61], v[42:45]
	v_mfma_f32_16x16x32_bf16 v[58:61], v[6:9], v[74:77], v[62:65]
	v_mfma_f32_16x16x32_bf16 v[62:65], v[118:121], v[74:77], v[94:97]
	s_nop 2
	v_add_u32_e32 v94, s23, v122
	v_min_u32_e32 v94, 32, v94
	v_add_u32_e32 v95, s23, v124
	v_mul_u32_u24_e32 v94, 0x210, v94
	v_min_u32_e32 v95, 32, v95
	v_add3_u32 v94, v0, v94, s30
	v_mul_u32_u24_e32 v95, 0x210, v95
	v_mfma_f32_16x16x32_bf16 v[102:105], v[6:9], v[82:85], v[102:105]
	v_mfma_f32_16x16x32_bf16 v[82:85], v[118:121], v[82:85], v[90:93]
	v_mfma_f32_16x16x32_bf16 v[38:41], v[6:9], v[54:57], v[38:41]
	v_mfma_f32_16x16x32_bf16 v[90:93], v[6:9], v[66:69], v[98:101]
	v_mfma_f32_16x16x32_bf16 v[30:33], v[6:9], v[50:53], v[30:33]
	s_waitcnt lgkmcnt(1)
	v_mfma_f32_16x16x32_bf16 v[78:81], v[6:9], v[106:109], v[78:81]
	s_waitcnt lgkmcnt(0)
	v_mfma_f32_16x16x32_bf16 v[2:5], v[6:9], v[110:113], v[2:5]
	v_add3_u32 v6, v0, v95, s30
	ds_read_b128 v[94:97], v94
	ds_read_b128 v[98:101], v6
	v_mfma_f32_16x16x32_bf16 v[34:37], v[118:121], v[54:57], v[34:37]
	v_mfma_f32_16x16x32_bf16 v[86:89], v[118:121], v[66:69], v[86:89]
	v_mfma_f32_16x16x32_bf16 v[26:29], v[118:121], v[50:53], v[26:29]
	v_mfma_f32_16x16x32_bf16 v[70:73], v[118:121], v[106:109], v[70:73]
	v_mfma_f32_16x16x32_bf16 v[6:9], v[118:121], v[110:113], v[22:25]
	s_nop 0
	s_nop 1
	v_add_u32_e32 v22, 64, v129
	v_min_i32_e32 v22, 0x1ff8, v22
	v_ashrrev_i32_e32 v23, 31, v22
	v_lshl_add_u64 v[118:119], v[22:23], 1, s[18:19]
	global_load_dwordx4 v[22:25], v[118:119], off
	global_load_dword v140, v[118:119], off offset:-4
	s_add_i32 s23, s11, 14
	s_waitcnt vmcnt(8)
	v_perm_b32 v118, v127, v10, s67
	v_perm_b32 v119, v10, v11, s67
	v_perm_b32 v120, v11, v12, s67
	v_perm_b32 v121, v12, v13, s67
	s_nop 0
	s_ashr_i32 s23, s23, 3
	v_mfma_f32_16x16x32_bf16 v[102:105], v[10:13], v[74:77], v[102:105]
	s_add_i32 s30, s22, 0x180
	s_and_b32 s30, s30, 0x1c0
	v_mfma_f32_16x16x32_bf16 v[74:77], v[118:121], v[74:77], v[82:85]
	v_mfma_f32_16x16x32_bf16 v[82:85], v[118:121], v[106:109], v[86:89]
	s_nop 2
	v_add_u32_e32 v86, s23, v122
	v_min_u32_e32 v86, 32, v86
	v_add_u32_e32 v87, s23, v124
	v_mul_u32_u24_e32 v86, 0x210, v86
	v_min_u32_e32 v87, 32, v87
	v_add3_u32 v86, v0, v86, s30
	v_mul_u32_u24_e32 v87, 0x210, v87
	v_mfma_f32_16x16x32_bf16 v[46:49], v[10:13], v[54:57], v[46:49]
	v_mfma_f32_16x16x32_bf16 v[42:45], v[118:121], v[54:57], v[42:45]
	v_mfma_f32_16x16x32_bf16 v[54:57], v[10:13], v[66:69], v[58:61]
	v_mfma_f32_16x16x32_bf16 v[58:61], v[118:121], v[66:69], v[62:65]
	v_mfma_f32_16x16x32_bf16 v[38:41], v[10:13], v[50:53], v[38:41]
	v_mfma_f32_16x16x32_bf16 v[62:65], v[10:13], v[106:109], v[90:93]
	v_mfma_f32_16x16x32_bf16 v[30:33], v[10:13], v[110:113], v[30:33]
	s_waitcnt lgkmcnt(1)
	v_mfma_f32_16x16x32_bf16 v[78:81], v[10:13], v[94:97], v[78:81]
	s_waitcnt lgkmcnt(0)
	v_mfma_f32_16x16x32_bf16 v[2:5], v[10:13], v[98:101], v[2:5]
	v_add3_u32 v10, v0, v87, s30
	ds_read_b128 v[86:89], v86
	ds_read_b128 v[130:133], v10
	v_mfma_f32_16x16x32_bf16 v[34:37], v[118:121], v[50:53], v[34:37]
	v_mfma_f32_16x16x32_bf16 v[26:29], v[118:121], v[110:113], v[26:29]
	v_mfma_f32_16x16x32_bf16 v[70:73], v[118:121], v[94:97], v[70:73]
	v_mfma_f32_16x16x32_bf16 v[6:9], v[118:121], v[98:101], v[6:9]
	s_nop 0
	v_add_u32_e32 v10, 0x60, v129
	v_min_i32_e32 v10, 0x1ff8, v10
	v_ashrrev_i32_e32 v11, 31, v10
	v_lshl_add_u64 v[10:11], v[10:11], 1, s[18:19]
	global_load_dwordx4 v[118:121], v[10:11], off
	global_load_dword v142, v[10:11], off offset:-4
	s_waitcnt vmcnt(8)
	v_perm_b32 v10, v128, v14, s67
	v_perm_b32 v11, v14, v15, s67
	v_perm_b32 v12, v15, v16, s67
	v_perm_b32 v13, v16, v17, s67
	s_add_i32 s23, s11, 15
	s_nop 0
	s_ashr_i32 s23, s23, 3
	v_mfma_f32_16x16x32_bf16 v[90:93], v[14:17], v[66:69], v[102:105]
	s_add_i32 s30, s22, 0x1c0
	s_and_b32 s30, s30, 0x1c0
	v_mfma_f32_16x16x32_bf16 v[66:69], v[10:13], v[66:69], v[74:77]
	s_nop 2
	v_add_u32_e32 v74, s23, v122
	v_min_u32_e32 v74, 32, v74
	v_mfma_f32_16x16x32_bf16 v[46:49], v[14:17], v[50:53], v[46:49]
	v_mfma_f32_16x16x32_bf16 v[42:45], v[10:13], v[50:53], v[42:45]
	v_mfma_f32_16x16x32_bf16 v[50:53], v[14:17], v[106:109], v[54:57]
	v_mfma_f32_16x16x32_bf16 v[54:57], v[10:13], v[106:109], v[58:61]
	v_mfma_f32_16x16x32_bf16 v[58:61], v[14:17], v[94:97], v[62:65]
	v_mfma_f32_16x16x32_bf16 v[62:65], v[10:13], v[94:97], v[82:85]
	s_nop 2
	v_mul_u32_u24_e32 v82, 0x210, v74
	s_waitcnt lgkmcnt(1)
	v_mfma_f32_16x16x32_bf16 v[74:77], v[14:17], v[86:89], v[78:81]
	s_nop 2
	v_add_u32_e32 v79, s23, v124
	v_min_u32_e32 v79, 32, v79
	v_add3_u32 v78, v0, v82, s30
	v_mul_u32_u24_e32 v79, 0x210, v79
	v_mfma_f32_16x16x32_bf16 v[38:41], v[14:17], v[110:113], v[38:41]
	v_mfma_f32_16x16x32_bf16 v[30:33], v[14:17], v[98:101], v[30:33]
	s_waitcnt lgkmcnt(0)
	v_mfma_f32_16x16x32_bf16 v[14:17], v[14:17], v[130:133], v[2:5]
	s_nop 2
	v_add3_u32 v2, v0, v79, s30
	ds_read_b128 v[78:81], v78
	ds_read_b128 v[134:137], v2
	v_mfma_f32_16x16x32_bf16 v[34:37], v[10:13], v[110:113], v[34:37]
	v_mfma_f32_16x16x32_bf16 v[26:29], v[10:13], v[98:101], v[26:29]
	v_mfma_f32_16x16x32_bf16 v[70:73], v[10:13], v[86:89], v[70:73]
	v_mfma_f32_16x16x32_bf16 v[6:9], v[10:13], v[130:133], v[6:9]
	s_nop 0
	v_add_u32_e32 v2, 0x80, v129
	v_min_i32_e32 v2, 0x1ff8, v2
	v_ashrrev_i32_e32 v3, 31, v2
	v_lshl_add_u64 v[10:11], v[2:3], 1, s[18:19]
	global_load_dwordx4 v[2:5], v[10:11], off
	global_load_dword v125, v[10:11], off offset:-4
	s_waitcnt vmcnt(8)
	v_perm_b32 v10, v138, v114, s67
	v_perm_b32 v11, v114, v115, s67
	v_perm_b32 v12, v115, v116, s67
	v_perm_b32 v13, v116, v117, s67
	s_add_i32 s23, s11, 16
	s_nop 0
	s_ashr_i32 s23, s23, 3
	v_mfma_f32_16x16x32_bf16 v[102:105], v[10:13], v[86:89], v[62:65]
	s_and_b32 s30, s22, 0x1c0
	s_nop 1
	v_add_u32_e32 v62, s23, v122
	v_add_u32_e32 v63, s23, v124
	v_min_u32_e32 v62, 32, v62
	v_min_u32_e32 v63, 32, v63
	v_mul_u32_u24_e32 v62, 0x210, v62
	v_mul_u32_u24_e32 v63, 0x210, v63
	v_add3_u32 v62, v0, v62, s30
	v_add3_u32 v63, v0, v63, s30
	v_mfma_f32_16x16x32_bf16 v[82:85], v[114:117], v[106:109], v[90:93]
	s_nop 2
	ds_read_b128 v[90:93], v62
	ds_read_b128 v[62:65], v63
	v_mfma_f32_16x16x32_bf16 v[66:69], v[10:13], v[106:109], v[66:69]
	v_mfma_f32_16x16x32_bf16 v[46:49], v[114:117], v[110:113], v[46:49]
	v_mfma_f32_16x16x32_bf16 v[42:45], v[10:13], v[110:113], v[42:45]
	v_mfma_f32_16x16x32_bf16 v[50:53], v[114:117], v[94:97], v[50:53]
	v_mfma_f32_16x16x32_bf16 v[54:57], v[10:13], v[94:97], v[54:57]
	v_mfma_f32_16x16x32_bf16 v[38:41], v[114:117], v[98:101], v[38:41]
	v_mfma_f32_16x16x32_bf16 v[34:37], v[10:13], v[98:101], v[34:37]
	v_mfma_f32_16x16x32_bf16 v[58:61], v[114:117], v[86:89], v[58:61]
	v_mfma_f32_16x16x32_bf16 v[30:33], v[114:117], v[130:133], v[30:33]
	v_mfma_f32_16x16x32_bf16 v[26:29], v[10:13], v[130:133], v[26:29]
	s_waitcnt lgkmcnt(3)
	v_mfma_f32_16x16x32_bf16 v[74:77], v[114:117], v[78:81], v[74:77]
	v_mfma_f32_16x16x32_bf16 v[70:73], v[10:13], v[78:81], v[70:73]
	s_waitcnt lgkmcnt(2)
	v_mfma_f32_16x16x32_bf16 v[14:17], v[114:117], v[134:137], v[14:17]
	v_mfma_f32_16x16x32_bf16 v[10:13], v[10:13], v[134:137], v[6:9]
	s_nop 0
	s_nop 1
	v_add_u32_e32 v6, 0xa0, v129
	v_min_i32_e32 v6, 0x1ff8, v6
	v_ashrrev_i32_e32 v7, 31, v6
	v_lshl_add_u64 v[106:107], v[6:7], 1, s[18:19]
	global_load_dwordx4 v[6:9], v[106:107], off
	global_load_dword v126, v[106:107], off offset:-4
	s_waitcnt vmcnt(8)
	v_perm_b32 v106, v139, v18, s67
	v_perm_b32 v107, v18, v19, s67
	v_perm_b32 v108, v19, v20, s67
	v_perm_b32 v109, v20, v21, s67
	s_add_i32 s23, s11, 17
	s_nop 0
	s_ashr_i32 s23, s23, 3
	v_mfma_f32_16x16x32_bf16 v[110:113], v[18:21], v[94:97], v[82:85]
	s_add_i32 s30, s22, 0x240
	s_and_b32 s30, s30, 0x1c0
	v_mfma_f32_16x16x32_bf16 v[66:69], v[106:109], v[94:97], v[66:69]
	v_mfma_f32_16x16x32_bf16 v[94:97], v[18:21], v[78:81], v[58:61]
	s_nop 2
	v_add_u32_e32 v58, s23, v122
	v_min_u32_e32 v58, 32, v58
	v_add_u32_e32 v59, s23, v124
	v_mul_u32_u24_e32 v58, 0x210, v58
	v_min_u32_e32 v59, 32, v59
	v_add3_u32 v58, v0, v58, s30
	v_mul_u32_u24_e32 v59, 0x210, v59
	v_mfma_f32_16x16x32_bf16 v[46:49], v[18:21], v[98:101], v[46:49]
	v_mfma_f32_16x16x32_bf16 v[50:53], v[18:21], v[86:89], v[50:53]
	v_mfma_f32_16x16x32_bf16 v[38:41], v[18:21], v[130:133], v[38:41]
	v_mfma_f32_16x16x32_bf16 v[30:33], v[18:21], v[134:137], v[30:33]
	s_waitcnt lgkmcnt(1)
	v_mfma_f32_16x16x32_bf16 v[74:77], v[18:21], v[90:93], v[74:77]
	s_waitcnt lgkmcnt(0)
; #define CONV_LOADA(e_, k_) do { const int xh_ = min(32 * (e_) + xa, L - 8); rh[k_] = *(const u32x4a4*)(Rc + xh_); asm volatile("" ::: "memory"); rl[k_] = *(const unsigned*)(Rc + xh_ - 2); } while (0)
; #define CONV_BLOCK(DO0, DO1) do { CONV_STEP(0, DO0, DO1); CONV_STEP(1, DO0, DO1); CONV_STEP(2, DO0, DO1); CONV_STEP(3, DO0, DO1); CONV_STEP(4, DO0, DO1); CONV_STEP(5, DO0, DO1); CONV_STEP(6, DO0, DO1); CONV_STEP(7, DO0, DO1); } while (0)
; template <bool PROMPT, int HALF>
; __device__ __forceinline__ void conv_item(unsigned char* ws, KArgs ka, int ib, int oct, int g, LAS unsigned char* lds, int tid, int lane, int wave) {
;     ...
; #pragma unroll
;     for (int k = 0; k < DA; ++k) CONV_LOADA(E0 + k, k);
;     { unsigned zz_ = 0u; asm volatile("" : "+v"(zz_));
; #pragma unroll
;       for (int k = 0; k < W; ++k) F1[k] = (u32x4){zz_, zz_, zz_, zz_}; }
;     for (int e = E0; e < E1; e += 8) CONV_BLOCK(false, true);
;     { unsigned zz_ = 0u; asm volatile("" : "+v"(zz_));
; #pragma unroll
;       for (int k = 0; k < W; ++k) F0[k] = (u32x4){zz_, zz_, zz_, zz_}; }
;     for (int e = E1; e < E2; e += 8) CONV_BLOCK(true, true);
;     for (int e = E2; e < E3; e += 8) CONV_BLOCK(true, false);
	v_mfma_f32_16x16x32_bf16 v[14:17], v[18:21], v[62:65], v[14:17]
	v_add3_u32 v18, v0, v59, s30
	ds_read_b128 v[82:85], v58
	ds_read_b128 v[58:61], v18
	v_mfma_f32_16x16x32_bf16 v[42:45], v[106:109], v[98:101], v[42:45]
	v_mfma_f32_16x16x32_bf16 v[54:57], v[106:109], v[86:89], v[54:57]
	v_mfma_f32_16x16x32_bf16 v[34:37], v[106:109], v[130:133], v[34:37]
	v_mfma_f32_16x16x32_bf16 v[98:101], v[106:109], v[78:81], v[102:105]
	v_mfma_f32_16x16x32_bf16 v[26:29], v[106:109], v[134:137], v[26:29]
	v_mfma_f32_16x16x32_bf16 v[70:73], v[106:109], v[90:93], v[70:73]
	v_mfma_f32_16x16x32_bf16 v[18:21], v[106:109], v[62:65], v[10:13]
	s_nop 0
	s_nop 1
	v_add_u32_e32 v10, 0xc0, v129
	v_min_i32_e32 v10, 0x1ff8, v10
	v_ashrrev_i32_e32 v11, 31, v10
	v_lshl_add_u64 v[102:103], v[10:11], 1, s[18:19]
	global_load_dwordx4 v[10:13], v[102:103], off
	global_load_dword v127, v[102:103], off offset:-4
	s_waitcnt vmcnt(8)
	v_perm_b32 v102, v140, v22, s67
	v_perm_b32 v103, v22, v23, s67
	v_perm_b32 v104, v23, v24, s67
	v_perm_b32 v105, v24, v25, s67
	s_add_i32 s23, s11, 18
	s_nop 0
	s_ashr_i32 s23, s23, 3
	v_mfma_f32_16x16x32_bf16 v[106:109], v[22:25], v[86:89], v[110:113]
	s_add_i32 s30, s22, 0x280
	s_and_b32 s30, s30, 0x1c0
	v_mfma_f32_16x16x32_bf16 v[66:69], v[102:105], v[86:89], v[66:69]
	v_mfma_f32_16x16x32_bf16 v[86:89], v[102:105], v[78:81], v[54:57]
	s_nop 2
	v_add_u32_e32 v54, s23, v122
	v_min_u32_e32 v54, 32, v54
	v_add_u32_e32 v55, s23, v124
	v_mul_u32_u24_e32 v54, 0x210, v54
	v_min_u32_e32 v55, 32, v55
	v_add3_u32 v54, v0, v54, s30
	v_mul_u32_u24_e32 v55, 0x210, v55
	v_mfma_f32_16x16x32_bf16 v[46:49], v[22:25], v[130:133], v[46:49]
	v_mfma_f32_16x16x32_bf16 v[50:53], v[22:25], v[78:81], v[50:53]
	v_mfma_f32_16x16x32_bf16 v[38:41], v[22:25], v[134:137], v[38:41]
	v_mfma_f32_16x16x32_bf16 v[114:117], v[22:25], v[90:93], v[94:97]
	v_mfma_f32_16x16x32_bf16 v[30:33], v[22:25], v[62:65], v[30:33]
	s_waitcnt lgkmcnt(1)
	v_mfma_f32_16x16x32_bf16 v[138:141], v[22:25], v[82:85], v[74:77]
	s_waitcnt lgkmcnt(0)
	v_mfma_f32_16x16x32_bf16 v[22:25], v[22:25], v[58:61], v[14:17]
	s_nop 2
	v_add3_u32 v14, v0, v55, s30
	ds_read_b128 v[74:77], v54
	ds_read_b128 v[54:57], v14
	v_mfma_f32_16x16x32_bf16 v[42:45], v[102:105], v[130:133], v[42:45]
	v_mfma_f32_16x16x32_bf16 v[34:37], v[102:105], v[134:137], v[34:37]
	v_mfma_f32_16x16x32_bf16 v[26:29], v[102:105], v[62:65], v[26:29]
	v_mfma_f32_16x16x32_bf16 v[70:73], v[102:105], v[82:85], v[70:73]
	v_mfma_f32_16x16x32_bf16 v[18:21], v[102:105], v[58:61], v[18:21]
	v_mfma_f32_16x16x32_bf16 v[130:133], v[102:105], v[90:93], v[98:101]
	s_nop 0
	v_add_u32_e32 v14, 0xe0, v129
	v_min_i32_e32 v14, 0x1ff8, v14
	v_ashrrev_i32_e32 v15, 31, v14
	v_lshl_add_u64 v[94:95], v[14:15], 1, s[18:19]
	global_load_dwordx4 v[14:17], v[94:95], off
	global_load_dword v128, v[94:95], off offset:-4
	s_add_i32 s23, s11, 19
	s_waitcnt vmcnt(8)
	v_perm_b32 v142, v142, v118, s67
	v_perm_b32 v143, v118, v119, s67
	v_perm_b32 v144, v119, v120, s67
	v_perm_b32 v145, v120, v121, s67
	s_nop 0
	s_ashr_i32 s23, s23, 3
	v_mfma_f32_16x16x32_bf16 v[102:105], v[118:121], v[78:81], v[106:109]
	s_add_i32 s30, s22, 0x2c0
	s_and_b32 s30, s30, 0x1c0
	v_mfma_f32_16x16x32_bf16 v[106:109], v[118:121], v[90:93], v[50:53]
	s_nop 2
	v_add_u32_e32 v50, s23, v122
	v_add_u32_e32 v51, s23, v124
	v_min_u32_e32 v50, 32, v50
	v_min_u32_e32 v51, 32, v51
	v_mul_u32_u24_e32 v50, 0x210, v50
	v_mul_u32_u24_e32 v51, 0x210, v51
	v_add3_u32 v50, v0, v50, s30
	v_add3_u32 v51, v0, v51, s30
	v_mfma_f32_16x16x32_bf16 v[110:113], v[142:145], v[78:81], v[66:69]
	s_nop 2
	ds_read_b128 v[66:69], v50
	ds_read_b128 v[50:53], v51
	v_mfma_f32_16x16x32_bf16 v[46:49], v[118:121], v[134:137], v[46:49]
	v_mfma_f32_16x16x32_bf16 v[42:45], v[142:145], v[134:137], v[42:45]
	v_mfma_f32_16x16x32_bf16 v[94:97], v[142:145], v[90:93], v[86:89]
	v_mfma_f32_16x16x32_bf16 v[38:41], v[118:121], v[62:65], v[38:41]
	v_mfma_f32_16x16x32_bf16 v[34:37], v[142:145], v[62:65], v[34:37]
	v_mfma_f32_16x16x32_bf16 v[98:101], v[118:121], v[82:85], v[114:117]
	v_mfma_f32_16x16x32_bf16 v[86:89], v[142:145], v[82:85], v[130:133]
	v_mfma_f32_16x16x32_bf16 v[30:33], v[118:121], v[58:61], v[30:33]
	v_mfma_f32_16x16x32_bf16 v[26:29], v[142:145], v[58:61], v[26:29]
	s_waitcnt lgkmcnt(3)
	v_mfma_f32_16x16x32_bf16 v[78:81], v[118:121], v[74:77], v[138:141]
	v_mfma_f32_16x16x32_bf16 v[70:73], v[142:145], v[74:77], v[70:73]
	s_waitcnt lgkmcnt(2)
	v_mfma_f32_16x16x32_bf16 v[22:25], v[118:121], v[54:57], v[22:25]
	v_mfma_f32_16x16x32_bf16 v[18:21], v[142:145], v[54:57], v[18:21]
	s_nop 0
	s_add_i32 s11, s11, 8
	s_addk_i32 s22, 0x200
	s_cmpk_gt_i32 s11, 0x78
	v_add_u32_e32 v129, 0x100, v129
	s_cbranch_scc0 .LBB0_771
	s_waitcnt lgkmcnt(0)
	v_add_u32_e32 v50, 0x1180, v123
	v_add_u32_e32 v51, 17, v122
	s_movk_i32 s11, 0x79
.LBB0_773:
	v_add_u32_e32 v52, 0xffffff20, v50
	v_min_i32_e32 v52, 0x1ff8, v52
	v_ashrrev_i32_e32 v53, 31, v52
	v_lshl_add_u64 v[56:57], v[52:53], 1, s[18:19]
	global_load_dwordx4 v[52:55], v[56:57], off
	global_load_dword v122, v[56:57], off offset:-4
	s_waitcnt vmcnt(8)
	v_perm_b32 v56, v125, v2, s67
	v_perm_b32 v57, v2, v3, s67
	v_perm_b32 v58, v3, v4, s67
	v_perm_b32 v59, v4, v5, s67
	s_nop 0
	v_add_u32_e32 v64, -1, v51
	v_min_u32_e32 v64, 32, v64
	v_mad_u32_u24 v118, v64, s58, v0
	v_mfma_f32_16x16x32_bf16 v[60:63], v[56:59], v[90:93], v[110:113]
	s_nop 2
	ds_read_b128 v[110:113], v118 offset:320
	v_mfma_f32_16x16x32_bf16 v[106:109], v[2:5], v[82:85], v[106:109]
	v_mfma_f32_16x16x32_bf16 v[94:97], v[56:59], v[82:85], v[94:97]
	v_mfma_f32_16x16x32_bf16 v[98:101], v[2:5], v[74:77], v[98:101]
	v_mfma_f32_16x16x32_bf16 v[86:89], v[56:59], v[74:77], v[86:89]
	s_waitcnt lgkmcnt(1)
	v_mfma_f32_16x16x32_bf16 v[78:81], v[2:5], v[66:69], v[78:81]
	v_mfma_f32_16x16x32_bf16 v[56:59], v[56:59], v[66:69], v[70:73]
	s_nop 0
	v_add_u32_e32 v64, 0xffffff40, v50
	v_min_i32_e32 v64, 0x1ff8, v64
	v_ashrrev_i32_e32 v65, 31, v64
	v_lshl_add_u64 v[64:65], v[64:65], 1, s[18:19]
	global_load_dwordx4 v[70:73], v[64:65], off
	global_load_dword v123, v[64:65], off offset:-4
	s_waitcnt vmcnt(8)
	v_perm_b32 v114, v126, v6, s67
	v_perm_b32 v115, v6, v7, s67
	v_perm_b32 v116, v7, v8, s67
	v_perm_b32 v117, v8, v9, s67
	s_nop 1

	v_mfma_f32_16x16x32_bf16 v[60:63], v[114:117], v[82:85], v[60:63]
	v_mfma_f32_16x16x32_bf16 v[106:109], v[6:9], v[74:77], v[106:109]
	v_mfma_f32_16x16x32_bf16 v[94:97], v[114:117], v[74:77], v[94:97]
	v_mfma_f32_16x16x32_bf16 v[98:101], v[6:9], v[66:69], v[98:101]
	v_mfma_f32_16x16x32_bf16 v[86:89], v[114:117], v[66:69], v[86:89]
	s_waitcnt lgkmcnt(0)
	v_mfma_f32_16x16x32_bf16 v[78:81], v[6:9], v[110:113], v[78:81]
	v_mfma_f32_16x16x32_bf16 v[56:59], v[114:117], v[110:113], v[56:59]
	ds_read_b128 v[114:117], v118 offset:384
	v_mfma_f32_16x16x32_bf16 v[2:5], v[2:5], v[90:93], v[102:105]
	s_nop 0
	v_add_u32_e32 v64, 0xffffff60, v50
	v_min_i32_e32 v64, 0x1ff8, v64
	v_ashrrev_i32_e32 v65, 31, v64
	v_lshl_add_u64 v[64:65], v[64:65], 1, s[18:19]
	global_load_dwordx4 v[102:105], v[64:65], off
	global_load_dword v124, v[64:65], off offset:-4
	s_waitcnt vmcnt(8)
	v_perm_b32 v90, v127, v10, s67
	v_perm_b32 v91, v10, v11, s67
	v_perm_b32 v92, v11, v12, s67
	v_perm_b32 v93, v12, v13, s67
	s_nop 0
	v_mfma_f32_16x16x32_bf16 v[106:109], v[10:13], v[66:69], v[106:109]
	ds_read_b128 v[118:121], v118 offset:448
	v_mfma_f32_16x16x32_bf16 v[94:97], v[90:93], v[66:69], v[94:97]
	v_mfma_f32_16x16x32_bf16 v[98:101], v[10:13], v[110:113], v[98:101]
	v_mfma_f32_16x16x32_bf16 v[86:89], v[90:93], v[110:113], v[86:89]
	s_waitcnt lgkmcnt(1)
	v_mfma_f32_16x16x32_bf16 v[78:81], v[10:13], v[114:117], v[78:81]
	v_mfma_f32_16x16x32_bf16 v[2:5], v[6:9], v[82:85], v[2:5]
	v_mfma_f32_16x16x32_bf16 v[60:63], v[90:93], v[74:77], v[60:63]
	v_mfma_f32_16x16x32_bf16 v[56:59], v[90:93], v[114:117], v[56:59]
	s_nop 0
	v_add_u32_e32 v6, 0xffffff80, v50
	v_min_i32_e32 v6, 0x1ff8, v6
	v_ashrrev_i32_e32 v7, 31, v6
	v_lshl_add_u64 v[6:7], v[6:7], 1, s[18:19]
	global_load_dwordx4 v[130:133], v[6:7], off
	global_load_dword v129, v[6:7], off offset:-4
	s_waitcnt vmcnt(8)
	v_perm_b32 v6, v128, v14, s67
	v_perm_b32 v7, v14, v15, s67
	v_perm_b32 v8, v15, v16, s67
	v_perm_b32 v9, v16, v17, s67
	s_nop 1

	v_mfma_f32_16x16x32_bf16 v[60:63], v[6:9], v[66:69], v[60:63]
	v_mfma_f32_16x16x32_bf16 v[90:93], v[6:9], v[110:113], v[94:97]
	v_mfma_f32_16x16x32_bf16 v[86:89], v[6:9], v[114:117], v[86:89]
	s_waitcnt lgkmcnt(0)
	v_mfma_f32_16x16x32_bf16 v[6:9], v[6:9], v[118:121], v[56:59]
	s_nop 2
	v_min_u32_e32 v56, 32, v51
	v_mad_u32_u24 v142, v56, s58, v0
	v_mfma_f32_16x16x32_bf16 v[82:85], v[14:17], v[110:113], v[106:109]
	ds_read_b128 v[56:59], v142
	v_mfma_f32_16x16x32_bf16 v[94:97], v[14:17], v[114:117], v[98:101]
	v_mfma_f32_16x16x32_bf16 v[78:81], v[14:17], v[118:121], v[78:81]
	v_mfma_f32_16x16x32_bf16 v[10:13], v[10:13], v[74:77], v[2:5]
	s_nop 0
	s_nop 1
	v_add_u32_e32 v2, 0xffffffa0, v50
	v_min_i32_e32 v2, 0x1ff8, v2
	v_ashrrev_i32_e32 v3, 31, v2
	v_lshl_add_u64 v[64:65], v[2:3], 1, s[18:19]
	global_load_dwordx4 v[2:5], v[64:65], off
	global_load_dword v125, v[64:65], off offset:-4
	s_waitcnt vmcnt(8)
	v_perm_b32 v74, v122, v52, s67
	v_perm_b32 v75, v52, v53, s67
	v_perm_b32 v76, v53, v54, s67
	v_perm_b32 v77, v54, v55, s67
	s_nop 1

	v_mfma_f32_16x16x32_bf16 v[98:101], v[74:77], v[114:117], v[90:93]
	s_nop 2
	ds_read_b128 v[90:93], v142 offset:64
	v_mfma_f32_16x16x32_bf16 v[60:63], v[74:77], v[110:113], v[60:63]
	v_mfma_f32_16x16x32_bf16 v[82:85], v[52:55], v[114:117], v[82:85]
	v_mfma_f32_16x16x32_bf16 v[94:97], v[52:55], v[118:121], v[94:97]
	v_mfma_f32_16x16x32_bf16 v[86:89], v[74:77], v[118:121], v[86:89]
	s_waitcnt lgkmcnt(1)
	v_mfma_f32_16x16x32_bf16 v[78:81], v[52:55], v[56:59], v[78:81]
	v_mfma_f32_16x16x32_bf16 v[74:77], v[74:77], v[56:59], v[6:9]
	v_mfma_f32_16x16x32_bf16 v[10:13], v[14:17], v[66:69], v[10:13]
	s_nop 0
	s_nop 0
	v_subrev_u32_e32 v6, 64, v50
	v_min_i32_e32 v6, 0x1ff8, v6
	v_ashrrev_i32_e32 v7, 31, v6
	v_lshl_add_u64 v[14:15], v[6:7], 1, s[18:19]
	global_load_dwordx4 v[6:9], v[14:15], off
	global_load_dword v126, v[14:15], off offset:-4
	s_waitcnt vmcnt(8)
	v_perm_b32 v14, v123, v70, s67
	v_perm_b32 v15, v70, v71, s67
	v_perm_b32 v16, v71, v72, s67
	v_perm_b32 v17, v72, v73, s67
	s_nop 0
	v_mfma_f32_16x16x32_bf16 v[64:67], v[70:73], v[118:121], v[82:85]
	s_nop 2
	ds_read_b128 v[82:85], v142 offset:128
	v_mfma_f32_16x16x32_bf16 v[60:63], v[14:17], v[114:117], v[60:63]
	v_mfma_f32_16x16x32_bf16 v[98:101], v[14:17], v[118:121], v[98:101]
	v_mfma_f32_16x16x32_bf16 v[94:97], v[70:73], v[56:59], v[94:97]
	v_mfma_f32_16x16x32_bf16 v[86:89], v[14:17], v[56:59], v[86:89]
	s_waitcnt lgkmcnt(1)
	v_mfma_f32_16x16x32_bf16 v[78:81], v[70:73], v[90:93], v[78:81]
	v_mfma_f32_16x16x32_bf16 v[14:17], v[14:17], v[90:93], v[74:77]
	v_mfma_f32_16x16x32_bf16 v[52:55], v[52:55], v[110:113], v[10:13]
	s_nop 0
	s_nop 1
	v_subrev_u32_e32 v10, 32, v50
	v_min_i32_e32 v10, 0x1ff8, v10
	v_ashrrev_i32_e32 v11, 31, v10
	v_lshl_add_u64 v[68:69], v[10:11], 1, s[18:19]
	global_load_dwordx4 v[10:13], v[68:69], off
	global_load_dword v127, v[68:69], off offset:-4
	s_waitcnt vmcnt(8)
	v_perm_b32 v74, v124, v102, s67
	v_perm_b32 v75, v102, v103, s67
	v_perm_b32 v76, v103, v104, s67
	v_perm_b32 v77, v104, v105, s67
	s_nop 1

; template <bool PROMPT, int HALF>
; __device__ __forceinline__ void conv_item(unsigned char* ws, KArgs ka, int ib, int oct, int g, LAS unsigned char* lds, int tid, int lane, int wave) {
;     ...
;     __syncthreads();
;     int lane2; { unsigned ones_ = ~0u; asm volatile("" : "+s"(ones_)); lane2 = (int)__builtin_amdgcn_mbcnt_hi(ones_, __builtin_amdgcn_mbcnt_lo(ones_, 0u)); }
;     const int nn2 = lane2 & 15, kq2 = lane2 >> 4;
;     float nsum = 0.f;
;     { const float* kq_ = (const float*)(ws + WS_KPART) + ((size_t)ib * 320 + (PROMPT ? 0 : 256)) * 2048; constexpr int ntile = PROMPT ? 256 : 64;
;       for (int q = lane2; q < ntile; q += 64) nsum += kq_[(size_t)q * 2048 + c] + kq_[(size_t)q * 2048 + 1024 + c];
	v_mfma_f32_16x16x32_bf16 v[60:63], v[74:77], v[118:121], v[60:63]
	v_mfma_f32_16x16x32_bf16 v[98:101], v[74:77], v[56:59], v[98:101]
	v_mfma_f32_16x16x32_bf16 v[86:89], v[74:77], v[90:93], v[86:89]
	s_waitcnt lgkmcnt(0)
	v_mfma_f32_16x16x32_bf16 v[138:141], v[74:77], v[82:85], v[14:17]
	ds_read_b128 v[74:77], v142 offset:192
	v_mfma_f32_16x16x32_bf16 v[64:67], v[102:105], v[56:59], v[64:67]
	v_mfma_f32_16x16x32_bf16 v[78:81], v[102:105], v[82:85], v[78:81]
	v_mfma_f32_16x16x32_bf16 v[134:137], v[102:105], v[90:93], v[94:97]
	v_mfma_f32_16x16x32_bf16 v[52:55], v[70:73], v[114:117], v[52:55]
	s_nop 0
	v_min_i32_e32 v14, 0x1ff8, v50
	v_ashrrev_i32_e32 v15, 31, v14
	v_lshl_add_u64 v[68:69], v[14:15], 1, s[18:19]
	global_load_dwordx4 v[14:17], v[68:69], off
	global_load_dword v128, v[68:69], off offset:-4
	s_waitcnt vmcnt(8)
	v_perm_b32 v68, v129, v130, s67
	v_perm_b32 v69, v130, v131, s67
	v_perm_b32 v70, v131, v132, s67
	v_perm_b32 v71, v132, v133, s67
	s_nop 0
	v_mfma_f32_16x16x32_bf16 v[52:55], v[102:105], v[118:121], v[52:55]
	v_mfma_f32_16x16x32_bf16 v[110:113], v[68:71], v[56:59], v[60:63]
	v_mfma_f32_16x16x32_bf16 v[106:109], v[130:133], v[90:93], v[64:67]
	v_mfma_f32_16x16x32_bf16 v[94:97], v[68:71], v[90:93], v[98:101]
	v_mfma_f32_16x16x32_bf16 v[86:89], v[68:71], v[82:85], v[86:89]
	s_waitcnt lgkmcnt(0)
	v_mfma_f32_16x16x32_bf16 v[70:73], v[68:71], v[74:77], v[138:141]
	ds_read_b128 v[66:69], v142 offset:256
	v_mfma_f32_16x16x32_bf16 v[98:101], v[130:133], v[82:85], v[134:137]
	v_mfma_f32_16x16x32_bf16 v[78:81], v[130:133], v[74:77], v[78:81]
	v_mfma_f32_16x16x32_bf16 v[102:105], v[130:133], v[56:59], v[52:55]
	s_nop 0
	s_add_i32 s11, s11, 8
	v_add_u32_e32 v50, 0x100, v50
	s_cmpk_gt_u32 s11, 0xf8
	v_add_u32_e32 v51, 1, v51
	s_cbranch_scc0 .LBB0_773
	s_mov_b32 s11, -1
	s_waitcnt lgkmcnt(0)
	s_barrier
	s_nop 0
	v_mbcnt_lo_u32_b32 v0, s11, 0
	s_waitcnt vmcnt(3)
	v_mbcnt_hi_u32_b32 v12, s11, v0
	s_movk_i32 s11, 0x100
	v_cmp_gt_i32_e32 vcc, s11, v12
	v_mov_b32_e32 v0, 0
	s_and_saveexec_b64 s[18:19], vcc
	s_cbranch_execz .LBB0_778
	s_ashr_i32 s43, s42, 31
	s_lshl_b64 s[22:23], s[42:43], 2
	s_add_u32 s22, s51, s22
	v_lshlrev_b32_e32 v0, 13, v12
	s_addc_u32 s23, s52, s23
	v_subrev_u32_e32 v4, 64, v12
	v_lshl_add_u64 v[2:3], s[22:23], 0, v[0:1]
	v_mov_b32_e32 v0, 0
	s_mov_b64 s[22:23], 0
